# GEMM K-loops: first iteration peeled with srcC=0 (no accumulator zeroing movs) in all 14 loops; plus ssm pass2 rewrite
# speedup vs baseline: 1.0129x; 1.0037x over previous
; #define PG8_STAGE(bufoff, gbase, voff) do { _Pragma("unroll") for (int _i = 0; _i < 2; ++_i) \
;         __builtin_amdgcn_global_load_lds((const unsigned*)((const char*)(gbase) + (voff)[_i]), (PG8_LAS unsigned*)(lds + (bufoff) + ldsw + _i * 8192), 16, 0, 0); } while (0)
; #define PG8_LDA(dst, b, h) do { _Pragma("unroll") for (int m = 0; m < 4; ++m) _Pragma("unroll") for (int k = 0; k < 2; ++k) dst[m][k] = *(const PG8_LAS bf16x8*)(lds + PG8_SA(b, h) + aoff + m * 2048 + k * 1024); } while (0)
; #define PG8_WAIT_V(n) asm volatile("s_waitcnt vmcnt(" #n ")" ::: "memory")
; #define PG8_WAIT_L(n) asm volatile("s_waitcnt lgkmcnt(" #n ")" ::: "memory")
; template <class Epi, class Sched, bool ALIGN_EPI = false, bool SP2 = false>
; __device__ __forceinline__ void gemm_phase(PG8_LAS unsigned char* lds, const Gemm g, const Sched& S, const Epi& E) {
;     ...
;     f32x4 acc[2][2][4][2];
; #pragma unroll
;     for (int a = 0; a < 2; ++a)
; #pragma unroll
;         for (int b = 0; b < 2; ++b)
; #pragma unroll
;             for (int m = 0; m < 4; ++m)
; #pragma unroll
;                 for (int n = 0; n < 2; ++n) acc[a][b][m][n] = (f32x4){0.f, 0.f, 0.f, 0.f};
;     ...
;         for (int t = 0; t < nt; t += 2) {
;             const bool last = (t == nt - 2);
;             const char* a1 = cA + (size_t)(t + 1) * kstep;
;             const char* a2 = last ? nA : cA + (size_t)(t + 2) * kstep; const char* b2 = last ? nB : cB + (size_t)(t + 2) * kstep;
;             const char* a3 = a2 + kstep; const char* b3 = b2 + kstep;
;             if (last && has_next) S.a_ready(nxt);
;             if constexpr (SP2) {
;             PG8_LDB(B0, 0, 0); PG8_LDB(B1, 0, 1); PG8_SCHED; PG8_LDA(At, 0, 0); PG8_STAGE(PG8_SA(1, 1), a1 + hstep, voffA);
;             PG8_WAIT_V(8); PG8_WAIT_L(0); PG8_BAR; PG8_MMA(0, 0, At, B0); PG8_MMA(0, 1, At, B1); PG8_BAR; PG8_SCHED;
;             PG8_LDA(At, 0, 1); PG8_STAGE(PG8_SB(0, 0), b2, voffB); PG8_STAGE(PG8_SB(0, 1), b2 + hstep, voffB); PG8_STAGE(PG8_SA(0, 0), a2, voffA);
;             PG8_WAIT_V(8); PG8_WAIT_L(0); PG8_BAR; PG8_MMA(1, 0, At, B0); PG8_MMA(1, 1, At, B1); PG8_BAR; PG8_SCHED;
;             PG8_LDB(B0, 1, 0); PG8_LDB(B1, 1, 1); PG8_SCHED; PG8_LDA(At, 1, 0); PG8_STAGE(PG8_SA(0, 1), a2 + hstep, voffA);
;             PG8_WAIT_V(8); PG8_WAIT_L(0); PG8_BAR; PG8_MMA(0, 0, At, B0); PG8_MMA(0, 1, At, B1); PG8_BAR; PG8_SCHED;
.LBB0_223:
	s_ashr_i32 s15, s14, 31
	s_lshl_b64 s[16:17], s[14:15], 19
	s_add_u32 s16, s36, s16
	s_addc_u32 s17, s37, s17
	s_and_b64 s[18:19], s[4:5], exec
	s_cselect_b32 s15, s17, s21
	s_cselect_b32 s68, s16, s20
	s_ashr_i32 s13, s12, 31
	s_lshl_b64 s[18:19], s[12:13], 19
	s_add_u32 s18, s53, s18
	s_addc_u32 s19, s54, s19
	s_and_b64 s[46:47], s[4:5], exec
	s_cselect_b32 s13, s19, s43
	s_cselect_b32 s69, s18, s42
	s_add_u32 s20, s20, 0x40080
	s_addc_u32 s21, s21, 0
	s_add_u32 s70, s42, 0x100
	s_addc_u32 s71, s43, 0
	s_mov_b32 s72, -2
	ds_read_b128 v[154:157], v150
	ds_read_b128 v[158:161], v150 offset:1024
	ds_read_b128 v[162:165], v150 offset:2048
	ds_read_b128 v[166:169], v150 offset:3072
	ds_read_b128 v[170:173], v151
	ds_read_b128 v[174:177], v151 offset:1024
	ds_read_b128 v[178:181], v151 offset:2048
	ds_read_b128 v[182:185], v151 offset:3072
	s_add_u32 s42, s20, 0xfffc0080
	s_addc_u32 s43, s21, -1
	s_cmp_eq_u32 s72, 12
	s_cselect_b32 s47, s15, s43
	s_cselect_b32 s46, s68, s42
	s_cselect_b32 s43, s13, s71
	s_cselect_b32 s42, s69, s70
	v_lshl_add_u64 v[144:145], s[20:21], 0, v[136:137]
	s_add_i32 m0, s35, 0xc000
	ds_read_b128 v[186:189], v152
	ds_read_b128 v[190:193], v152 offset:1024
	ds_read_b128 v[198:201], v152 offset:2048
	ds_read_b128 v[202:205], v152 offset:3072
	ds_read_b128 v[206:209], v152 offset:4096
	ds_read_b128 v[210:213], v152 offset:5120
	ds_read_b128 v[214:217], v152 offset:6144
	ds_read_b128 v[218:221], v152 offset:7168
	global_load_lds_dwordx4 v[144:145], off
	v_lshl_add_u64 v[144:145], s[20:21], 0, v[138:139]
	s_add_i32 m0, s35, 0xe000
	s_nop 0
	global_load_lds_dwordx4 v[144:145], off
	s_waitcnt vmcnt(8)
	s_waitcnt lgkmcnt(0)
	s_barrier
	s_setprio 1
	s_waitcnt lgkmcnt(0)
	v_mfma_f32_16x16x32_bf16 v[124:127], v[154:157], v[186:189], 0
	v_mfma_f32_16x16x32_bf16 v[116:119], v[162:165], v[186:189], 0
	v_mfma_f32_16x16x32_bf16 v[108:111], v[154:157], v[198:201], 0
	v_mfma_f32_16x16x32_bf16 v[100:103], v[162:165], v[198:201], 0
	v_mfma_f32_16x16x32_bf16 v[92:95], v[154:157], v[206:209], 0
	v_mfma_f32_16x16x32_bf16 v[84:87], v[162:165], v[206:209], 0
	v_mfma_f32_16x16x32_bf16 v[76:79], v[154:157], v[214:217], 0
	v_mfma_f32_16x16x32_bf16 v[68:71], v[162:165], v[214:217], 0
	v_mfma_f32_16x16x32_bf16 v[124:127], v[158:161], v[190:193], v[124:127]
	v_mfma_f32_16x16x32_bf16 v[116:119], v[166:169], v[190:193], v[116:119]
	v_mfma_f32_16x16x32_bf16 v[108:111], v[158:161], v[202:205], v[108:111]
	v_mfma_f32_16x16x32_bf16 v[100:103], v[166:169], v[202:205], v[100:103]
	v_mfma_f32_16x16x32_bf16 v[92:95], v[158:161], v[210:213], v[92:95]
	v_mfma_f32_16x16x32_bf16 v[84:87], v[166:169], v[210:213], v[84:87]
	v_mfma_f32_16x16x32_bf16 v[76:79], v[158:161], v[218:221], v[76:79]
	v_mfma_f32_16x16x32_bf16 v[68:71], v[166:169], v[218:221], v[68:71]
	s_setprio 0
	s_setprio 1
	v_mfma_f32_16x16x32_bf16 v[120:123], v[170:173], v[186:189], 0
	v_mfma_f32_16x16x32_bf16 v[112:115], v[178:181], v[186:189], 0
	v_mfma_f32_16x16x32_bf16 v[104:107], v[170:173], v[198:201], 0
	v_mfma_f32_16x16x32_bf16 v[96:99], v[178:181], v[198:201], 0
	v_mfma_f32_16x16x32_bf16 v[88:91], v[170:173], v[206:209], 0
	v_mfma_f32_16x16x32_bf16 v[80:83], v[178:181], v[206:209], 0
	v_mfma_f32_16x16x32_bf16 v[72:75], v[170:173], v[214:217], 0
	v_mfma_f32_16x16x32_bf16 v[64:67], v[178:181], v[214:217], 0
	v_mfma_f32_16x16x32_bf16 v[120:123], v[174:177], v[190:193], v[120:123]
	v_mfma_f32_16x16x32_bf16 v[112:115], v[182:185], v[190:193], v[112:115]
	v_mfma_f32_16x16x32_bf16 v[104:107], v[174:177], v[202:205], v[104:107]
	v_mfma_f32_16x16x32_bf16 v[96:99], v[182:185], v[202:205], v[96:99]
	v_mfma_f32_16x16x32_bf16 v[88:91], v[174:177], v[210:213], v[88:91]
	v_mfma_f32_16x16x32_bf16 v[80:83], v[182:185], v[210:213], v[80:83]
	v_mfma_f32_16x16x32_bf16 v[72:75], v[174:177], v[218:221], v[72:75]
	v_mfma_f32_16x16x32_bf16 v[64:67], v[182:185], v[218:221], v[64:67]
	s_setprio 0
	s_barrier
	s_add_i32 s73, s63, s55
	v_lshl_add_u64 v[144:145], s[42:43], 0, v[132:133]
	s_mov_b32 m0, s73
	ds_read_b128 v[186:189], v152 offset:16384
	ds_read_b128 v[190:193], v152 offset:17408
	ds_read_b128 v[198:201], v152 offset:18432
	ds_read_b128 v[202:205], v152 offset:19456
	ds_read_b128 v[206:209], v152 offset:20480
	ds_read_b128 v[210:213], v152 offset:21504
	ds_read_b128 v[214:217], v152 offset:22528
	ds_read_b128 v[218:221], v152 offset:23552
	global_load_lds_dwordx4 v[144:145], off
	s_add_i32 m0, s73, 0x2000
	s_add_u32 s74, s42, 0x40000
	v_lshl_add_u64 v[194:195], s[42:43], 0, v[128:129]
	s_addc_u32 s75, s43, 0
	s_add_i32 s73, s64, s55
	global_load_lds_dwordx4 v[194:195], off
	v_lshl_add_u64 v[222:223], s[74:75], 0, v[132:133]
	s_mov_b32 m0, s73
	v_lshl_add_u64 v[224:225], s[46:47], 0, v[130:131]
	global_load_lds_dwordx4 v[222:223], off
	v_lshl_add_u64 v[222:223], s[74:75], 0, v[128:129]
	s_add_i32 m0, s73, 0x2000
	s_nop 0
	global_load_lds_dwordx4 v[222:223], off
	v_lshl_add_u64 v[222:223], s[46:47], 0, v[134:135]
	s_mov_b32 m0, s35
	s_nop 0
	global_load_lds_dwordx4 v[222:223], off
	s_mov_b32 m0, s57
	s_nop 0
	global_load_lds_dwordx4 v[224:225], off
	s_waitcnt vmcnt(8)
	s_waitcnt lgkmcnt(0)
	s_barrier
; #define PG8_STAGE(bufoff, gbase, voff) do { _Pragma("unroll") for (int _i = 0; _i < 2; ++_i) \
;         __builtin_amdgcn_global_load_lds((const unsigned*)((const char*)(gbase) + (voff)[_i]), (PG8_LAS unsigned*)(lds + (bufoff) + ldsw + _i * 8192), 16, 0, 0); } while (0)
; #define PG8_LDA(dst, b, h) do { _Pragma("unroll") for (int m = 0; m < 4; ++m) _Pragma("unroll") for (int k = 0; k < 2; ++k) dst[m][k] = *(const PG8_LAS bf16x8*)(lds + PG8_SA(b, h) + aoff + m * 2048 + k * 1024); } while (0)
; #define PG8_LDB(dst, b, h) do { _Pragma("unroll") for (int n = 0; n < 2; ++n) _Pragma("unroll") for (int k = 0; k < 2; ++k) dst[n][k] = *(const PG8_LAS bf16x8*)(lds + PG8_SB(b, h) + boff + n * 2048 + k * 1024); } while (0)
; #define PG8_MMA(ai, bj, At, Bt) do { __builtin_amdgcn_s_setprio(1); _Pragma("unroll") for (int m = 0; m < 4; ++m) _Pragma("unroll") for (int n = 0; n < 2; ++n) _Pragma("unroll") for (int k = 0; k < 2; ++k) \
;         acc[ai][bj][m][n] = __builtin_amdgcn_mfma_f32_16x16x32_bf16(Bt[n][k], At[m][k], acc[ai][bj][m][n], 0, 0, 0); __builtin_amdgcn_s_setprio(0); } while (0)
; #define PG8_WAIT_V(n) asm volatile("s_waitcnt vmcnt(" #n ")" ::: "memory")
; #define PG8_WAIT_L(n) asm volatile("s_waitcnt lgkmcnt(" #n ")" ::: "memory")
; #define PG8_BAR __builtin_amdgcn_s_barrier()
; #define PG8_SCHED __builtin_amdgcn_sched_barrier(0)
; template <class Epi, class Sched, bool ALIGN_EPI = false, bool SP2 = false>
; __device__ __forceinline__ void gemm_phase(PG8_LAS unsigned char* lds, const Gemm g, const Sched& S, const Epi& E) {
;     ...
;             PG8_LDA(At, 0, 1); PG8_STAGE(PG8_SB(0, 0), b2, voffB); PG8_STAGE(PG8_SB(0, 1), b2 + hstep, voffB); PG8_STAGE(PG8_SA(0, 0), a2, voffA);
;             PG8_WAIT_V(8); PG8_WAIT_L(0); PG8_BAR; PG8_MMA(1, 0, At, B0); PG8_MMA(1, 1, At, B1); PG8_BAR; PG8_SCHED;
;             PG8_LDB(B0, 1, 0); PG8_LDB(B1, 1, 1); PG8_SCHED; PG8_LDA(At, 1, 0); PG8_STAGE(PG8_SA(0, 1), a2 + hstep, voffA);
;             PG8_WAIT_V(8); PG8_WAIT_L(0); PG8_BAR; PG8_MMA(0, 0, At, B0); PG8_MMA(0, 1, At, B1); PG8_BAR; PG8_SCHED;
	s_setprio 1
	s_waitcnt lgkmcnt(0)
	v_mfma_f32_16x16x32_bf16 v[60:63], v[154:157], v[186:189], 0
	v_mfma_f32_16x16x32_bf16 v[52:55], v[162:165], v[186:189], 0
	v_mfma_f32_16x16x32_bf16 v[44:47], v[154:157], v[198:201], 0
	v_mfma_f32_16x16x32_bf16 v[36:39], v[162:165], v[198:201], 0
	v_mfma_f32_16x16x32_bf16 v[28:31], v[154:157], v[206:209], 0
	v_mfma_f32_16x16x32_bf16 v[20:23], v[162:165], v[206:209], 0
	v_mfma_f32_16x16x32_bf16 v[12:15], v[154:157], v[214:217], 0
	v_mfma_f32_16x16x32_bf16 v[4:7], v[162:165], v[214:217], 0
	v_mfma_f32_16x16x32_bf16 v[60:63], v[158:161], v[190:193], v[60:63]
	v_mfma_f32_16x16x32_bf16 v[52:55], v[166:169], v[190:193], v[52:55]
	v_mfma_f32_16x16x32_bf16 v[44:47], v[158:161], v[202:205], v[44:47]
	v_mfma_f32_16x16x32_bf16 v[36:39], v[166:169], v[202:205], v[36:39]
	v_mfma_f32_16x16x32_bf16 v[28:31], v[158:161], v[210:213], v[28:31]
	v_mfma_f32_16x16x32_bf16 v[20:23], v[166:169], v[210:213], v[20:23]
	v_mfma_f32_16x16x32_bf16 v[12:15], v[158:161], v[218:221], v[12:15]
	v_mfma_f32_16x16x32_bf16 v[4:7], v[166:169], v[218:221], v[4:7]
	s_setprio 0
	s_setprio 1
	v_mfma_f32_16x16x32_bf16 v[56:59], v[170:173], v[186:189], 0
	v_mfma_f32_16x16x32_bf16 v[48:51], v[178:181], v[186:189], 0
	v_mfma_f32_16x16x32_bf16 v[40:43], v[170:173], v[198:201], 0
	v_mfma_f32_16x16x32_bf16 v[32:35], v[178:181], v[198:201], 0
	v_mfma_f32_16x16x32_bf16 v[24:27], v[170:173], v[206:209], 0
	v_mfma_f32_16x16x32_bf16 v[16:19], v[178:181], v[206:209], 0
	v_mfma_f32_16x16x32_bf16 v[8:11], v[170:173], v[214:217], 0
	v_mfma_f32_16x16x32_bf16 v[0:3], v[178:181], v[214:217], 0
	v_mfma_f32_16x16x32_bf16 v[56:59], v[174:177], v[190:193], v[56:59]
	v_mfma_f32_16x16x32_bf16 v[48:51], v[182:185], v[190:193], v[48:51]
	v_mfma_f32_16x16x32_bf16 v[40:43], v[174:177], v[202:205], v[40:43]
	v_mfma_f32_16x16x32_bf16 v[32:35], v[182:185], v[202:205], v[32:35]
	v_mfma_f32_16x16x32_bf16 v[24:27], v[174:177], v[210:213], v[24:27]
	v_mfma_f32_16x16x32_bf16 v[16:19], v[182:185], v[210:213], v[16:19]
	v_mfma_f32_16x16x32_bf16 v[8:11], v[174:177], v[218:221], v[8:11]
	v_mfma_f32_16x16x32_bf16 v[0:3], v[182:185], v[218:221], v[0:3]
	s_setprio 0
	s_barrier
	s_add_i32 s73, 0, 0x18000
	v_add_u32_e32 v153, s73, v147
	s_add_i32 s74, 0, 0x1c000
	ds_read_b128 v[154:157], v153
	ds_read_b128 v[158:161], v153 offset:1024
	ds_read_b128 v[162:165], v153 offset:2048
	ds_read_b128 v[166:169], v153 offset:3072
	v_add_u32_e32 v153, s74, v147
	ds_read_b128 v[170:173], v153
	ds_read_b128 v[174:177], v153 offset:1024
	ds_read_b128 v[178:181], v153 offset:2048
	ds_read_b128 v[182:185], v153 offset:3072
	s_add_u32 s46, s46, 0x40000
	s_addc_u32 s47, s47, 0
	s_mov_b32 m0, s58
	v_lshl_add_u64 v[226:227], s[46:47], 0, v[134:135]
	ds_read_b128 v[186:189], v152 offset:32768
	ds_read_b128 v[190:193], v152 offset:33792
	ds_read_b128 v[198:201], v152 offset:34816
	ds_read_b128 v[202:205], v152 offset:35840
	ds_read_b128 v[206:209], v152 offset:36864
	ds_read_b128 v[210:213], v152 offset:37888
	ds_read_b128 v[214:217], v152 offset:38912
	ds_read_b128 v[218:221], v152 offset:39936
	global_load_lds_dwordx4 v[226:227], off
	v_lshl_add_u64 v[226:227], s[46:47], 0, v[130:131]
	s_mov_b32 m0, s59
	s_nop 0
	global_load_lds_dwordx4 v[226:227], off
	s_waitcnt vmcnt(8)
	s_waitcnt lgkmcnt(0)
	s_barrier
	s_setprio 1
	s_waitcnt lgkmcnt(0)
	v_mfma_f32_16x16x32_bf16 v[124:127], v[154:157], v[186:189], v[124:127]
	v_mfma_f32_16x16x32_bf16 v[116:119], v[162:165], v[186:189], v[116:119]
	v_mfma_f32_16x16x32_bf16 v[108:111], v[154:157], v[198:201], v[108:111]
	v_mfma_f32_16x16x32_bf16 v[100:103], v[162:165], v[198:201], v[100:103]
	v_mfma_f32_16x16x32_bf16 v[92:95], v[154:157], v[206:209], v[92:95]
	v_mfma_f32_16x16x32_bf16 v[84:87], v[162:165], v[206:209], v[84:87]
	v_mfma_f32_16x16x32_bf16 v[76:79], v[154:157], v[214:217], v[76:79]
	v_mfma_f32_16x16x32_bf16 v[68:71], v[162:165], v[214:217], v[68:71]
	v_mfma_f32_16x16x32_bf16 v[124:127], v[158:161], v[190:193], v[124:127]
	v_mfma_f32_16x16x32_bf16 v[116:119], v[166:169], v[190:193], v[116:119]
	v_mfma_f32_16x16x32_bf16 v[108:111], v[158:161], v[202:205], v[108:111]
	v_mfma_f32_16x16x32_bf16 v[100:103], v[166:169], v[202:205], v[100:103]
	v_mfma_f32_16x16x32_bf16 v[92:95], v[158:161], v[210:213], v[92:95]
	v_mfma_f32_16x16x32_bf16 v[84:87], v[166:169], v[210:213], v[84:87]
	v_mfma_f32_16x16x32_bf16 v[76:79], v[158:161], v[218:221], v[76:79]
	v_mfma_f32_16x16x32_bf16 v[68:71], v[166:169], v[218:221], v[68:71]
	s_setprio 0
	s_setprio 1
	v_mfma_f32_16x16x32_bf16 v[120:123], v[170:173], v[186:189], v[120:123]
	v_mfma_f32_16x16x32_bf16 v[112:115], v[178:181], v[186:189], v[112:115]
	v_mfma_f32_16x16x32_bf16 v[104:107], v[170:173], v[198:201], v[104:107]
	v_mfma_f32_16x16x32_bf16 v[96:99], v[178:181], v[198:201], v[96:99]
	v_mfma_f32_16x16x32_bf16 v[88:91], v[170:173], v[206:209], v[88:91]
	v_mfma_f32_16x16x32_bf16 v[80:83], v[178:181], v[206:209], v[80:83]
	v_mfma_f32_16x16x32_bf16 v[72:75], v[170:173], v[214:217], v[72:75]
	v_mfma_f32_16x16x32_bf16 v[64:67], v[178:181], v[214:217], v[64:67]
	v_mfma_f32_16x16x32_bf16 v[120:123], v[174:177], v[190:193], v[120:123]
	v_mfma_f32_16x16x32_bf16 v[112:115], v[182:185], v[190:193], v[112:115]
	v_mfma_f32_16x16x32_bf16 v[104:107], v[174:177], v[202:205], v[104:107]
	v_mfma_f32_16x16x32_bf16 v[96:99], v[182:185], v[202:205], v[96:99]
	v_mfma_f32_16x16x32_bf16 v[88:91], v[174:177], v[210:213], v[88:91]
	v_mfma_f32_16x16x32_bf16 v[80:83], v[182:185], v[210:213], v[80:83]
	v_mfma_f32_16x16x32_bf16 v[72:75], v[174:177], v[218:221], v[72:75]
	v_mfma_f32_16x16x32_bf16 v[64:67], v[182:185], v[218:221], v[64:67]
	s_setprio 0
	s_barrier
; #define PG8_STAGE(bufoff, gbase, voff) do { _Pragma("unroll") for (int _i = 0; _i < 2; ++_i) \
;         __builtin_amdgcn_global_load_lds((const unsigned*)((const char*)(gbase) + (voff)[_i]), (PG8_LAS unsigned*)(lds + (bufoff) + ldsw + _i * 8192), 16, 0, 0); } while (0)
; #define PG8_LDA(dst, b, h) do { _Pragma("unroll") for (int m = 0; m < 4; ++m) _Pragma("unroll") for (int k = 0; k < 2; ++k) dst[m][k] = *(const PG8_LAS bf16x8*)(lds + PG8_SA(b, h) + aoff + m * 2048 + k * 1024); } while (0)
; #define PG8_LDB(dst, b, h) do { _Pragma("unroll") for (int n = 0; n < 2; ++n) _Pragma("unroll") for (int k = 0; k < 2; ++k) dst[n][k] = *(const PG8_LAS bf16x8*)(lds + PG8_SB(b, h) + boff + n * 2048 + k * 1024); } while (0)
; #define PG8_MMA(ai, bj, At, Bt) do { __builtin_amdgcn_s_setprio(1); _Pragma("unroll") for (int m = 0; m < 4; ++m) _Pragma("unroll") for (int n = 0; n < 2; ++n) _Pragma("unroll") for (int k = 0; k < 2; ++k) \
;         acc[ai][bj][m][n] = __builtin_amdgcn_mfma_f32_16x16x32_bf16(Bt[n][k], At[m][k], acc[ai][bj][m][n], 0, 0, 0); __builtin_amdgcn_s_setprio(0); } while (0)
; #define PG8_WAIT_V(n) asm volatile("s_waitcnt vmcnt(" #n ")" ::: "memory")
; #define PG8_WAIT_L(n) asm volatile("s_waitcnt lgkmcnt(" #n ")" ::: "memory")
; #define PG8_BAR __builtin_amdgcn_s_barrier()
; template <class Epi, class Sched, bool ALIGN_EPI = false, bool SP2 = false>
; __device__ __forceinline__ void gemm_phase(PG8_LAS unsigned char* lds, const Gemm g, const Sched& S, const Epi& E) {
;     ...
;         for (int t = 0; t < nt; t += 2) {
;             const bool last = (t == nt - 2);
;             const char* a1 = cA + (size_t)(t + 1) * kstep;
;             const char* a2 = last ? nA : cA + (size_t)(t + 2) * kstep; const char* b2 = last ? nB : cB + (size_t)(t + 2) * kstep;
;             const char* a3 = a2 + kstep; const char* b3 = b2 + kstep;
;     ...
;             PG8_LDB(B0, 1, 0); PG8_LDB(B1, 1, 1); PG8_SCHED; PG8_LDA(At, 1, 0); PG8_STAGE(PG8_SA(0, 1), a2 + hstep, voffA);
;             PG8_WAIT_V(8); PG8_WAIT_L(0); PG8_BAR; PG8_MMA(0, 0, At, B0); PG8_MMA(0, 1, At, B1); PG8_BAR; PG8_SCHED;
;             PG8_LDA(At, 1, 1); PG8_STAGE(PG8_SB(1, 0), b3, voffB); PG8_STAGE(PG8_SB(1, 1), b3 + hstep, voffB); PG8_STAGE(PG8_SA(1, 0), a3, voffA);
;             PG8_WAIT_V(8); PG8_WAIT_L(0); PG8_BAR; PG8_MMA(1, 0, At, B0); PG8_MMA(1, 1, At, B1); PG8_BAR; PG8_SCHED;
	s_add_i32 s46, s73, s55
	v_lshl_add_u64 v[144:145], v[144:145], 0, s[8:9]
	s_mov_b32 m0, s46
	ds_read_b128 v[186:189], v152 offset:49152
	ds_read_b128 v[190:193], v152 offset:50176
	ds_read_b128 v[198:201], v152 offset:51200
	ds_read_b128 v[202:205], v152 offset:52224
	ds_read_b128 v[206:209], v152 offset:53248
	ds_read_b128 v[210:213], v152 offset:54272
	ds_read_b128 v[214:217], v152 offset:55296
	ds_read_b128 v[218:221], v152 offset:56320
	global_load_lds_dwordx4 v[144:145], off
	s_add_i32 m0, s46, 0x2000
	s_add_u32 s42, s42, 0x40080
	v_lshl_add_u64 v[144:145], v[194:195], 0, s[8:9]
	s_addc_u32 s43, s43, 0
	s_add_i32 s46, s74, s55
	global_load_lds_dwordx4 v[144:145], off
	v_lshl_add_u64 v[144:145], s[42:43], 0, v[132:133]
	s_mov_b32 m0, s46
	s_nop 0
	global_load_lds_dwordx4 v[144:145], off
	v_lshl_add_u64 v[144:145], s[42:43], 0, v[128:129]
	s_add_i32 m0, s46, 0x2000
	s_nop 0
	global_load_lds_dwordx4 v[144:145], off
	v_lshl_add_u64 v[144:145], v[222:223], 0, s[8:9]
	s_mov_b32 m0, s61
	s_nop 0
	global_load_lds_dwordx4 v[144:145], off
	v_lshl_add_u64 v[144:145], v[224:225], 0, s[8:9]
	s_mov_b32 m0, s62
	s_nop 0
	global_load_lds_dwordx4 v[144:145], off
	s_waitcnt vmcnt(8)
	s_waitcnt lgkmcnt(0)
	s_barrier
	s_setprio 1
	s_waitcnt lgkmcnt(0)
	v_mfma_f32_16x16x32_bf16 v[60:63], v[154:157], v[186:189], v[60:63]
	v_mfma_f32_16x16x32_bf16 v[52:55], v[162:165], v[186:189], v[52:55]
	v_mfma_f32_16x16x32_bf16 v[44:47], v[154:157], v[198:201], v[44:47]
	v_mfma_f32_16x16x32_bf16 v[36:39], v[162:165], v[198:201], v[36:39]
	v_mfma_f32_16x16x32_bf16 v[28:31], v[154:157], v[206:209], v[28:31]
	v_mfma_f32_16x16x32_bf16 v[20:23], v[162:165], v[206:209], v[20:23]
	v_mfma_f32_16x16x32_bf16 v[12:15], v[154:157], v[214:217], v[12:15]
	v_mfma_f32_16x16x32_bf16 v[4:7], v[162:165], v[214:217], v[4:7]
	v_mfma_f32_16x16x32_bf16 v[60:63], v[158:161], v[190:193], v[60:63]
	v_mfma_f32_16x16x32_bf16 v[52:55], v[166:169], v[190:193], v[52:55]
	v_mfma_f32_16x16x32_bf16 v[44:47], v[158:161], v[202:205], v[44:47]
	v_mfma_f32_16x16x32_bf16 v[36:39], v[166:169], v[202:205], v[36:39]
	v_mfma_f32_16x16x32_bf16 v[28:31], v[158:161], v[210:213], v[28:31]
	v_mfma_f32_16x16x32_bf16 v[20:23], v[166:169], v[210:213], v[20:23]
	v_mfma_f32_16x16x32_bf16 v[12:15], v[158:161], v[218:221], v[12:15]
	v_mfma_f32_16x16x32_bf16 v[4:7], v[166:169], v[218:221], v[4:7]
	s_setprio 0
	s_setprio 1
	v_mfma_f32_16x16x32_bf16 v[56:59], v[170:173], v[186:189], v[56:59]
	v_mfma_f32_16x16x32_bf16 v[48:51], v[178:181], v[186:189], v[48:51]
	v_mfma_f32_16x16x32_bf16 v[40:43], v[170:173], v[198:201], v[40:43]
	v_mfma_f32_16x16x32_bf16 v[32:35], v[178:181], v[198:201], v[32:35]
	v_mfma_f32_16x16x32_bf16 v[24:27], v[170:173], v[206:209], v[24:27]
	v_mfma_f32_16x16x32_bf16 v[16:19], v[178:181], v[206:209], v[16:19]
	v_mfma_f32_16x16x32_bf16 v[8:11], v[170:173], v[214:217], v[8:11]
	v_mfma_f32_16x16x32_bf16 v[0:3], v[178:181], v[214:217], v[0:3]
	v_mfma_f32_16x16x32_bf16 v[56:59], v[174:177], v[190:193], v[56:59]
	v_mfma_f32_16x16x32_bf16 v[48:51], v[182:185], v[190:193], v[48:51]
	v_mfma_f32_16x16x32_bf16 v[40:43], v[174:177], v[202:205], v[40:43]
	v_mfma_f32_16x16x32_bf16 v[32:35], v[182:185], v[202:205], v[32:35]
	v_mfma_f32_16x16x32_bf16 v[24:27], v[174:177], v[210:213], v[24:27]
	v_mfma_f32_16x16x32_bf16 v[16:19], v[182:185], v[210:213], v[16:19]
	v_mfma_f32_16x16x32_bf16 v[8:11], v[174:177], v[218:221], v[8:11]
	v_mfma_f32_16x16x32_bf16 v[0:3], v[182:185], v[218:221], v[0:3]
	s_setprio 0
	s_barrier
	s_add_i32 s72, s72, 2
	s_add_u32 s20, s20, 0x100
	s_addc_u32 s21, s21, 0
	s_add_u32 s70, s70, 0x100
	s_addc_u32 s71, s71, 0
	s_cmp_gt_u32 s72, 13

; #define PG8_STAGE(bufoff, gbase, voff) do { _Pragma("unroll") for (int _i = 0; _i < 2; ++_i) \
;         __builtin_amdgcn_global_load_lds((const unsigned*)((const char*)(gbase) + (voff)[_i]), (PG8_LAS unsigned*)(lds + (bufoff) + ldsw + _i * 8192), 16, 0, 0); } while (0)
; #define PG8_LDA(dst, b, h) do { _Pragma("unroll") for (int m = 0; m < 4; ++m) _Pragma("unroll") for (int k = 0; k < 2; ++k) dst[m][k] = *(const PG8_LAS bf16x8*)(lds + PG8_SA(b, h) + aoff + m * 2048 + k * 1024); } while (0)
; #define PG8_WAIT_V(n) asm volatile("s_waitcnt vmcnt(" #n ")" ::: "memory")
; #define PG8_WAIT_L(n) asm volatile("s_waitcnt lgkmcnt(" #n ")" ::: "memory")
; template <class Epi, class Sched, bool ALIGN_EPI = false, bool SP2 = false>
; __device__ __forceinline__ void gemm_phase(PG8_LAS unsigned char* lds, const Gemm g, const Sched& S, const Epi& E) {
;     ...
;     f32x4 acc[2][2][4][2];
; #pragma unroll
;     for (int a = 0; a < 2; ++a)
; #pragma unroll
;         for (int b = 0; b < 2; ++b)
; #pragma unroll
;             for (int m = 0; m < 4; ++m)
; #pragma unroll
;                 for (int n = 0; n < 2; ++n) acc[a][b][m][n] = (f32x4){0.f, 0.f, 0.f, 0.f};
;     ...
;         for (int t = 0; t < nt; t += 2) {
;             const bool last = (t == nt - 2);
;             const char* a1 = cA + (size_t)(t + 1) * kstep;
;             const char* a2 = last ? nA : cA + (size_t)(t + 2) * kstep; const char* b2 = last ? nB : cB + (size_t)(t + 2) * kstep;
;             const char* a3 = a2 + kstep; const char* b3 = b2 + kstep;
;             if (last && has_next) S.a_ready(nxt);
;             if constexpr (SP2) {
;             PG8_LDB(B0, 0, 0); PG8_LDB(B1, 0, 1); PG8_SCHED; PG8_LDA(At, 0, 0); PG8_STAGE(PG8_SA(1, 1), a1 + hstep, voffA);
;             PG8_WAIT_V(8); PG8_WAIT_L(0); PG8_BAR; PG8_MMA(0, 0, At, B0); PG8_MMA(0, 1, At, B1); PG8_BAR; PG8_SCHED;
;             PG8_LDA(At, 0, 1); PG8_STAGE(PG8_SB(0, 0), b2, voffB); PG8_STAGE(PG8_SB(0, 1), b2 + hstep, voffB); PG8_STAGE(PG8_SA(0, 0), a2, voffA);
;             PG8_WAIT_V(8); PG8_WAIT_L(0); PG8_BAR; PG8_MMA(1, 0, At, B0); PG8_MMA(1, 1, At, B1); PG8_BAR; PG8_SCHED;
;             PG8_LDB(B0, 1, 0); PG8_LDB(B1, 1, 1); PG8_SCHED; PG8_LDA(At, 1, 0); PG8_STAGE(PG8_SA(0, 1), a2 + hstep, voffA);
;             PG8_WAIT_V(8); PG8_WAIT_L(0); PG8_BAR; PG8_MMA(0, 0, At, B0); PG8_MMA(0, 1, At, B1); PG8_BAR; PG8_SCHED;
.LBB0_308:
	s_add_u32 s20, s20, 0xb0080
	s_addc_u32 s21, s21, 0
	s_add_u32 s73, s34, 0x100
	s_addc_u32 s74, s35, 0
	s_mov_b32 s75, -2
	s_waitcnt lgkmcnt(0)
	s_waitcnt lgkmcnt(0)
	ds_read_b128 v[96:99], v223
	ds_read_b128 v[108:111], v223 offset:1024
	ds_read_b128 v[120:123], v223 offset:2048
	ds_read_b128 v[128:131], v223 offset:3072
	ds_read_b128 v[144:147], v224
	ds_read_b128 v[148:151], v224 offset:1024
	ds_read_b128 v[152:155], v224 offset:2048
	ds_read_b128 v[156:159], v224 offset:3072
	s_add_u32 s34, s20, 0xfff50080
	s_addc_u32 s35, s21, -1
	s_cmp_eq_u32 s75, 40
	s_cselect_b32 s51, s1, s35
	s_cselect_b32 s50, s0, s34
	s_cselect_b32 s35, s49, s74
	s_cselect_b32 s34, s48, s73
	v_lshl_add_u64 v[210:211], s[20:21], 0, v[192:193]
	s_add_i32 m0, s54, 0xc000
	ds_read_b128 v[160:163], v225
	ds_read_b128 v[164:167], v225 offset:1024
	ds_read_b128 v[168:171], v225 offset:2048
	ds_read_b128 v[172:175], v225 offset:3072
	ds_read_b128 v[176:179], v225 offset:4096
	ds_read_b128 v[180:183], v225 offset:5120
	ds_read_b128 v[202:205], v225 offset:6144
	ds_read_b128 v[206:209], v225 offset:7168
	global_load_lds_dwordx4 v[210:211], off
	v_lshl_add_u64 v[210:211], s[20:21], 0, v[194:195]
	s_add_i32 m0, s54, 0xe000
	s_nop 0
	global_load_lds_dwordx4 v[210:211], off
	s_waitcnt vmcnt(8)
	s_waitcnt lgkmcnt(0)
	s_barrier
	s_setprio 1
	s_waitcnt lgkmcnt(0)
	v_mfma_f32_16x16x32_bf16 v[140:143], v[96:99], v[160:163], 0
	v_mfma_f32_16x16x32_bf16 v[136:139], v[120:123], v[160:163], 0
	v_mfma_f32_16x16x32_bf16 v[116:119], v[96:99], v[168:171], 0
	v_mfma_f32_16x16x32_bf16 v[112:115], v[120:123], v[168:171], 0
	v_mfma_f32_16x16x32_bf16 v[92:95], v[96:99], v[176:179], 0
	v_mfma_f32_16x16x32_bf16 v[88:91], v[120:123], v[176:179], 0
	v_mfma_f32_16x16x32_bf16 v[76:79], v[96:99], v[202:205], 0
	v_mfma_f32_16x16x32_bf16 v[72:75], v[120:123], v[202:205], 0
	v_mfma_f32_16x16x32_bf16 v[140:143], v[108:111], v[164:167], v[140:143]
	v_mfma_f32_16x16x32_bf16 v[136:139], v[128:131], v[164:167], v[136:139]
	v_mfma_f32_16x16x32_bf16 v[116:119], v[108:111], v[172:175], v[116:119]
	v_mfma_f32_16x16x32_bf16 v[112:115], v[128:131], v[172:175], v[112:115]
	v_mfma_f32_16x16x32_bf16 v[92:95], v[108:111], v[180:183], v[92:95]
	v_mfma_f32_16x16x32_bf16 v[88:91], v[128:131], v[180:183], v[88:91]
	v_mfma_f32_16x16x32_bf16 v[76:79], v[108:111], v[206:209], v[76:79]
	v_mfma_f32_16x16x32_bf16 v[72:75], v[128:131], v[206:209], v[72:75]
	s_setprio 0
	s_setprio 1
	v_mfma_f32_16x16x32_bf16 v[132:135], v[144:147], v[160:163], 0
	v_mfma_f32_16x16x32_bf16 v[124:127], v[152:155], v[160:163], 0
	v_mfma_f32_16x16x32_bf16 v[104:107], v[144:147], v[168:171], 0
	v_mfma_f32_16x16x32_bf16 v[100:103], v[152:155], v[168:171], 0
	v_mfma_f32_16x16x32_bf16 v[84:87], v[144:147], v[176:179], 0
	v_mfma_f32_16x16x32_bf16 v[80:83], v[152:155], v[176:179], 0
	v_mfma_f32_16x16x32_bf16 v[68:71], v[144:147], v[202:205], 0
	v_mfma_f32_16x16x32_bf16 v[64:67], v[152:155], v[202:205], 0
	v_mfma_f32_16x16x32_bf16 v[132:135], v[148:151], v[164:167], v[132:135]
	v_mfma_f32_16x16x32_bf16 v[124:127], v[156:159], v[164:167], v[124:127]
	v_mfma_f32_16x16x32_bf16 v[104:107], v[148:151], v[172:175], v[104:107]
	v_mfma_f32_16x16x32_bf16 v[100:103], v[156:159], v[172:175], v[100:103]
	v_mfma_f32_16x16x32_bf16 v[84:87], v[148:151], v[180:183], v[84:87]
	v_mfma_f32_16x16x32_bf16 v[80:83], v[156:159], v[180:183], v[80:83]
	v_mfma_f32_16x16x32_bf16 v[68:71], v[148:151], v[206:209], v[68:71]
	v_mfma_f32_16x16x32_bf16 v[64:67], v[156:159], v[206:209], v[64:67]
	s_setprio 0
	s_barrier
	s_add_i32 s76, s67, s53
	v_lshl_add_u64 v[210:211], s[34:35], 0, v[186:187]
	s_mov_b32 m0, s76
	ds_read_b128 v[160:163], v225 offset:16384
	ds_read_b128 v[164:167], v225 offset:17408
	ds_read_b128 v[168:171], v225 offset:18432
	ds_read_b128 v[172:175], v225 offset:19456
	ds_read_b128 v[176:179], v225 offset:20480
	ds_read_b128 v[180:183], v225 offset:21504
	ds_read_b128 v[202:205], v225 offset:22528
	ds_read_b128 v[206:209], v225 offset:23552
	global_load_lds_dwordx4 v[210:211], off
	s_add_i32 m0, s76, 0x2000
	s_add_u32 s76, s34, 0xb0000
	v_lshl_add_u64 v[212:213], s[34:35], 0, v[190:191]
	s_addc_u32 s77, s35, 0
	s_add_i32 s78, s68, s53
	global_load_lds_dwordx4 v[212:213], off
	v_lshl_add_u64 v[214:215], s[76:77], 0, v[186:187]
	s_mov_b32 m0, s78
	v_lshl_add_u64 v[216:217], s[50:51], 0, v[188:189]
	global_load_lds_dwordx4 v[214:215], off
	v_lshl_add_u64 v[214:215], s[76:77], 0, v[190:191]
	s_add_i32 m0, s78, 0x2000
	s_nop 0
	global_load_lds_dwordx4 v[214:215], off
	v_lshl_add_u64 v[214:215], s[50:51], 0, v[184:185]
	s_mov_b32 m0, s54
	s_nop 0
	global_load_lds_dwordx4 v[214:215], off
	s_mov_b32 m0, s55
	s_nop 0
	global_load_lds_dwordx4 v[216:217], off
	s_waitcnt vmcnt(8)
	s_waitcnt lgkmcnt(0)
	s_barrier
; #define PG8_STAGE(bufoff, gbase, voff) do { _Pragma("unroll") for (int _i = 0; _i < 2; ++_i) \
;         __builtin_amdgcn_global_load_lds((const unsigned*)((const char*)(gbase) + (voff)[_i]), (PG8_LAS unsigned*)(lds + (bufoff) + ldsw + _i * 8192), 16, 0, 0); } while (0)
; #define PG8_LDA(dst, b, h) do { _Pragma("unroll") for (int m = 0; m < 4; ++m) _Pragma("unroll") for (int k = 0; k < 2; ++k) dst[m][k] = *(const PG8_LAS bf16x8*)(lds + PG8_SA(b, h) + aoff + m * 2048 + k * 1024); } while (0)
; #define PG8_LDB(dst, b, h) do { _Pragma("unroll") for (int n = 0; n < 2; ++n) _Pragma("unroll") for (int k = 0; k < 2; ++k) dst[n][k] = *(const PG8_LAS bf16x8*)(lds + PG8_SB(b, h) + boff + n * 2048 + k * 1024); } while (0)
; #define PG8_MMA(ai, bj, At, Bt) do { __builtin_amdgcn_s_setprio(1); _Pragma("unroll") for (int m = 0; m < 4; ++m) _Pragma("unroll") for (int n = 0; n < 2; ++n) _Pragma("unroll") for (int k = 0; k < 2; ++k) \
;         acc[ai][bj][m][n] = __builtin_amdgcn_mfma_f32_16x16x32_bf16(Bt[n][k], At[m][k], acc[ai][bj][m][n], 0, 0, 0); __builtin_amdgcn_s_setprio(0); } while (0)
; #define PG8_WAIT_V(n) asm volatile("s_waitcnt vmcnt(" #n ")" ::: "memory")
; #define PG8_WAIT_L(n) asm volatile("s_waitcnt lgkmcnt(" #n ")" ::: "memory")
; #define PG8_BAR __builtin_amdgcn_s_barrier()
; #define PG8_SCHED __builtin_amdgcn_sched_barrier(0)
; template <class Epi, class Sched, bool ALIGN_EPI = false, bool SP2 = false>
; __device__ __forceinline__ void gemm_phase(PG8_LAS unsigned char* lds, const Gemm g, const Sched& S, const Epi& E) {
;     ...
;             PG8_LDA(At, 0, 1); PG8_STAGE(PG8_SB(0, 0), b2, voffB); PG8_STAGE(PG8_SB(0, 1), b2 + hstep, voffB); PG8_STAGE(PG8_SA(0, 0), a2, voffA);
;             PG8_WAIT_V(8); PG8_WAIT_L(0); PG8_BAR; PG8_MMA(1, 0, At, B0); PG8_MMA(1, 1, At, B1); PG8_BAR; PG8_SCHED;
;             PG8_LDB(B0, 1, 0); PG8_LDB(B1, 1, 1); PG8_SCHED; PG8_LDA(At, 1, 0); PG8_STAGE(PG8_SA(0, 1), a2 + hstep, voffA);
;             PG8_WAIT_V(8); PG8_WAIT_L(0); PG8_BAR; PG8_MMA(0, 0, At, B0); PG8_MMA(0, 1, At, B1); PG8_BAR; PG8_SCHED;
	s_setprio 1
	s_waitcnt lgkmcnt(0)
	v_mfma_f32_16x16x32_bf16 v[60:63], v[96:99], v[160:163], 0
	v_mfma_f32_16x16x32_bf16 v[56:59], v[120:123], v[160:163], 0
	v_mfma_f32_16x16x32_bf16 v[44:47], v[96:99], v[168:171], 0
	v_mfma_f32_16x16x32_bf16 v[40:43], v[120:123], v[168:171], 0
	v_mfma_f32_16x16x32_bf16 v[28:31], v[96:99], v[176:179], 0
	v_mfma_f32_16x16x32_bf16 v[24:27], v[120:123], v[176:179], 0
	v_mfma_f32_16x16x32_bf16 v[12:15], v[96:99], v[202:205], 0
	v_mfma_f32_16x16x32_bf16 v[8:11], v[120:123], v[202:205], 0
	v_mfma_f32_16x16x32_bf16 v[60:63], v[108:111], v[164:167], v[60:63]
	v_mfma_f32_16x16x32_bf16 v[56:59], v[128:131], v[164:167], v[56:59]
	v_mfma_f32_16x16x32_bf16 v[44:47], v[108:111], v[172:175], v[44:47]
	v_mfma_f32_16x16x32_bf16 v[40:43], v[128:131], v[172:175], v[40:43]
	v_mfma_f32_16x16x32_bf16 v[28:31], v[108:111], v[180:183], v[28:31]
	v_mfma_f32_16x16x32_bf16 v[24:27], v[128:131], v[180:183], v[24:27]
	v_mfma_f32_16x16x32_bf16 v[12:15], v[108:111], v[206:209], v[12:15]
	v_mfma_f32_16x16x32_bf16 v[8:11], v[128:131], v[206:209], v[8:11]
	s_setprio 0
	s_setprio 1
	v_mfma_f32_16x16x32_bf16 v[52:55], v[144:147], v[160:163], 0
	v_mfma_f32_16x16x32_bf16 v[48:51], v[152:155], v[160:163], 0
	v_mfma_f32_16x16x32_bf16 v[36:39], v[144:147], v[168:171], 0
	v_mfma_f32_16x16x32_bf16 v[32:35], v[152:155], v[168:171], 0
	v_mfma_f32_16x16x32_bf16 v[20:23], v[144:147], v[176:179], 0
	v_mfma_f32_16x16x32_bf16 v[16:19], v[152:155], v[176:179], 0
	v_mfma_f32_16x16x32_bf16 v[4:7], v[144:147], v[202:205], 0
	v_mfma_f32_16x16x32_bf16 v[0:3], v[152:155], v[202:205], 0
	v_mfma_f32_16x16x32_bf16 v[52:55], v[148:151], v[164:167], v[52:55]
	v_mfma_f32_16x16x32_bf16 v[48:51], v[156:159], v[164:167], v[48:51]
	v_mfma_f32_16x16x32_bf16 v[36:39], v[148:151], v[172:175], v[36:39]
	v_mfma_f32_16x16x32_bf16 v[32:35], v[156:159], v[172:175], v[32:35]
	v_mfma_f32_16x16x32_bf16 v[20:23], v[148:151], v[180:183], v[20:23]
	v_mfma_f32_16x16x32_bf16 v[16:19], v[156:159], v[180:183], v[16:19]
	v_mfma_f32_16x16x32_bf16 v[4:7], v[148:151], v[206:209], v[4:7]
	v_mfma_f32_16x16x32_bf16 v[0:3], v[156:159], v[206:209], v[0:3]
	s_setprio 0
	s_barrier
	s_add_i32 s76, 0, 0x18000
	s_add_i32 s77, 0, 0x1c000
	v_add_u32_e32 v128, s76, v221
	v_add_u32_e32 v156, s77, v221
	ds_read_b128 v[96:99], v128
	ds_read_b128 v[108:111], v128 offset:1024
	ds_read_b128 v[120:123], v128 offset:2048
	ds_read_b128 v[128:131], v128 offset:3072
	ds_read_b128 v[144:147], v156
	ds_read_b128 v[148:151], v156 offset:1024
	ds_read_b128 v[152:155], v156 offset:2048
	ds_read_b128 v[156:159], v156 offset:3072
	s_add_u32 s50, s50, 0xb0000
	s_addc_u32 s51, s51, 0
	s_mov_b32 m0, s56
	v_lshl_add_u64 v[218:219], s[50:51], 0, v[184:185]
	ds_read_b128 v[160:163], v225 offset:32768
	ds_read_b128 v[164:167], v225 offset:33792
	ds_read_b128 v[168:171], v225 offset:34816
	ds_read_b128 v[172:175], v225 offset:35840
	ds_read_b128 v[176:179], v225 offset:36864
	ds_read_b128 v[180:183], v225 offset:37888
	ds_read_b128 v[202:205], v225 offset:38912
	ds_read_b128 v[206:209], v225 offset:39936
	global_load_lds_dwordx4 v[218:219], off
	v_lshl_add_u64 v[218:219], s[50:51], 0, v[188:189]
	s_mov_b32 m0, s57
	s_nop 0
	global_load_lds_dwordx4 v[218:219], off
	s_waitcnt vmcnt(8)
	s_waitcnt lgkmcnt(0)
	s_barrier
	s_setprio 1
	s_waitcnt lgkmcnt(0)
	v_mfma_f32_16x16x32_bf16 v[140:143], v[96:99], v[160:163], v[140:143]
	v_mfma_f32_16x16x32_bf16 v[136:139], v[120:123], v[160:163], v[136:139]
	v_mfma_f32_16x16x32_bf16 v[116:119], v[96:99], v[168:171], v[116:119]
	v_mfma_f32_16x16x32_bf16 v[112:115], v[120:123], v[168:171], v[112:115]
	v_mfma_f32_16x16x32_bf16 v[92:95], v[96:99], v[176:179], v[92:95]
	v_mfma_f32_16x16x32_bf16 v[88:91], v[120:123], v[176:179], v[88:91]
	v_mfma_f32_16x16x32_bf16 v[76:79], v[96:99], v[202:205], v[76:79]
	v_mfma_f32_16x16x32_bf16 v[72:75], v[120:123], v[202:205], v[72:75]
	v_mfma_f32_16x16x32_bf16 v[140:143], v[108:111], v[164:167], v[140:143]
	v_mfma_f32_16x16x32_bf16 v[136:139], v[128:131], v[164:167], v[136:139]
	v_mfma_f32_16x16x32_bf16 v[116:119], v[108:111], v[172:175], v[116:119]
	v_mfma_f32_16x16x32_bf16 v[112:115], v[128:131], v[172:175], v[112:115]
	v_mfma_f32_16x16x32_bf16 v[92:95], v[108:111], v[180:183], v[92:95]
	v_mfma_f32_16x16x32_bf16 v[88:91], v[128:131], v[180:183], v[88:91]
	v_mfma_f32_16x16x32_bf16 v[76:79], v[108:111], v[206:209], v[76:79]
	v_mfma_f32_16x16x32_bf16 v[72:75], v[128:131], v[206:209], v[72:75]
	s_setprio 0
	s_setprio 1
	v_mfma_f32_16x16x32_bf16 v[132:135], v[144:147], v[160:163], v[132:135]
	v_mfma_f32_16x16x32_bf16 v[124:127], v[152:155], v[160:163], v[124:127]
	v_mfma_f32_16x16x32_bf16 v[104:107], v[144:147], v[168:171], v[104:107]
	v_mfma_f32_16x16x32_bf16 v[100:103], v[152:155], v[168:171], v[100:103]
	v_mfma_f32_16x16x32_bf16 v[84:87], v[144:147], v[176:179], v[84:87]
	v_mfma_f32_16x16x32_bf16 v[80:83], v[152:155], v[176:179], v[80:83]
	v_mfma_f32_16x16x32_bf16 v[68:71], v[144:147], v[202:205], v[68:71]
	v_mfma_f32_16x16x32_bf16 v[64:67], v[152:155], v[202:205], v[64:67]
	v_mfma_f32_16x16x32_bf16 v[132:135], v[148:151], v[164:167], v[132:135]
	v_mfma_f32_16x16x32_bf16 v[124:127], v[156:159], v[164:167], v[124:127]
	v_mfma_f32_16x16x32_bf16 v[104:107], v[148:151], v[172:175], v[104:107]
	v_mfma_f32_16x16x32_bf16 v[100:103], v[156:159], v[172:175], v[100:103]
	v_mfma_f32_16x16x32_bf16 v[84:87], v[148:151], v[180:183], v[84:87]
	v_mfma_f32_16x16x32_bf16 v[80:83], v[156:159], v[180:183], v[80:83]
	v_mfma_f32_16x16x32_bf16 v[68:71], v[148:151], v[206:209], v[68:71]
	v_mfma_f32_16x16x32_bf16 v[64:67], v[156:159], v[206:209], v[64:67]
	s_setprio 0
	s_barrier
; #define PG8_STAGE(bufoff, gbase, voff) do { _Pragma("unroll") for (int _i = 0; _i < 2; ++_i) \
;         __builtin_amdgcn_global_load_lds((const unsigned*)((const char*)(gbase) + (voff)[_i]), (PG8_LAS unsigned*)(lds + (bufoff) + ldsw + _i * 8192), 16, 0, 0); } while (0)
; #define PG8_LDA(dst, b, h) do { _Pragma("unroll") for (int m = 0; m < 4; ++m) _Pragma("unroll") for (int k = 0; k < 2; ++k) dst[m][k] = *(const PG8_LAS bf16x8*)(lds + PG8_SA(b, h) + aoff + m * 2048 + k * 1024); } while (0)
; #define PG8_LDB(dst, b, h) do { _Pragma("unroll") for (int n = 0; n < 2; ++n) _Pragma("unroll") for (int k = 0; k < 2; ++k) dst[n][k] = *(const PG8_LAS bf16x8*)(lds + PG8_SB(b, h) + boff + n * 2048 + k * 1024); } while (0)
; #define PG8_MMA(ai, bj, At, Bt) do { __builtin_amdgcn_s_setprio(1); _Pragma("unroll") for (int m = 0; m < 4; ++m) _Pragma("unroll") for (int n = 0; n < 2; ++n) _Pragma("unroll") for (int k = 0; k < 2; ++k) \
;         acc[ai][bj][m][n] = __builtin_amdgcn_mfma_f32_16x16x32_bf16(Bt[n][k], At[m][k], acc[ai][bj][m][n], 0, 0, 0); __builtin_amdgcn_s_setprio(0); } while (0)
; #define PG8_WAIT_V(n) asm volatile("s_waitcnt vmcnt(" #n ")" ::: "memory")
; #define PG8_WAIT_L(n) asm volatile("s_waitcnt lgkmcnt(" #n ")" ::: "memory")
; #define PG8_BAR __builtin_amdgcn_s_barrier()
; template <class Epi, class Sched, bool ALIGN_EPI = false, bool SP2 = false>
; __device__ __forceinline__ void gemm_phase(PG8_LAS unsigned char* lds, const Gemm g, const Sched& S, const Epi& E) {
;     ...
;         for (int t = 0; t < nt; t += 2) {
;             const bool last = (t == nt - 2);
;             const char* a1 = cA + (size_t)(t + 1) * kstep;
;             const char* a2 = last ? nA : cA + (size_t)(t + 2) * kstep; const char* b2 = last ? nB : cB + (size_t)(t + 2) * kstep;
;             const char* a3 = a2 + kstep; const char* b3 = b2 + kstep;
;     ...
;             PG8_LDB(B0, 1, 0); PG8_LDB(B1, 1, 1); PG8_SCHED; PG8_LDA(At, 1, 0); PG8_STAGE(PG8_SA(0, 1), a2 + hstep, voffA);
;             PG8_WAIT_V(8); PG8_WAIT_L(0); PG8_BAR; PG8_MMA(0, 0, At, B0); PG8_MMA(0, 1, At, B1); PG8_BAR; PG8_SCHED;
;             PG8_LDA(At, 1, 1); PG8_STAGE(PG8_SB(1, 0), b3, voffB); PG8_STAGE(PG8_SB(1, 1), b3 + hstep, voffB); PG8_STAGE(PG8_SA(1, 0), a3, voffA);
;             PG8_WAIT_V(8); PG8_WAIT_L(0); PG8_BAR; PG8_MMA(1, 0, At, B0); PG8_MMA(1, 1, At, B1); PG8_BAR; PG8_SCHED;
	s_add_i32 s50, s76, s53
	v_lshl_add_u64 v[210:211], v[210:211], 0, s[12:13]
	s_mov_b32 m0, s50
	ds_read_b128 v[160:163], v225 offset:49152
	ds_read_b128 v[164:167], v225 offset:50176
	ds_read_b128 v[168:171], v225 offset:51200
	ds_read_b128 v[172:175], v225 offset:52224
	ds_read_b128 v[176:179], v225 offset:53248
	ds_read_b128 v[180:183], v225 offset:54272
	ds_read_b128 v[202:205], v225 offset:55296
	ds_read_b128 v[206:209], v225 offset:56320
	global_load_lds_dwordx4 v[210:211], off
	s_add_i32 m0, s50, 0x2000
	s_add_u32 s34, s34, 0xb0080
	v_lshl_add_u64 v[210:211], v[212:213], 0, s[12:13]
	s_addc_u32 s35, s35, 0
	s_add_i32 s50, s77, s53
	global_load_lds_dwordx4 v[210:211], off
	v_lshl_add_u64 v[210:211], s[34:35], 0, v[186:187]
	s_mov_b32 m0, s50
	s_nop 0
	global_load_lds_dwordx4 v[210:211], off
	v_lshl_add_u64 v[210:211], s[34:35], 0, v[190:191]
	s_add_i32 m0, s50, 0x2000
	s_nop 0
	global_load_lds_dwordx4 v[210:211], off
	v_lshl_add_u64 v[210:211], v[214:215], 0, s[12:13]
	s_mov_b32 m0, s62
	s_nop 0
	global_load_lds_dwordx4 v[210:211], off
	v_lshl_add_u64 v[210:211], v[216:217], 0, s[12:13]
	s_mov_b32 m0, s63
	s_nop 0
	global_load_lds_dwordx4 v[210:211], off
	s_waitcnt vmcnt(8)
	s_waitcnt lgkmcnt(0)
	s_barrier
	s_setprio 1
	s_waitcnt lgkmcnt(0)
	v_mfma_f32_16x16x32_bf16 v[60:63], v[96:99], v[160:163], v[60:63]
	v_mfma_f32_16x16x32_bf16 v[56:59], v[120:123], v[160:163], v[56:59]
	v_mfma_f32_16x16x32_bf16 v[44:47], v[96:99], v[168:171], v[44:47]
	v_mfma_f32_16x16x32_bf16 v[40:43], v[120:123], v[168:171], v[40:43]
	v_mfma_f32_16x16x32_bf16 v[28:31], v[96:99], v[176:179], v[28:31]
	v_mfma_f32_16x16x32_bf16 v[24:27], v[120:123], v[176:179], v[24:27]
	v_mfma_f32_16x16x32_bf16 v[12:15], v[96:99], v[202:205], v[12:15]
	v_mfma_f32_16x16x32_bf16 v[8:11], v[120:123], v[202:205], v[8:11]
	v_mfma_f32_16x16x32_bf16 v[60:63], v[108:111], v[164:167], v[60:63]
	v_mfma_f32_16x16x32_bf16 v[56:59], v[128:131], v[164:167], v[56:59]
	v_mfma_f32_16x16x32_bf16 v[44:47], v[108:111], v[172:175], v[44:47]
	v_mfma_f32_16x16x32_bf16 v[40:43], v[128:131], v[172:175], v[40:43]
	v_mfma_f32_16x16x32_bf16 v[28:31], v[108:111], v[180:183], v[28:31]
	v_mfma_f32_16x16x32_bf16 v[24:27], v[128:131], v[180:183], v[24:27]
	v_mfma_f32_16x16x32_bf16 v[12:15], v[108:111], v[206:209], v[12:15]
	v_mfma_f32_16x16x32_bf16 v[8:11], v[128:131], v[206:209], v[8:11]
	s_setprio 0
	s_setprio 1
	v_mfma_f32_16x16x32_bf16 v[52:55], v[144:147], v[160:163], v[52:55]
	v_mfma_f32_16x16x32_bf16 v[48:51], v[152:155], v[160:163], v[48:51]
	v_mfma_f32_16x16x32_bf16 v[36:39], v[144:147], v[168:171], v[36:39]
	v_mfma_f32_16x16x32_bf16 v[32:35], v[152:155], v[168:171], v[32:35]
	v_mfma_f32_16x16x32_bf16 v[20:23], v[144:147], v[176:179], v[20:23]
	v_mfma_f32_16x16x32_bf16 v[16:19], v[152:155], v[176:179], v[16:19]
	v_mfma_f32_16x16x32_bf16 v[4:7], v[144:147], v[202:205], v[4:7]
	v_mfma_f32_16x16x32_bf16 v[0:3], v[152:155], v[202:205], v[0:3]
	v_mfma_f32_16x16x32_bf16 v[52:55], v[148:151], v[164:167], v[52:55]
	v_mfma_f32_16x16x32_bf16 v[48:51], v[156:159], v[164:167], v[48:51]
	v_mfma_f32_16x16x32_bf16 v[36:39], v[148:151], v[172:175], v[36:39]
	v_mfma_f32_16x16x32_bf16 v[32:35], v[156:159], v[172:175], v[32:35]
	v_mfma_f32_16x16x32_bf16 v[20:23], v[148:151], v[180:183], v[20:23]
	v_mfma_f32_16x16x32_bf16 v[16:19], v[156:159], v[180:183], v[16:19]
	v_mfma_f32_16x16x32_bf16 v[4:7], v[148:151], v[206:209], v[4:7]
	v_mfma_f32_16x16x32_bf16 v[0:3], v[156:159], v[206:209], v[0:3]
	s_setprio 0
	s_barrier
	s_add_i32 s75, s75, 2
	s_add_u32 s20, s20, 0x100
	s_addc_u32 s21, s21, 0
	s_add_u32 s73, s73, 0x100
	s_addc_u32 s74, s74, 0
	s_cmp_gt_u32 s75, 41

; #define PG8_STAGE(bufoff, gbase, voff) do { _Pragma("unroll") for (int _i = 0; _i < 2; ++_i) \
;         __builtin_amdgcn_global_load_lds((const unsigned*)((const char*)(gbase) + (voff)[_i]), (PG8_LAS unsigned*)(lds + (bufoff) + ldsw + _i * 8192), 16, 0, 0); } while (0)
; #define PG8_LDA(dst, b, h) do { _Pragma("unroll") for (int m = 0; m < 4; ++m) _Pragma("unroll") for (int k = 0; k < 2; ++k) dst[m][k] = *(const PG8_LAS bf16x8*)(lds + PG8_SA(b, h) + aoff + m * 2048 + k * 1024); } while (0)
; #define PG8_WAIT_V(n) asm volatile("s_waitcnt vmcnt(" #n ")" ::: "memory")
; #define PG8_WAIT_L(n) asm volatile("s_waitcnt lgkmcnt(" #n ")" ::: "memory")
; template <class Epi, class Sched, bool ALIGN_EPI = false, bool SP2 = false>
; __device__ __forceinline__ void gemm_phase(PG8_LAS unsigned char* lds, const Gemm g, const Sched& S, const Epi& E) {
;     ...
;     f32x4 acc[2][2][4][2];
; #pragma unroll
;     for (int a = 0; a < 2; ++a)
; #pragma unroll
;         for (int b = 0; b < 2; ++b)
; #pragma unroll
;             for (int m = 0; m < 4; ++m)
; #pragma unroll
;                 for (int n = 0; n < 2; ++n) acc[a][b][m][n] = (f32x4){0.f, 0.f, 0.f, 0.f};
;     ...
;         for (int t = 0; t < nt; t += 2) {
;             const bool last = (t == nt - 2);
;             const char* a1 = cA + (size_t)(t + 1) * kstep;
;             const char* a2 = last ? nA : cA + (size_t)(t + 2) * kstep; const char* b2 = last ? nB : cB + (size_t)(t + 2) * kstep;
;             const char* a3 = a2 + kstep; const char* b3 = b2 + kstep;
;             if (last && has_next) S.a_ready(nxt);
;             if constexpr (SP2) {
;             PG8_LDB(B0, 0, 0); PG8_LDB(B1, 0, 1); PG8_SCHED; PG8_LDA(At, 0, 0); PG8_STAGE(PG8_SA(1, 1), a1 + hstep, voffA);
;             PG8_WAIT_V(8); PG8_WAIT_L(0); PG8_BAR; PG8_MMA(0, 0, At, B0); PG8_MMA(0, 1, At, B1); PG8_BAR; PG8_SCHED;
;             PG8_LDA(At, 0, 1); PG8_STAGE(PG8_SB(0, 0), b2, voffB); PG8_STAGE(PG8_SB(0, 1), b2 + hstep, voffB); PG8_STAGE(PG8_SA(0, 0), a2, voffA);
;             PG8_WAIT_V(8); PG8_WAIT_L(0); PG8_BAR; PG8_MMA(1, 0, At, B0); PG8_MMA(1, 1, At, B1); PG8_BAR; PG8_SCHED;
;             PG8_LDB(B0, 1, 0); PG8_LDB(B1, 1, 1); PG8_SCHED; PG8_LDA(At, 1, 0); PG8_STAGE(PG8_SA(0, 1), a2 + hstep, voffA);
;             PG8_WAIT_V(8); PG8_WAIT_L(0); PG8_BAR; PG8_MMA(0, 0, At, B0); PG8_MMA(0, 1, At, B1); PG8_BAR; PG8_SCHED;
.LBB0_413:
	s_ashr_i32 s43, s42, 31
	s_lshl_b64 s[48:49], s[42:43], 19
	s_add_u32 s48, s36, s48
	s_addc_u32 s49, s37, s49
	s_and_b64 s[50:51], s[4:5], exec
	s_cselect_b32 s43, s49, s21
	s_cselect_b32 s78, s48, s20
	s_ashr_i32 s19, s18, 31
	s_lshl_b64 s[50:51], s[18:19], 19
	s_add_u32 s50, s61, s50
	s_addc_u32 s51, s62, s51
	s_and_b64 s[54:55], s[4:5], exec
	s_cselect_b32 s19, s51, s53
	s_cselect_b32 s79, s50, s52
	s_add_u32 s20, s20, 0x40080
	s_addc_u32 s21, s21, 0
	s_add_u32 s80, s52, 0x100
	s_addc_u32 s81, s53, 0
	s_mov_b32 s84, -2
	ds_read_b128 v[146:149], v165
	ds_read_b128 v[150:153], v165 offset:1024
	ds_read_b128 v[154:157], v165 offset:2048
	ds_read_b128 v[168:171], v165 offset:3072
	ds_read_b128 v[172:175], v166
	ds_read_b128 v[176:179], v166 offset:1024
	ds_read_b128 v[180:183], v166 offset:2048
	ds_read_b128 v[184:187], v166 offset:3072
	s_add_u32 s52, s20, 0xfffc0080
	s_addc_u32 s53, s21, -1
	s_cmp_eq_u32 s84, 12
	s_cselect_b32 s55, s43, s53
	s_cselect_b32 s54, s78, s52
	s_cselect_b32 s53, s19, s81
	s_cselect_b32 s52, s79, s80
	v_lshl_add_u64 v[158:159], s[20:21], 0, v[138:139]
	s_add_i32 m0, s35, 0xc000
	ds_read_b128 v[188:191], v167
	ds_read_b128 v[192:195], v167 offset:1024
	ds_read_b128 v[198:201], v167 offset:2048
	ds_read_b128 v[202:205], v167 offset:3072
	ds_read_b128 v[206:209], v167 offset:4096
	ds_read_b128 v[210:213], v167 offset:5120
	ds_read_b128 v[214:217], v167 offset:6144
	ds_read_b128 v[218:221], v167 offset:7168
	global_load_lds_dwordx4 v[158:159], off
	v_lshl_add_u64 v[158:159], s[20:21], 0, v[140:141]
	s_add_i32 m0, s35, 0xe000
	s_nop 0
	global_load_lds_dwordx4 v[158:159], off
	s_waitcnt vmcnt(8)
	s_waitcnt lgkmcnt(0)
	s_barrier
	s_setprio 1
	s_waitcnt lgkmcnt(0)
	v_mfma_f32_16x16x32_bf16 v[124:127], v[146:149], v[188:191], 0
	v_mfma_f32_16x16x32_bf16 v[120:123], v[154:157], v[188:191], 0
	v_mfma_f32_16x16x32_bf16 v[108:111], v[146:149], v[198:201], 0
	v_mfma_f32_16x16x32_bf16 v[104:107], v[154:157], v[198:201], 0
	v_mfma_f32_16x16x32_bf16 v[92:95], v[146:149], v[206:209], 0
	v_mfma_f32_16x16x32_bf16 v[88:91], v[154:157], v[206:209], 0
	v_mfma_f32_16x16x32_bf16 v[76:79], v[146:149], v[214:217], 0
	v_mfma_f32_16x16x32_bf16 v[72:75], v[154:157], v[214:217], 0
	v_mfma_f32_16x16x32_bf16 v[124:127], v[150:153], v[192:195], v[124:127]
	v_mfma_f32_16x16x32_bf16 v[120:123], v[168:171], v[192:195], v[120:123]
	v_mfma_f32_16x16x32_bf16 v[108:111], v[150:153], v[202:205], v[108:111]
	v_mfma_f32_16x16x32_bf16 v[104:107], v[168:171], v[202:205], v[104:107]
	v_mfma_f32_16x16x32_bf16 v[92:95], v[150:153], v[210:213], v[92:95]
	v_mfma_f32_16x16x32_bf16 v[88:91], v[168:171], v[210:213], v[88:91]
	v_mfma_f32_16x16x32_bf16 v[76:79], v[150:153], v[218:221], v[76:79]
	v_mfma_f32_16x16x32_bf16 v[72:75], v[168:171], v[218:221], v[72:75]
	s_setprio 0
	s_setprio 1
	v_mfma_f32_16x16x32_bf16 v[116:119], v[172:175], v[188:191], 0
	v_mfma_f32_16x16x32_bf16 v[112:115], v[180:183], v[188:191], 0
	v_mfma_f32_16x16x32_bf16 v[100:103], v[172:175], v[198:201], 0
	v_mfma_f32_16x16x32_bf16 v[96:99], v[180:183], v[198:201], 0
	v_mfma_f32_16x16x32_bf16 v[84:87], v[172:175], v[206:209], 0
	v_mfma_f32_16x16x32_bf16 v[80:83], v[180:183], v[206:209], 0
	v_mfma_f32_16x16x32_bf16 v[68:71], v[172:175], v[214:217], 0
	v_mfma_f32_16x16x32_bf16 v[64:67], v[180:183], v[214:217], 0
	v_mfma_f32_16x16x32_bf16 v[116:119], v[176:179], v[192:195], v[116:119]
	v_mfma_f32_16x16x32_bf16 v[112:115], v[184:187], v[192:195], v[112:115]
	v_mfma_f32_16x16x32_bf16 v[100:103], v[176:179], v[202:205], v[100:103]
	v_mfma_f32_16x16x32_bf16 v[96:99], v[184:187], v[202:205], v[96:99]
	v_mfma_f32_16x16x32_bf16 v[84:87], v[176:179], v[210:213], v[84:87]
	v_mfma_f32_16x16x32_bf16 v[80:83], v[184:187], v[210:213], v[80:83]
	v_mfma_f32_16x16x32_bf16 v[68:71], v[176:179], v[218:221], v[68:71]
	v_mfma_f32_16x16x32_bf16 v[64:67], v[184:187], v[218:221], v[64:67]
	s_setprio 0
	s_barrier
	s_add_i32 s85, s72, s63
	v_lshl_add_u64 v[158:159], s[52:53], 0, v[132:133]
	s_mov_b32 m0, s85
	ds_read_b128 v[188:191], v167 offset:16384
	ds_read_b128 v[192:195], v167 offset:17408
	ds_read_b128 v[198:201], v167 offset:18432
	ds_read_b128 v[202:205], v167 offset:19456
	ds_read_b128 v[206:209], v167 offset:20480
	ds_read_b128 v[210:213], v167 offset:21504
	ds_read_b128 v[214:217], v167 offset:22528
	ds_read_b128 v[218:221], v167 offset:23552
	global_load_lds_dwordx4 v[158:159], off
	s_add_i32 m0, s85, 0x2000
	s_add_u32 s86, s52, 0x40000
	v_lshl_add_u64 v[222:223], s[52:53], 0, v[128:129]
	s_addc_u32 s87, s53, 0
	s_add_i32 s85, s73, s63
	global_load_lds_dwordx4 v[222:223], off
	v_lshl_add_u64 v[224:225], s[86:87], 0, v[132:133]
	s_mov_b32 m0, s85
	v_lshl_add_u64 v[226:227], s[54:55], 0, v[130:131]
	global_load_lds_dwordx4 v[224:225], off
	v_lshl_add_u64 v[224:225], s[86:87], 0, v[128:129]
	s_add_i32 m0, s85, 0x2000
	s_nop 0
	global_load_lds_dwordx4 v[224:225], off
	v_lshl_add_u64 v[224:225], s[54:55], 0, v[134:135]
	s_mov_b32 m0, s35
	s_nop 0
	global_load_lds_dwordx4 v[224:225], off
	s_mov_b32 m0, s65
	s_nop 0
	global_load_lds_dwordx4 v[226:227], off
	s_waitcnt vmcnt(8)
	s_waitcnt lgkmcnt(0)
	s_barrier
; #define PG8_STAGE(bufoff, gbase, voff) do { _Pragma("unroll") for (int _i = 0; _i < 2; ++_i) \
;         __builtin_amdgcn_global_load_lds((const unsigned*)((const char*)(gbase) + (voff)[_i]), (PG8_LAS unsigned*)(lds + (bufoff) + ldsw + _i * 8192), 16, 0, 0); } while (0)
; #define PG8_LDA(dst, b, h) do { _Pragma("unroll") for (int m = 0; m < 4; ++m) _Pragma("unroll") for (int k = 0; k < 2; ++k) dst[m][k] = *(const PG8_LAS bf16x8*)(lds + PG8_SA(b, h) + aoff + m * 2048 + k * 1024); } while (0)
; #define PG8_LDB(dst, b, h) do { _Pragma("unroll") for (int n = 0; n < 2; ++n) _Pragma("unroll") for (int k = 0; k < 2; ++k) dst[n][k] = *(const PG8_LAS bf16x8*)(lds + PG8_SB(b, h) + boff + n * 2048 + k * 1024); } while (0)
; #define PG8_MMA(ai, bj, At, Bt) do { __builtin_amdgcn_s_setprio(1); _Pragma("unroll") for (int m = 0; m < 4; ++m) _Pragma("unroll") for (int n = 0; n < 2; ++n) _Pragma("unroll") for (int k = 0; k < 2; ++k) \
;         acc[ai][bj][m][n] = __builtin_amdgcn_mfma_f32_16x16x32_bf16(Bt[n][k], At[m][k], acc[ai][bj][m][n], 0, 0, 0); __builtin_amdgcn_s_setprio(0); } while (0)
; #define PG8_WAIT_V(n) asm volatile("s_waitcnt vmcnt(" #n ")" ::: "memory")
; #define PG8_WAIT_L(n) asm volatile("s_waitcnt lgkmcnt(" #n ")" ::: "memory")
; #define PG8_BAR __builtin_amdgcn_s_barrier()
; #define PG8_SCHED __builtin_amdgcn_sched_barrier(0)
; template <class Epi, class Sched, bool ALIGN_EPI = false, bool SP2 = false>
; __device__ __forceinline__ void gemm_phase(PG8_LAS unsigned char* lds, const Gemm g, const Sched& S, const Epi& E) {
;     ...
;             PG8_LDA(At, 0, 1); PG8_STAGE(PG8_SB(0, 0), b2, voffB); PG8_STAGE(PG8_SB(0, 1), b2 + hstep, voffB); PG8_STAGE(PG8_SA(0, 0), a2, voffA);
;             PG8_WAIT_V(8); PG8_WAIT_L(0); PG8_BAR; PG8_MMA(1, 0, At, B0); PG8_MMA(1, 1, At, B1); PG8_BAR; PG8_SCHED;
;             PG8_LDB(B0, 1, 0); PG8_LDB(B1, 1, 1); PG8_SCHED; PG8_LDA(At, 1, 0); PG8_STAGE(PG8_SA(0, 1), a2 + hstep, voffA);
;             PG8_WAIT_V(8); PG8_WAIT_L(0); PG8_BAR; PG8_MMA(0, 0, At, B0); PG8_MMA(0, 1, At, B1); PG8_BAR; PG8_SCHED;
	s_setprio 1
	s_waitcnt lgkmcnt(0)
	v_mfma_f32_16x16x32_bf16 v[60:63], v[146:149], v[188:191], 0
	v_mfma_f32_16x16x32_bf16 v[56:59], v[154:157], v[188:191], 0
	v_mfma_f32_16x16x32_bf16 v[44:47], v[146:149], v[198:201], 0
	v_mfma_f32_16x16x32_bf16 v[40:43], v[154:157], v[198:201], 0
	v_mfma_f32_16x16x32_bf16 v[28:31], v[146:149], v[206:209], 0
	v_mfma_f32_16x16x32_bf16 v[24:27], v[154:157], v[206:209], 0
	v_mfma_f32_16x16x32_bf16 v[12:15], v[146:149], v[214:217], 0
	v_mfma_f32_16x16x32_bf16 v[8:11], v[154:157], v[214:217], 0
	v_mfma_f32_16x16x32_bf16 v[60:63], v[150:153], v[192:195], v[60:63]
	v_mfma_f32_16x16x32_bf16 v[56:59], v[168:171], v[192:195], v[56:59]
	v_mfma_f32_16x16x32_bf16 v[44:47], v[150:153], v[202:205], v[44:47]
	v_mfma_f32_16x16x32_bf16 v[40:43], v[168:171], v[202:205], v[40:43]
	v_mfma_f32_16x16x32_bf16 v[28:31], v[150:153], v[210:213], v[28:31]
	v_mfma_f32_16x16x32_bf16 v[24:27], v[168:171], v[210:213], v[24:27]
	v_mfma_f32_16x16x32_bf16 v[12:15], v[150:153], v[218:221], v[12:15]
	v_mfma_f32_16x16x32_bf16 v[8:11], v[168:171], v[218:221], v[8:11]
	s_setprio 0
	s_setprio 1
	v_mfma_f32_16x16x32_bf16 v[52:55], v[172:175], v[188:191], 0
	v_mfma_f32_16x16x32_bf16 v[48:51], v[180:183], v[188:191], 0
	v_mfma_f32_16x16x32_bf16 v[36:39], v[172:175], v[198:201], 0
	v_mfma_f32_16x16x32_bf16 v[32:35], v[180:183], v[198:201], 0
	v_mfma_f32_16x16x32_bf16 v[20:23], v[172:175], v[206:209], 0
	v_mfma_f32_16x16x32_bf16 v[16:19], v[180:183], v[206:209], 0
	v_mfma_f32_16x16x32_bf16 v[4:7], v[172:175], v[214:217], 0
	v_mfma_f32_16x16x32_bf16 v[0:3], v[180:183], v[214:217], 0
	v_mfma_f32_16x16x32_bf16 v[52:55], v[176:179], v[192:195], v[52:55]
	v_mfma_f32_16x16x32_bf16 v[48:51], v[184:187], v[192:195], v[48:51]
	v_mfma_f32_16x16x32_bf16 v[36:39], v[176:179], v[202:205], v[36:39]
	v_mfma_f32_16x16x32_bf16 v[32:35], v[184:187], v[202:205], v[32:35]
	v_mfma_f32_16x16x32_bf16 v[20:23], v[176:179], v[210:213], v[20:23]
	v_mfma_f32_16x16x32_bf16 v[16:19], v[184:187], v[210:213], v[16:19]
	v_mfma_f32_16x16x32_bf16 v[4:7], v[176:179], v[218:221], v[4:7]
	v_mfma_f32_16x16x32_bf16 v[0:3], v[184:187], v[218:221], v[0:3]
	s_setprio 0
	s_barrier
	s_add_i32 s85, 0, 0x18000
	v_add_u32_e32 v136, s85, v161
	s_add_i32 s86, 0, 0x1c000
	ds_read_b128 v[146:149], v136
	ds_read_b128 v[150:153], v136 offset:1024
	ds_read_b128 v[154:157], v136 offset:2048
	ds_read_b128 v[168:171], v136 offset:3072
	v_add_u32_e32 v136, s86, v161
	ds_read_b128 v[172:175], v136
	ds_read_b128 v[176:179], v136 offset:1024
	ds_read_b128 v[180:183], v136 offset:2048
	ds_read_b128 v[184:187], v136 offset:3072
	s_add_u32 s54, s54, 0x40000
	s_addc_u32 s55, s55, 0
	s_mov_b32 m0, s66
	v_lshl_add_u64 v[228:229], s[54:55], 0, v[134:135]
	ds_read_b128 v[188:191], v167 offset:32768
	ds_read_b128 v[192:195], v167 offset:33792
	ds_read_b128 v[198:201], v167 offset:34816
	ds_read_b128 v[202:205], v167 offset:35840
	ds_read_b128 v[206:209], v167 offset:36864
	ds_read_b128 v[210:213], v167 offset:37888
	ds_read_b128 v[214:217], v167 offset:38912
	ds_read_b128 v[218:221], v167 offset:39936
	global_load_lds_dwordx4 v[228:229], off
	v_lshl_add_u64 v[228:229], s[54:55], 0, v[130:131]
	s_mov_b32 m0, s67
	s_nop 0
	global_load_lds_dwordx4 v[228:229], off
	s_waitcnt vmcnt(8)
	s_waitcnt lgkmcnt(0)
	s_barrier
	s_setprio 1
	s_waitcnt lgkmcnt(0)
	v_mfma_f32_16x16x32_bf16 v[124:127], v[146:149], v[188:191], v[124:127]
	v_mfma_f32_16x16x32_bf16 v[120:123], v[154:157], v[188:191], v[120:123]
	v_mfma_f32_16x16x32_bf16 v[108:111], v[146:149], v[198:201], v[108:111]
	v_mfma_f32_16x16x32_bf16 v[104:107], v[154:157], v[198:201], v[104:107]
	v_mfma_f32_16x16x32_bf16 v[92:95], v[146:149], v[206:209], v[92:95]
	v_mfma_f32_16x16x32_bf16 v[88:91], v[154:157], v[206:209], v[88:91]
	v_mfma_f32_16x16x32_bf16 v[76:79], v[146:149], v[214:217], v[76:79]
	v_mfma_f32_16x16x32_bf16 v[72:75], v[154:157], v[214:217], v[72:75]
	v_mfma_f32_16x16x32_bf16 v[124:127], v[150:153], v[192:195], v[124:127]
	v_mfma_f32_16x16x32_bf16 v[120:123], v[168:171], v[192:195], v[120:123]
	v_mfma_f32_16x16x32_bf16 v[108:111], v[150:153], v[202:205], v[108:111]
	v_mfma_f32_16x16x32_bf16 v[104:107], v[168:171], v[202:205], v[104:107]
	v_mfma_f32_16x16x32_bf16 v[92:95], v[150:153], v[210:213], v[92:95]
	v_mfma_f32_16x16x32_bf16 v[88:91], v[168:171], v[210:213], v[88:91]
	v_mfma_f32_16x16x32_bf16 v[76:79], v[150:153], v[218:221], v[76:79]
	v_mfma_f32_16x16x32_bf16 v[72:75], v[168:171], v[218:221], v[72:75]
	s_setprio 0
	s_setprio 1
	v_mfma_f32_16x16x32_bf16 v[116:119], v[172:175], v[188:191], v[116:119]
	v_mfma_f32_16x16x32_bf16 v[112:115], v[180:183], v[188:191], v[112:115]
	v_mfma_f32_16x16x32_bf16 v[100:103], v[172:175], v[198:201], v[100:103]
	v_mfma_f32_16x16x32_bf16 v[96:99], v[180:183], v[198:201], v[96:99]
	v_mfma_f32_16x16x32_bf16 v[84:87], v[172:175], v[206:209], v[84:87]
	v_mfma_f32_16x16x32_bf16 v[80:83], v[180:183], v[206:209], v[80:83]
	v_mfma_f32_16x16x32_bf16 v[68:71], v[172:175], v[214:217], v[68:71]
	v_mfma_f32_16x16x32_bf16 v[64:67], v[180:183], v[214:217], v[64:67]
	v_mfma_f32_16x16x32_bf16 v[116:119], v[176:179], v[192:195], v[116:119]
	v_mfma_f32_16x16x32_bf16 v[112:115], v[184:187], v[192:195], v[112:115]
	v_mfma_f32_16x16x32_bf16 v[100:103], v[176:179], v[202:205], v[100:103]
	v_mfma_f32_16x16x32_bf16 v[96:99], v[184:187], v[202:205], v[96:99]
	v_mfma_f32_16x16x32_bf16 v[84:87], v[176:179], v[210:213], v[84:87]
	v_mfma_f32_16x16x32_bf16 v[80:83], v[184:187], v[210:213], v[80:83]
	v_mfma_f32_16x16x32_bf16 v[68:71], v[176:179], v[218:221], v[68:71]
	v_mfma_f32_16x16x32_bf16 v[64:67], v[184:187], v[218:221], v[64:67]
	s_setprio 0
	s_barrier
; #define PG8_STAGE(bufoff, gbase, voff) do { _Pragma("unroll") for (int _i = 0; _i < 2; ++_i) \
;         __builtin_amdgcn_global_load_lds((const unsigned*)((const char*)(gbase) + (voff)[_i]), (PG8_LAS unsigned*)(lds + (bufoff) + ldsw + _i * 8192), 16, 0, 0); } while (0)
; #define PG8_LDA(dst, b, h) do { _Pragma("unroll") for (int m = 0; m < 4; ++m) _Pragma("unroll") for (int k = 0; k < 2; ++k) dst[m][k] = *(const PG8_LAS bf16x8*)(lds + PG8_SA(b, h) + aoff + m * 2048 + k * 1024); } while (0)
; #define PG8_LDB(dst, b, h) do { _Pragma("unroll") for (int n = 0; n < 2; ++n) _Pragma("unroll") for (int k = 0; k < 2; ++k) dst[n][k] = *(const PG8_LAS bf16x8*)(lds + PG8_SB(b, h) + boff + n * 2048 + k * 1024); } while (0)
; #define PG8_MMA(ai, bj, At, Bt) do { __builtin_amdgcn_s_setprio(1); _Pragma("unroll") for (int m = 0; m < 4; ++m) _Pragma("unroll") for (int n = 0; n < 2; ++n) _Pragma("unroll") for (int k = 0; k < 2; ++k) \
;         acc[ai][bj][m][n] = __builtin_amdgcn_mfma_f32_16x16x32_bf16(Bt[n][k], At[m][k], acc[ai][bj][m][n], 0, 0, 0); __builtin_amdgcn_s_setprio(0); } while (0)
; #define PG8_WAIT_V(n) asm volatile("s_waitcnt vmcnt(" #n ")" ::: "memory")
; #define PG8_WAIT_L(n) asm volatile("s_waitcnt lgkmcnt(" #n ")" ::: "memory")
; #define PG8_BAR __builtin_amdgcn_s_barrier()
; template <class Epi, class Sched, bool ALIGN_EPI = false, bool SP2 = false>
; __device__ __forceinline__ void gemm_phase(PG8_LAS unsigned char* lds, const Gemm g, const Sched& S, const Epi& E) {
;     ...
;         for (int t = 0; t < nt; t += 2) {
;             const bool last = (t == nt - 2);
;             const char* a1 = cA + (size_t)(t + 1) * kstep;
;             const char* a2 = last ? nA : cA + (size_t)(t + 2) * kstep; const char* b2 = last ? nB : cB + (size_t)(t + 2) * kstep;
;             const char* a3 = a2 + kstep; const char* b3 = b2 + kstep;
;     ...
;             PG8_LDB(B0, 1, 0); PG8_LDB(B1, 1, 1); PG8_SCHED; PG8_LDA(At, 1, 0); PG8_STAGE(PG8_SA(0, 1), a2 + hstep, voffA);
;             PG8_WAIT_V(8); PG8_WAIT_L(0); PG8_BAR; PG8_MMA(0, 0, At, B0); PG8_MMA(0, 1, At, B1); PG8_BAR; PG8_SCHED;
;             PG8_LDA(At, 1, 1); PG8_STAGE(PG8_SB(1, 0), b3, voffB); PG8_STAGE(PG8_SB(1, 1), b3 + hstep, voffB); PG8_STAGE(PG8_SA(1, 0), a3, voffA);
;             PG8_WAIT_V(8); PG8_WAIT_L(0); PG8_BAR; PG8_MMA(1, 0, At, B0); PG8_MMA(1, 1, At, B1); PG8_BAR; PG8_SCHED;
	s_add_i32 s54, s85, s63
	v_lshl_add_u64 v[158:159], v[158:159], 0, s[8:9]
	s_mov_b32 m0, s54
	ds_read_b128 v[188:191], v167 offset:49152
	ds_read_b128 v[192:195], v167 offset:50176
	ds_read_b128 v[198:201], v167 offset:51200
	ds_read_b128 v[202:205], v167 offset:52224
	ds_read_b128 v[206:209], v167 offset:53248
	ds_read_b128 v[210:213], v167 offset:54272
	ds_read_b128 v[214:217], v167 offset:55296
	ds_read_b128 v[218:221], v167 offset:56320
	global_load_lds_dwordx4 v[158:159], off
	s_add_i32 m0, s54, 0x2000
	s_add_u32 s52, s52, 0x40080
	v_lshl_add_u64 v[158:159], v[222:223], 0, s[8:9]
	s_addc_u32 s53, s53, 0
	s_add_i32 s54, s86, s63
	global_load_lds_dwordx4 v[158:159], off
	v_lshl_add_u64 v[158:159], s[52:53], 0, v[132:133]
	s_mov_b32 m0, s54
	s_nop 0
	global_load_lds_dwordx4 v[158:159], off
	v_lshl_add_u64 v[158:159], s[52:53], 0, v[128:129]
	s_add_i32 m0, s54, 0x2000
	s_nop 0
	global_load_lds_dwordx4 v[158:159], off
	v_lshl_add_u64 v[158:159], v[224:225], 0, s[8:9]
	s_mov_b32 m0, s69
	s_nop 0
	global_load_lds_dwordx4 v[158:159], off
	v_lshl_add_u64 v[158:159], v[226:227], 0, s[8:9]
	s_mov_b32 m0, s70
	s_nop 0
	global_load_lds_dwordx4 v[158:159], off
	s_waitcnt vmcnt(8)
	s_waitcnt lgkmcnt(0)
	s_barrier
	s_setprio 1
	s_waitcnt lgkmcnt(0)
	v_mfma_f32_16x16x32_bf16 v[60:63], v[146:149], v[188:191], v[60:63]
	v_mfma_f32_16x16x32_bf16 v[56:59], v[154:157], v[188:191], v[56:59]
	v_mfma_f32_16x16x32_bf16 v[44:47], v[146:149], v[198:201], v[44:47]
	v_mfma_f32_16x16x32_bf16 v[40:43], v[154:157], v[198:201], v[40:43]
	v_mfma_f32_16x16x32_bf16 v[28:31], v[146:149], v[206:209], v[28:31]
	v_mfma_f32_16x16x32_bf16 v[24:27], v[154:157], v[206:209], v[24:27]
	v_mfma_f32_16x16x32_bf16 v[12:15], v[146:149], v[214:217], v[12:15]
	v_mfma_f32_16x16x32_bf16 v[8:11], v[154:157], v[214:217], v[8:11]
	v_mfma_f32_16x16x32_bf16 v[60:63], v[150:153], v[192:195], v[60:63]
	v_mfma_f32_16x16x32_bf16 v[56:59], v[168:171], v[192:195], v[56:59]
	v_mfma_f32_16x16x32_bf16 v[44:47], v[150:153], v[202:205], v[44:47]
	v_mfma_f32_16x16x32_bf16 v[40:43], v[168:171], v[202:205], v[40:43]
	v_mfma_f32_16x16x32_bf16 v[28:31], v[150:153], v[210:213], v[28:31]
	v_mfma_f32_16x16x32_bf16 v[24:27], v[168:171], v[210:213], v[24:27]
	v_mfma_f32_16x16x32_bf16 v[12:15], v[150:153], v[218:221], v[12:15]
	v_mfma_f32_16x16x32_bf16 v[8:11], v[168:171], v[218:221], v[8:11]
	s_setprio 0
	s_setprio 1
	v_mfma_f32_16x16x32_bf16 v[52:55], v[172:175], v[188:191], v[52:55]
	v_mfma_f32_16x16x32_bf16 v[48:51], v[180:183], v[188:191], v[48:51]
	v_mfma_f32_16x16x32_bf16 v[36:39], v[172:175], v[198:201], v[36:39]
	v_mfma_f32_16x16x32_bf16 v[32:35], v[180:183], v[198:201], v[32:35]
	v_mfma_f32_16x16x32_bf16 v[20:23], v[172:175], v[206:209], v[20:23]
	v_mfma_f32_16x16x32_bf16 v[16:19], v[180:183], v[206:209], v[16:19]
	v_mfma_f32_16x16x32_bf16 v[4:7], v[172:175], v[214:217], v[4:7]
	v_mfma_f32_16x16x32_bf16 v[0:3], v[180:183], v[214:217], v[0:3]
	v_mfma_f32_16x16x32_bf16 v[52:55], v[176:179], v[192:195], v[52:55]
	v_mfma_f32_16x16x32_bf16 v[48:51], v[184:187], v[192:195], v[48:51]
	v_mfma_f32_16x16x32_bf16 v[36:39], v[176:179], v[202:205], v[36:39]
	v_mfma_f32_16x16x32_bf16 v[32:35], v[184:187], v[202:205], v[32:35]
	v_mfma_f32_16x16x32_bf16 v[20:23], v[176:179], v[210:213], v[20:23]
	v_mfma_f32_16x16x32_bf16 v[16:19], v[184:187], v[210:213], v[16:19]
	v_mfma_f32_16x16x32_bf16 v[4:7], v[176:179], v[218:221], v[4:7]
	v_mfma_f32_16x16x32_bf16 v[0:3], v[184:187], v[218:221], v[0:3]
	s_setprio 0
	s_barrier
	s_add_i32 s84, s84, 2
	s_add_u32 s20, s20, 0x100
	s_addc_u32 s21, s21, 0
	s_add_u32 s80, s80, 0x100
	s_addc_u32 s81, s81, 0
	s_cmp_gt_u32 s84, 13

; #define PG8_STAGE(bufoff, gbase, voff) do { _Pragma("unroll") for (int _i = 0; _i < 2; ++_i) \
;         __builtin_amdgcn_global_load_lds((const unsigned*)((const char*)(gbase) + (voff)[_i]), (PG8_LAS unsigned*)(lds + (bufoff) + ldsw + _i * 8192), 16, 0, 0); } while (0)
; #define PG8_LDA(dst, b, h) do { _Pragma("unroll") for (int m = 0; m < 4; ++m) _Pragma("unroll") for (int k = 0; k < 2; ++k) dst[m][k] = *(const PG8_LAS bf16x8*)(lds + PG8_SA(b, h) + aoff + m * 2048 + k * 1024); } while (0)
; #define PG8_LDB(dst, b, h) do { _Pragma("unroll") for (int n = 0; n < 2; ++n) _Pragma("unroll") for (int k = 0; k < 2; ++k) dst[n][k] = *(const PG8_LAS bf16x8*)(lds + PG8_SB(b, h) + boff + n * 2048 + k * 1024); } while (0)
; #define PG8_WAIT_V(n) asm volatile("s_waitcnt vmcnt(" #n ")" ::: "memory")
; #define PG8_WAIT_L(n) asm volatile("s_waitcnt lgkmcnt(" #n ")" ::: "memory")
; #define PG8_BAR __builtin_amdgcn_s_barrier()
; template <class Epi, class Sched, bool ALIGN_EPI = false, bool SP2 = false>
; __device__ __forceinline__ void gemm_phase(PG8_LAS unsigned char* lds, const Gemm g, const Sched& S, const Epi& E) {
;     ...
;     f32x4 acc[2][2][4][2];
; #pragma unroll
;     for (int a = 0; a < 2; ++a)
; #pragma unroll
;         for (int b = 0; b < 2; ++b)
; #pragma unroll
;             for (int m = 0; m < 4; ++m)
; #pragma unroll
;                 for (int n = 0; n < 2; ++n) acc[a][b][m][n] = (f32x4){0.f, 0.f, 0.f, 0.f};
;     ...
;         for (int t = 0; t < nt; t += 2) {
;             const bool last = (t == nt - 2);
;             const char* a1 = cA + (size_t)(t + 1) * kstep;
;             const char* a2 = last ? nA : cA + (size_t)(t + 2) * kstep; const char* b2 = last ? nB : cB + (size_t)(t + 2) * kstep;
;             const char* a3 = a2 + kstep; const char* b3 = b2 + kstep;
;             if (last && has_next) S.a_ready(nxt);
;             if constexpr (SP2) {
;             PG8_LDB(B0, 0, 0); PG8_LDB(B1, 0, 1); PG8_SCHED; PG8_LDA(At, 0, 0); PG8_STAGE(PG8_SA(1, 1), a1 + hstep, voffA);
;             PG8_WAIT_V(8); PG8_WAIT_L(0); PG8_BAR; PG8_MMA(0, 0, At, B0); PG8_MMA(0, 1, At, B1); PG8_BAR; PG8_SCHED;
;             PG8_LDA(At, 0, 1); PG8_STAGE(PG8_SB(0, 0), b2, voffB); PG8_STAGE(PG8_SB(0, 1), b2 + hstep, voffB); PG8_STAGE(PG8_SA(0, 0), a2, voffA);
;             PG8_WAIT_V(8); PG8_WAIT_L(0); PG8_BAR; PG8_MMA(1, 0, At, B0); PG8_MMA(1, 1, At, B1); PG8_BAR; PG8_SCHED;
.LBB0_623:
	s_ashr_i32 s17, s16, 31
	s_lshl_b64 s[18:19], s[16:17], 18
	s_add_u32 s18, s0, s18
	s_addc_u32 s19, s1, s19
	s_and_b64 s[38:39], s[4:5], exec
	s_cselect_b32 s17, s19, s21
	s_cselect_b32 s63, s18, s20
	s_ashr_i32 s15, s14, 31
	s_lshl_b64 s[38:39], s[14:15], 18
	s_add_u32 s38, s33, s38
	s_addc_u32 s39, s50, s39
	s_and_b64 s[48:49], s[4:5], exec
	s_cselect_b32 s15, s39, s47
	s_cselect_b32 s64, s38, s46
	s_add_u32 s20, s20, 0x20080
	s_addc_u32 s21, s21, 0
	s_add_u32 s65, s46, 0x100
	s_addc_u32 s66, s47, 0
	s_mov_b32 s67, -2
	ds_read_b128 v[112:115], v167
	ds_read_b128 v[116:119], v167 offset:1024
	ds_read_b128 v[152:155], v167 offset:2048
	ds_read_b128 v[156:159], v167 offset:3072
	ds_read_b128 v[160:163], v168
	ds_read_b128 v[170:173], v168 offset:1024
	ds_read_b128 v[174:177], v168 offset:2048
	ds_read_b128 v[178:181], v168 offset:3072
	s_add_u32 s46, s20, 0xfffe0080
	s_addc_u32 s47, s21, -1
	s_cmp_eq_u32 s67, 4
	s_cselect_b32 s49, s17, s47
	s_cselect_b32 s48, s63, s46
	s_cselect_b32 s47, s15, s66
	s_cselect_b32 s46, s64, s65
	v_lshl_add_u64 v[194:195], s[20:21], 0, v[144:145]
	s_add_i32 m0, s35, 0xc000
	ds_read_b128 v[182:185], v169
	ds_read_b128 v[186:189], v169 offset:1024
	ds_read_b128 v[190:193], v169 offset:2048
	ds_read_b128 v[198:201], v169 offset:3072
	ds_read_b128 v[202:205], v169 offset:4096
	ds_read_b128 v[206:209], v169 offset:5120
	ds_read_b128 v[210:213], v169 offset:6144
	ds_read_b128 v[214:217], v169 offset:7168
	global_load_lds_dwordx4 v[194:195], off
	v_lshl_add_u64 v[194:195], s[20:21], 0, v[146:147]
	s_add_i32 m0, s35, 0xe000
	s_nop 0
	global_load_lds_dwordx4 v[194:195], off
	s_waitcnt vmcnt(8)
	s_waitcnt lgkmcnt(0)
	s_barrier
	s_setprio 1
	s_waitcnt lgkmcnt(0)
	v_mfma_f32_16x16x32_bf16 v[132:135], v[112:115], v[182:185], 0
	v_mfma_f32_16x16x32_bf16 v[128:131], v[152:155], v[182:185], 0
	v_mfma_f32_16x16x32_bf16 v[124:127], v[112:115], v[190:193], 0
	v_mfma_f32_16x16x32_bf16 v[120:123], v[152:155], v[190:193], 0
	v_mfma_f32_16x16x32_bf16 v[108:111], v[112:115], v[202:205], 0
	v_mfma_f32_16x16x32_bf16 v[104:107], v[152:155], v[202:205], 0
	v_mfma_f32_16x16x32_bf16 v[100:103], v[112:115], v[210:213], 0
	v_mfma_f32_16x16x32_bf16 v[96:99], v[152:155], v[210:213], 0
	v_mfma_f32_16x16x32_bf16 v[132:135], v[116:119], v[186:189], v[132:135]
	v_mfma_f32_16x16x32_bf16 v[128:131], v[156:159], v[186:189], v[128:131]
	v_mfma_f32_16x16x32_bf16 v[124:127], v[116:119], v[198:201], v[124:127]
	v_mfma_f32_16x16x32_bf16 v[120:123], v[156:159], v[198:201], v[120:123]
	v_mfma_f32_16x16x32_bf16 v[108:111], v[116:119], v[206:209], v[108:111]
	v_mfma_f32_16x16x32_bf16 v[104:107], v[156:159], v[206:209], v[104:107]
	v_mfma_f32_16x16x32_bf16 v[100:103], v[116:119], v[214:217], v[100:103]
	v_mfma_f32_16x16x32_bf16 v[96:99], v[156:159], v[214:217], v[96:99]
	s_setprio 0
	s_setprio 1
	v_mfma_f32_16x16x32_bf16 v[60:63], v[160:163], v[182:185], 0
	v_mfma_f32_16x16x32_bf16 v[56:59], v[174:177], v[182:185], 0
	v_mfma_f32_16x16x32_bf16 v[52:55], v[160:163], v[190:193], 0
	v_mfma_f32_16x16x32_bf16 v[48:51], v[174:177], v[190:193], 0
	v_mfma_f32_16x16x32_bf16 v[44:47], v[160:163], v[202:205], 0
	v_mfma_f32_16x16x32_bf16 v[40:43], v[174:177], v[202:205], 0
	v_mfma_f32_16x16x32_bf16 v[36:39], v[160:163], v[210:213], 0
	v_mfma_f32_16x16x32_bf16 v[32:35], v[174:177], v[210:213], 0
	v_mfma_f32_16x16x32_bf16 v[60:63], v[170:173], v[186:189], v[60:63]
	v_mfma_f32_16x16x32_bf16 v[56:59], v[178:181], v[186:189], v[56:59]
	v_mfma_f32_16x16x32_bf16 v[52:55], v[170:173], v[198:201], v[52:55]
	v_mfma_f32_16x16x32_bf16 v[48:51], v[178:181], v[198:201], v[48:51]
	v_mfma_f32_16x16x32_bf16 v[44:47], v[170:173], v[206:209], v[44:47]
	v_mfma_f32_16x16x32_bf16 v[40:43], v[178:181], v[206:209], v[40:43]
	v_mfma_f32_16x16x32_bf16 v[36:39], v[170:173], v[214:217], v[36:39]
	v_mfma_f32_16x16x32_bf16 v[32:35], v[178:181], v[214:217], v[32:35]
	s_setprio 0
	s_barrier
	s_add_i32 s68, s60, s51
	v_lshl_add_u64 v[194:195], s[46:47], 0, v[138:139]
	s_mov_b32 m0, s68
	ds_read_b128 v[182:185], v169 offset:16384
	ds_read_b128 v[186:189], v169 offset:17408
	ds_read_b128 v[190:193], v169 offset:18432
	ds_read_b128 v[198:201], v169 offset:19456
	ds_read_b128 v[202:205], v169 offset:20480
	ds_read_b128 v[206:209], v169 offset:21504
	ds_read_b128 v[210:213], v169 offset:22528
	ds_read_b128 v[214:217], v169 offset:23552
	global_load_lds_dwordx4 v[194:195], off
	s_add_i32 m0, s68, 0x2000
	s_add_u32 s68, s46, 0x20000
	v_lshl_add_u64 v[218:219], s[46:47], 0, v[142:143]
	s_addc_u32 s69, s47, 0
	s_add_i32 s70, s61, s51
	global_load_lds_dwordx4 v[218:219], off
	v_lshl_add_u64 v[220:221], s[68:69], 0, v[138:139]
	s_mov_b32 m0, s70
	v_lshl_add_u64 v[222:223], s[48:49], 0, v[140:141]
	global_load_lds_dwordx4 v[220:221], off
	v_lshl_add_u64 v[220:221], s[68:69], 0, v[142:143]
	s_add_i32 m0, s70, 0x2000
	s_nop 0
	global_load_lds_dwordx4 v[220:221], off
	v_lshl_add_u64 v[220:221], s[48:49], 0, v[136:137]
	s_mov_b32 m0, s35
	s_nop 0
	global_load_lds_dwordx4 v[220:221], off
	s_mov_b32 m0, s52
	s_nop 0
	global_load_lds_dwordx4 v[222:223], off
	s_waitcnt vmcnt(8)
	s_waitcnt lgkmcnt(0)
	s_barrier
; #define PG8_STAGE(bufoff, gbase, voff) do { _Pragma("unroll") for (int _i = 0; _i < 2; ++_i) \
;         __builtin_amdgcn_global_load_lds((const unsigned*)((const char*)(gbase) + (voff)[_i]), (PG8_LAS unsigned*)(lds + (bufoff) + ldsw + _i * 8192), 16, 0, 0); } while (0)
; #define PG8_LDA(dst, b, h) do { _Pragma("unroll") for (int m = 0; m < 4; ++m) _Pragma("unroll") for (int k = 0; k < 2; ++k) dst[m][k] = *(const PG8_LAS bf16x8*)(lds + PG8_SA(b, h) + aoff + m * 2048 + k * 1024); } while (0)
; #define PG8_LDB(dst, b, h) do { _Pragma("unroll") for (int n = 0; n < 2; ++n) _Pragma("unroll") for (int k = 0; k < 2; ++k) dst[n][k] = *(const PG8_LAS bf16x8*)(lds + PG8_SB(b, h) + boff + n * 2048 + k * 1024); } while (0)
; #define PG8_MMA(ai, bj, At, Bt) do { __builtin_amdgcn_s_setprio(1); _Pragma("unroll") for (int m = 0; m < 4; ++m) _Pragma("unroll") for (int n = 0; n < 2; ++n) _Pragma("unroll") for (int k = 0; k < 2; ++k) \
;         acc[ai][bj][m][n] = __builtin_amdgcn_mfma_f32_16x16x32_bf16(Bt[n][k], At[m][k], acc[ai][bj][m][n], 0, 0, 0); __builtin_amdgcn_s_setprio(0); } while (0)
; #define PG8_WAIT_V(n) asm volatile("s_waitcnt vmcnt(" #n ")" ::: "memory")
; #define PG8_WAIT_L(n) asm volatile("s_waitcnt lgkmcnt(" #n ")" ::: "memory")
; #define PG8_BAR __builtin_amdgcn_s_barrier()
; #define PG8_SCHED __builtin_amdgcn_sched_barrier(0)
; template <class Epi, class Sched, bool ALIGN_EPI = false, bool SP2 = false>
; __device__ __forceinline__ void gemm_phase(PG8_LAS unsigned char* lds, const Gemm g, const Sched& S, const Epi& E) {
;     ...
;             PG8_WAIT_V(8); PG8_WAIT_L(0); PG8_BAR; PG8_MMA(1, 0, At, B0); PG8_MMA(1, 1, At, B1); PG8_BAR; PG8_SCHED;
;             PG8_LDB(B0, 1, 0); PG8_LDB(B1, 1, 1); PG8_SCHED; PG8_LDA(At, 1, 0); PG8_STAGE(PG8_SA(0, 1), a2 + hstep, voffA);
;             PG8_WAIT_V(8); PG8_WAIT_L(0); PG8_BAR; PG8_MMA(0, 0, At, B0); PG8_MMA(0, 1, At, B1); PG8_BAR; PG8_SCHED;
	s_setprio 1
	s_waitcnt lgkmcnt(0)
	v_mfma_f32_16x16x32_bf16 v[92:95], v[112:115], v[182:185], 0
	v_mfma_f32_16x16x32_bf16 v[88:91], v[152:155], v[182:185], 0
	v_mfma_f32_16x16x32_bf16 v[84:87], v[112:115], v[190:193], 0
	v_mfma_f32_16x16x32_bf16 v[80:83], v[152:155], v[190:193], 0
	v_mfma_f32_16x16x32_bf16 v[76:79], v[112:115], v[202:205], 0
	v_mfma_f32_16x16x32_bf16 v[72:75], v[152:155], v[202:205], 0
	v_mfma_f32_16x16x32_bf16 v[68:71], v[112:115], v[210:213], 0
	v_mfma_f32_16x16x32_bf16 v[64:67], v[152:155], v[210:213], 0
	v_mfma_f32_16x16x32_bf16 v[92:95], v[116:119], v[186:189], v[92:95]
	v_mfma_f32_16x16x32_bf16 v[88:91], v[156:159], v[186:189], v[88:91]
	v_mfma_f32_16x16x32_bf16 v[84:87], v[116:119], v[198:201], v[84:87]
	v_mfma_f32_16x16x32_bf16 v[80:83], v[156:159], v[198:201], v[80:83]
	v_mfma_f32_16x16x32_bf16 v[76:79], v[116:119], v[206:209], v[76:79]
	v_mfma_f32_16x16x32_bf16 v[72:75], v[156:159], v[206:209], v[72:75]
	v_mfma_f32_16x16x32_bf16 v[68:71], v[116:119], v[214:217], v[68:71]
	v_mfma_f32_16x16x32_bf16 v[64:67], v[156:159], v[214:217], v[64:67]
	s_setprio 0
	s_setprio 1
	v_mfma_f32_16x16x32_bf16 v[28:31], v[160:163], v[182:185], 0
	v_mfma_f32_16x16x32_bf16 v[24:27], v[174:177], v[182:185], 0
	v_mfma_f32_16x16x32_bf16 v[20:23], v[160:163], v[190:193], 0
	v_mfma_f32_16x16x32_bf16 v[16:19], v[174:177], v[190:193], 0
	v_mfma_f32_16x16x32_bf16 v[12:15], v[160:163], v[202:205], 0
	v_mfma_f32_16x16x32_bf16 v[8:11], v[174:177], v[202:205], 0
	v_mfma_f32_16x16x32_bf16 v[4:7], v[160:163], v[210:213], 0
	v_mfma_f32_16x16x32_bf16 v[0:3], v[174:177], v[210:213], 0
	v_mfma_f32_16x16x32_bf16 v[28:31], v[170:173], v[186:189], v[28:31]
	v_mfma_f32_16x16x32_bf16 v[24:27], v[178:181], v[186:189], v[24:27]
	v_mfma_f32_16x16x32_bf16 v[20:23], v[170:173], v[198:201], v[20:23]
	v_mfma_f32_16x16x32_bf16 v[16:19], v[178:181], v[198:201], v[16:19]
	v_mfma_f32_16x16x32_bf16 v[12:15], v[170:173], v[206:209], v[12:15]
	v_mfma_f32_16x16x32_bf16 v[8:11], v[178:181], v[206:209], v[8:11]
	v_mfma_f32_16x16x32_bf16 v[4:7], v[170:173], v[214:217], v[4:7]
	v_mfma_f32_16x16x32_bf16 v[0:3], v[178:181], v[214:217], v[0:3]
	s_setprio 0
	s_barrier
	s_add_i32 s68, 0, 0x18000
	s_add_i32 s69, 0, 0x1c000
	v_add_u32_e32 v156, s68, v165
	v_add_u32_e32 v178, s69, v165
	ds_read_b128 v[112:115], v156
	ds_read_b128 v[116:119], v156 offset:1024
	ds_read_b128 v[152:155], v156 offset:2048
	ds_read_b128 v[156:159], v156 offset:3072
	ds_read_b128 v[160:163], v178
	ds_read_b128 v[170:173], v178 offset:1024
	ds_read_b128 v[174:177], v178 offset:2048
	ds_read_b128 v[178:181], v178 offset:3072
	s_add_u32 s48, s48, 0x20000
	s_addc_u32 s49, s49, 0
	s_mov_b32 m0, s53
	v_lshl_add_u64 v[224:225], s[48:49], 0, v[136:137]
	ds_read_b128 v[182:185], v169 offset:32768
	ds_read_b128 v[186:189], v169 offset:33792
	ds_read_b128 v[190:193], v169 offset:34816
	ds_read_b128 v[198:201], v169 offset:35840
	ds_read_b128 v[202:205], v169 offset:36864
	ds_read_b128 v[206:209], v169 offset:37888
	ds_read_b128 v[210:213], v169 offset:38912
	ds_read_b128 v[214:217], v169 offset:39936
	global_load_lds_dwordx4 v[224:225], off
	v_lshl_add_u64 v[224:225], s[48:49], 0, v[140:141]
	s_mov_b32 m0, s54
	s_nop 0
	global_load_lds_dwordx4 v[224:225], off
	s_waitcnt vmcnt(8)
	s_waitcnt lgkmcnt(0)
	s_barrier
	s_setprio 1
	s_waitcnt lgkmcnt(0)
	v_mfma_f32_16x16x32_bf16 v[132:135], v[112:115], v[182:185], v[132:135]
	v_mfma_f32_16x16x32_bf16 v[128:131], v[152:155], v[182:185], v[128:131]
	v_mfma_f32_16x16x32_bf16 v[124:127], v[112:115], v[190:193], v[124:127]
	v_mfma_f32_16x16x32_bf16 v[120:123], v[152:155], v[190:193], v[120:123]
	v_mfma_f32_16x16x32_bf16 v[108:111], v[112:115], v[202:205], v[108:111]
	v_mfma_f32_16x16x32_bf16 v[104:107], v[152:155], v[202:205], v[104:107]
	v_mfma_f32_16x16x32_bf16 v[100:103], v[112:115], v[210:213], v[100:103]
	v_mfma_f32_16x16x32_bf16 v[96:99], v[152:155], v[210:213], v[96:99]
	v_mfma_f32_16x16x32_bf16 v[132:135], v[116:119], v[186:189], v[132:135]
	v_mfma_f32_16x16x32_bf16 v[128:131], v[156:159], v[186:189], v[128:131]
	v_mfma_f32_16x16x32_bf16 v[124:127], v[116:119], v[198:201], v[124:127]
	v_mfma_f32_16x16x32_bf16 v[120:123], v[156:159], v[198:201], v[120:123]
	v_mfma_f32_16x16x32_bf16 v[108:111], v[116:119], v[206:209], v[108:111]
	v_mfma_f32_16x16x32_bf16 v[104:107], v[156:159], v[206:209], v[104:107]
	v_mfma_f32_16x16x32_bf16 v[100:103], v[116:119], v[214:217], v[100:103]
	v_mfma_f32_16x16x32_bf16 v[96:99], v[156:159], v[214:217], v[96:99]
	s_setprio 0
	s_setprio 1
	v_mfma_f32_16x16x32_bf16 v[60:63], v[160:163], v[182:185], v[60:63]
	v_mfma_f32_16x16x32_bf16 v[56:59], v[174:177], v[182:185], v[56:59]
	v_mfma_f32_16x16x32_bf16 v[52:55], v[160:163], v[190:193], v[52:55]
	v_mfma_f32_16x16x32_bf16 v[48:51], v[174:177], v[190:193], v[48:51]
	v_mfma_f32_16x16x32_bf16 v[44:47], v[160:163], v[202:205], v[44:47]
	v_mfma_f32_16x16x32_bf16 v[40:43], v[174:177], v[202:205], v[40:43]
	v_mfma_f32_16x16x32_bf16 v[36:39], v[160:163], v[210:213], v[36:39]
	v_mfma_f32_16x16x32_bf16 v[32:35], v[174:177], v[210:213], v[32:35]
	v_mfma_f32_16x16x32_bf16 v[60:63], v[170:173], v[186:189], v[60:63]
	v_mfma_f32_16x16x32_bf16 v[56:59], v[178:181], v[186:189], v[56:59]
	v_mfma_f32_16x16x32_bf16 v[52:55], v[170:173], v[198:201], v[52:55]
	v_mfma_f32_16x16x32_bf16 v[48:51], v[178:181], v[198:201], v[48:51]
	v_mfma_f32_16x16x32_bf16 v[44:47], v[170:173], v[206:209], v[44:47]
	v_mfma_f32_16x16x32_bf16 v[40:43], v[178:181], v[206:209], v[40:43]
	v_mfma_f32_16x16x32_bf16 v[36:39], v[170:173], v[214:217], v[36:39]
	v_mfma_f32_16x16x32_bf16 v[32:35], v[178:181], v[214:217], v[32:35]
	s_setprio 0
	s_barrier
; #define PG8_STAGE(bufoff, gbase, voff) do { _Pragma("unroll") for (int _i = 0; _i < 2; ++_i) \
;         __builtin_amdgcn_global_load_lds((const unsigned*)((const char*)(gbase) + (voff)[_i]), (PG8_LAS unsigned*)(lds + (bufoff) + ldsw + _i * 8192), 16, 0, 0); } while (0)
; #define PG8_LDA(dst, b, h) do { _Pragma("unroll") for (int m = 0; m < 4; ++m) _Pragma("unroll") for (int k = 0; k < 2; ++k) dst[m][k] = *(const PG8_LAS bf16x8*)(lds + PG8_SA(b, h) + aoff + m * 2048 + k * 1024); } while (0)
; #define PG8_MMA(ai, bj, At, Bt) do { __builtin_amdgcn_s_setprio(1); _Pragma("unroll") for (int m = 0; m < 4; ++m) _Pragma("unroll") for (int n = 0; n < 2; ++n) _Pragma("unroll") for (int k = 0; k < 2; ++k) \
;         acc[ai][bj][m][n] = __builtin_amdgcn_mfma_f32_16x16x32_bf16(Bt[n][k], At[m][k], acc[ai][bj][m][n], 0, 0, 0); __builtin_amdgcn_s_setprio(0); } while (0)
; #define PG8_WAIT_V(n) asm volatile("s_waitcnt vmcnt(" #n ")" ::: "memory")
; #define PG8_WAIT_L(n) asm volatile("s_waitcnt lgkmcnt(" #n ")" ::: "memory")
; #define PG8_BAR __builtin_amdgcn_s_barrier()
; #define PG8_SCHED __builtin_amdgcn_sched_barrier(0)
; template <class Epi, class Sched, bool ALIGN_EPI = false, bool SP2 = false>
; __device__ __forceinline__ void gemm_phase(PG8_LAS unsigned char* lds, const Gemm g, const Sched& S, const Epi& E) {
;     ...
;         for (int t = 0; t < nt; t += 2) {
;     ...
;             PG8_LDA(At, 1, 1); PG8_STAGE(PG8_SB(1, 0), b3, voffB); PG8_STAGE(PG8_SB(1, 1), b3 + hstep, voffB); PG8_STAGE(PG8_SA(1, 0), a3, voffA);
;             PG8_WAIT_V(8); PG8_WAIT_L(0); PG8_BAR; PG8_MMA(1, 0, At, B0); PG8_MMA(1, 1, At, B1); PG8_BAR; PG8_SCHED;
	s_add_i32 s48, s68, s51
	v_lshl_add_u64 v[194:195], v[194:195], 0, s[10:11]
	s_mov_b32 m0, s48
	ds_read_b128 v[182:185], v169 offset:49152
	ds_read_b128 v[186:189], v169 offset:50176
	ds_read_b128 v[190:193], v169 offset:51200
	ds_read_b128 v[198:201], v169 offset:52224
	ds_read_b128 v[202:205], v169 offset:53248
	ds_read_b128 v[206:209], v169 offset:54272
	ds_read_b128 v[210:213], v169 offset:55296
	ds_read_b128 v[214:217], v169 offset:56320
	global_load_lds_dwordx4 v[194:195], off
	s_add_i32 m0, s48, 0x2000
	s_add_u32 s46, s46, 0x20080
	v_lshl_add_u64 v[194:195], v[218:219], 0, s[10:11]
	s_addc_u32 s47, s47, 0
	s_add_i32 s48, s69, s51
	global_load_lds_dwordx4 v[194:195], off
	v_lshl_add_u64 v[194:195], s[46:47], 0, v[138:139]
	s_mov_b32 m0, s48
	s_nop 0
	global_load_lds_dwordx4 v[194:195], off
	v_lshl_add_u64 v[194:195], s[46:47], 0, v[142:143]
	s_add_i32 m0, s48, 0x2000
	s_nop 0
	global_load_lds_dwordx4 v[194:195], off
	v_lshl_add_u64 v[194:195], v[220:221], 0, s[10:11]
	s_mov_b32 m0, s56
	s_nop 0
	global_load_lds_dwordx4 v[194:195], off
	v_lshl_add_u64 v[194:195], v[222:223], 0, s[10:11]
	s_mov_b32 m0, s57
	s_nop 0
	global_load_lds_dwordx4 v[194:195], off
	s_waitcnt vmcnt(8)
	s_waitcnt lgkmcnt(0)
	s_barrier
	s_setprio 1
	s_waitcnt lgkmcnt(0)
	v_mfma_f32_16x16x32_bf16 v[92:95], v[112:115], v[182:185], v[92:95]
	v_mfma_f32_16x16x32_bf16 v[88:91], v[152:155], v[182:185], v[88:91]
	v_mfma_f32_16x16x32_bf16 v[84:87], v[112:115], v[190:193], v[84:87]
	v_mfma_f32_16x16x32_bf16 v[80:83], v[152:155], v[190:193], v[80:83]
	v_mfma_f32_16x16x32_bf16 v[76:79], v[112:115], v[202:205], v[76:79]
	v_mfma_f32_16x16x32_bf16 v[72:75], v[152:155], v[202:205], v[72:75]
	v_mfma_f32_16x16x32_bf16 v[68:71], v[112:115], v[210:213], v[68:71]
	v_mfma_f32_16x16x32_bf16 v[64:67], v[152:155], v[210:213], v[64:67]
	v_mfma_f32_16x16x32_bf16 v[92:95], v[116:119], v[186:189], v[92:95]
	v_mfma_f32_16x16x32_bf16 v[88:91], v[156:159], v[186:189], v[88:91]
	v_mfma_f32_16x16x32_bf16 v[84:87], v[116:119], v[198:201], v[84:87]
	v_mfma_f32_16x16x32_bf16 v[80:83], v[156:159], v[198:201], v[80:83]
	v_mfma_f32_16x16x32_bf16 v[76:79], v[116:119], v[206:209], v[76:79]
	v_mfma_f32_16x16x32_bf16 v[72:75], v[156:159], v[206:209], v[72:75]
	v_mfma_f32_16x16x32_bf16 v[68:71], v[116:119], v[214:217], v[68:71]
	v_mfma_f32_16x16x32_bf16 v[64:67], v[156:159], v[214:217], v[64:67]
	s_setprio 0
	s_setprio 1
	v_mfma_f32_16x16x32_bf16 v[28:31], v[160:163], v[182:185], v[28:31]
	v_mfma_f32_16x16x32_bf16 v[24:27], v[174:177], v[182:185], v[24:27]
	v_mfma_f32_16x16x32_bf16 v[20:23], v[160:163], v[190:193], v[20:23]
	v_mfma_f32_16x16x32_bf16 v[16:19], v[174:177], v[190:193], v[16:19]
	v_mfma_f32_16x16x32_bf16 v[12:15], v[160:163], v[202:205], v[12:15]
	v_mfma_f32_16x16x32_bf16 v[8:11], v[174:177], v[202:205], v[8:11]
	v_mfma_f32_16x16x32_bf16 v[4:7], v[160:163], v[210:213], v[4:7]
	v_mfma_f32_16x16x32_bf16 v[0:3], v[174:177], v[210:213], v[0:3]
	v_mfma_f32_16x16x32_bf16 v[28:31], v[170:173], v[186:189], v[28:31]
	v_mfma_f32_16x16x32_bf16 v[24:27], v[178:181], v[186:189], v[24:27]
	v_mfma_f32_16x16x32_bf16 v[20:23], v[170:173], v[198:201], v[20:23]
	v_mfma_f32_16x16x32_bf16 v[16:19], v[178:181], v[198:201], v[16:19]
	v_mfma_f32_16x16x32_bf16 v[12:15], v[170:173], v[206:209], v[12:15]
	v_mfma_f32_16x16x32_bf16 v[8:11], v[178:181], v[206:209], v[8:11]
	v_mfma_f32_16x16x32_bf16 v[4:7], v[170:173], v[214:217], v[4:7]
	v_mfma_f32_16x16x32_bf16 v[0:3], v[178:181], v[214:217], v[0:3]
	s_setprio 0
	s_barrier
	s_add_i32 s67, s67, 2
	s_add_u32 s20, s20, 0x100
	s_addc_u32 s21, s21, 0
	s_add_u32 s65, s65, 0x100
	s_addc_u32 s66, s66, 0
	s_cmp_gt_u32 s67, 5

; #define PG8_STAGE(bufoff, gbase, voff) do { _Pragma("unroll") for (int _i = 0; _i < 2; ++_i) \
;         __builtin_amdgcn_global_load_lds((const unsigned*)((const char*)(gbase) + (voff)[_i]), (PG8_LAS unsigned*)(lds + (bufoff) + ldsw + _i * 8192), 16, 0, 0); } while (0)
; #define PG8_LDA(dst, b, h) do { _Pragma("unroll") for (int m = 0; m < 4; ++m) _Pragma("unroll") for (int k = 0; k < 2; ++k) dst[m][k] = *(const PG8_LAS bf16x8*)(lds + PG8_SA(b, h) + aoff + m * 2048 + k * 1024); } while (0)
; #define PG8_LDB(dst, b, h) do { _Pragma("unroll") for (int n = 0; n < 2; ++n) _Pragma("unroll") for (int k = 0; k < 2; ++k) dst[n][k] = *(const PG8_LAS bf16x8*)(lds + PG8_SB(b, h) + boff + n * 2048 + k * 1024); } while (0)
; #define PG8_WAIT_V(n) asm volatile("s_waitcnt vmcnt(" #n ")" ::: "memory")
; #define PG8_WAIT_L(n) asm volatile("s_waitcnt lgkmcnt(" #n ")" ::: "memory")
; #define PG8_BAR __builtin_amdgcn_s_barrier()
; #define PG8_SCHED __builtin_amdgcn_sched_barrier(0)
; template <class Epi, class Sched, bool ALIGN_EPI = false, bool SP2 = false>
; __device__ __forceinline__ void gemm_phase(PG8_LAS unsigned char* lds, const Gemm g, const Sched& S, const Epi& E) {
;     ...
;         const bool has_next = S.next(ui + 1, nxt);
;         const char* nA = has_next ? (const char*)g.A + (size_t)nxt.pm * tstep : cA; const char* nB = has_next ? (const char*)g.Bt + (size_t)nxt.pn * tstep : cB;
;         for (int t = 0; t < nt; t += 2) {
;             const bool last = (t == nt - 2);
;             const char* a1 = cA + (size_t)(t + 1) * kstep;
;             const char* a2 = last ? nA : cA + (size_t)(t + 2) * kstep; const char* b2 = last ? nB : cB + (size_t)(t + 2) * kstep;
;             const char* a3 = a2 + kstep; const char* b3 = b2 + kstep;
;             if (last && has_next) S.a_ready(nxt);
;             if constexpr (SP2) {
;             PG8_LDB(B0, 0, 0); PG8_LDB(B1, 0, 1); PG8_SCHED; PG8_LDA(At, 0, 0); PG8_STAGE(PG8_SA(1, 1), a1 + hstep, voffA);
;             PG8_WAIT_V(8); PG8_WAIT_L(0); PG8_BAR; PG8_MMA(0, 0, At, B0); PG8_MMA(0, 1, At, B1); PG8_BAR; PG8_SCHED;
;             PG8_LDA(At, 0, 1); PG8_STAGE(PG8_SB(0, 0), b2, voffB); PG8_STAGE(PG8_SB(0, 1), b2 + hstep, voffB); PG8_STAGE(PG8_SA(0, 0), a2, voffA);
;             PG8_WAIT_V(8); PG8_WAIT_L(0); PG8_BAR; PG8_MMA(1, 0, At, B0); PG8_MMA(1, 1, At, B1); PG8_BAR; PG8_SCHED;
.LBB0_704:
	s_ashr_i32 s47, s46, 31
	s_lshl_b64 s[48:49], s[46:47], 19
	s_add_u32 s48, s42, s48
	s_addc_u32 s49, s43, s49
	s_and_b64 s[50:51], s[6:7], exec
	s_cselect_b32 s35, s49, s21
	s_cselect_b32 s47, s48, s20
	s_ashr_i32 s45, s44, 31
	s_lshl_b64 s[50:51], s[44:45], 19
	s_add_u32 s50, s3, s50
	s_addc_u32 s51, s33, s51
	s_and_b64 s[56:57], s[6:7], exec
	s_cselect_b32 s45, s51, s55
	s_cselect_b32 s73, s50, s54
	s_add_u32 s20, s20, 0x40080
	s_addc_u32 s21, s21, 0
	s_add_u32 s74, s54, 0x100
	s_addc_u32 s75, s55, 0
	s_mov_b32 s76, -2
	s_waitcnt lgkmcnt(0)
	ds_read_b128 v[96:99], v223
	ds_read_b128 v[108:111], v223 offset:1024
	ds_read_b128 v[120:123], v223 offset:2048
	ds_read_b128 v[128:131], v223 offset:3072
	ds_read_b128 v[144:147], v224
	ds_read_b128 v[148:151], v224 offset:1024
	ds_read_b128 v[152:155], v224 offset:2048
	ds_read_b128 v[156:159], v224 offset:3072
	s_add_u32 s54, s20, 0xfffc0080
	s_addc_u32 s55, s21, -1
	s_cmp_eq_u32 s76, 12
	s_cselect_b32 s57, s35, s55
	s_cselect_b32 s56, s47, s54
	s_cselect_b32 s55, s45, s75
	s_cselect_b32 s54, s73, s74
	v_lshl_add_u64 v[210:211], s[20:21], 0, v[192:193]
	s_add_i32 m0, s53, 0xc000
	ds_read_b128 v[160:163], v225
	ds_read_b128 v[164:167], v225 offset:1024
	ds_read_b128 v[168:171], v225 offset:2048
	ds_read_b128 v[172:175], v225 offset:3072
	ds_read_b128 v[176:179], v225 offset:4096
	ds_read_b128 v[180:183], v225 offset:5120
	ds_read_b128 v[202:205], v225 offset:6144
	ds_read_b128 v[206:209], v225 offset:7168
	global_load_lds_dwordx4 v[210:211], off
	v_lshl_add_u64 v[210:211], s[20:21], 0, v[194:195]
	s_add_i32 m0, s53, 0xe000
	s_nop 0
	global_load_lds_dwordx4 v[210:211], off
	s_waitcnt vmcnt(8)
	s_waitcnt lgkmcnt(0)
	s_barrier
	s_setprio 1
	s_waitcnt lgkmcnt(0)
	v_mfma_f32_16x16x32_bf16 v[140:143], v[96:99], v[160:163], 0
	v_mfma_f32_16x16x32_bf16 v[136:139], v[120:123], v[160:163], 0
	v_mfma_f32_16x16x32_bf16 v[116:119], v[96:99], v[168:171], 0
	v_mfma_f32_16x16x32_bf16 v[112:115], v[120:123], v[168:171], 0
	v_mfma_f32_16x16x32_bf16 v[92:95], v[96:99], v[176:179], 0
	v_mfma_f32_16x16x32_bf16 v[88:91], v[120:123], v[176:179], 0
	v_mfma_f32_16x16x32_bf16 v[76:79], v[96:99], v[202:205], 0
	v_mfma_f32_16x16x32_bf16 v[72:75], v[120:123], v[202:205], 0
	v_mfma_f32_16x16x32_bf16 v[140:143], v[108:111], v[164:167], v[140:143]
	v_mfma_f32_16x16x32_bf16 v[136:139], v[128:131], v[164:167], v[136:139]
	v_mfma_f32_16x16x32_bf16 v[116:119], v[108:111], v[172:175], v[116:119]
	v_mfma_f32_16x16x32_bf16 v[112:115], v[128:131], v[172:175], v[112:115]
	v_mfma_f32_16x16x32_bf16 v[92:95], v[108:111], v[180:183], v[92:95]
	v_mfma_f32_16x16x32_bf16 v[88:91], v[128:131], v[180:183], v[88:91]
	v_mfma_f32_16x16x32_bf16 v[76:79], v[108:111], v[206:209], v[76:79]
	v_mfma_f32_16x16x32_bf16 v[72:75], v[128:131], v[206:209], v[72:75]
	s_setprio 0
	s_setprio 1
	v_mfma_f32_16x16x32_bf16 v[132:135], v[144:147], v[160:163], 0
	v_mfma_f32_16x16x32_bf16 v[124:127], v[152:155], v[160:163], 0
	v_mfma_f32_16x16x32_bf16 v[104:107], v[144:147], v[168:171], 0
	v_mfma_f32_16x16x32_bf16 v[100:103], v[152:155], v[168:171], 0
	v_mfma_f32_16x16x32_bf16 v[84:87], v[144:147], v[176:179], 0
	v_mfma_f32_16x16x32_bf16 v[80:83], v[152:155], v[176:179], 0
	v_mfma_f32_16x16x32_bf16 v[68:71], v[144:147], v[202:205], 0
	v_mfma_f32_16x16x32_bf16 v[64:67], v[152:155], v[202:205], 0
	v_mfma_f32_16x16x32_bf16 v[132:135], v[148:151], v[164:167], v[132:135]
	v_mfma_f32_16x16x32_bf16 v[124:127], v[156:159], v[164:167], v[124:127]
	v_mfma_f32_16x16x32_bf16 v[104:107], v[148:151], v[172:175], v[104:107]
	v_mfma_f32_16x16x32_bf16 v[100:103], v[156:159], v[172:175], v[100:103]
	v_mfma_f32_16x16x32_bf16 v[84:87], v[148:151], v[180:183], v[84:87]
	v_mfma_f32_16x16x32_bf16 v[80:83], v[156:159], v[180:183], v[80:83]
	v_mfma_f32_16x16x32_bf16 v[68:71], v[148:151], v[206:209], v[68:71]
	v_mfma_f32_16x16x32_bf16 v[64:67], v[156:159], v[206:209], v[64:67]
	s_setprio 0
	s_barrier
	s_add_i32 s77, s71, s58
	v_lshl_add_u64 v[210:211], s[54:55], 0, v[186:187]
	s_mov_b32 m0, s77
	ds_read_b128 v[160:163], v225 offset:16384
	ds_read_b128 v[164:167], v225 offset:17408
	ds_read_b128 v[168:171], v225 offset:18432
	ds_read_b128 v[172:175], v225 offset:19456
	ds_read_b128 v[176:179], v225 offset:20480
	ds_read_b128 v[180:183], v225 offset:21504
	ds_read_b128 v[202:205], v225 offset:22528
	ds_read_b128 v[206:209], v225 offset:23552
	global_load_lds_dwordx4 v[210:211], off
	s_add_i32 m0, s77, 0x2000
	s_add_u32 s78, s54, 0x40000
	v_lshl_add_u64 v[212:213], s[54:55], 0, v[190:191]
	s_addc_u32 s79, s55, 0
	s_add_i32 s77, s72, s58
	global_load_lds_dwordx4 v[212:213], off
	v_lshl_add_u64 v[214:215], s[78:79], 0, v[186:187]
	s_mov_b32 m0, s77
	v_lshl_add_u64 v[216:217], s[56:57], 0, v[188:189]
	global_load_lds_dwordx4 v[214:215], off
	v_lshl_add_u64 v[214:215], s[78:79], 0, v[190:191]
	s_add_i32 m0, s77, 0x2000
	s_nop 0
	global_load_lds_dwordx4 v[214:215], off
	v_lshl_add_u64 v[214:215], s[56:57], 0, v[184:185]
	s_mov_b32 m0, s53
	s_nop 0
	global_load_lds_dwordx4 v[214:215], off
	s_mov_b32 m0, s59
	s_nop 0
	global_load_lds_dwordx4 v[216:217], off
	s_waitcnt vmcnt(8)
	s_waitcnt lgkmcnt(0)
	s_barrier
; #define PG8_STAGE(bufoff, gbase, voff) do { _Pragma("unroll") for (int _i = 0; _i < 2; ++_i) \
;         __builtin_amdgcn_global_load_lds((const unsigned*)((const char*)(gbase) + (voff)[_i]), (PG8_LAS unsigned*)(lds + (bufoff) + ldsw + _i * 8192), 16, 0, 0); } while (0)
; #define PG8_LDA(dst, b, h) do { _Pragma("unroll") for (int m = 0; m < 4; ++m) _Pragma("unroll") for (int k = 0; k < 2; ++k) dst[m][k] = *(const PG8_LAS bf16x8*)(lds + PG8_SA(b, h) + aoff + m * 2048 + k * 1024); } while (0)
; #define PG8_LDB(dst, b, h) do { _Pragma("unroll") for (int n = 0; n < 2; ++n) _Pragma("unroll") for (int k = 0; k < 2; ++k) dst[n][k] = *(const PG8_LAS bf16x8*)(lds + PG8_SB(b, h) + boff + n * 2048 + k * 1024); } while (0)
; #define PG8_MMA(ai, bj, At, Bt) do { __builtin_amdgcn_s_setprio(1); _Pragma("unroll") for (int m = 0; m < 4; ++m) _Pragma("unroll") for (int n = 0; n < 2; ++n) _Pragma("unroll") for (int k = 0; k < 2; ++k) \
;         acc[ai][bj][m][n] = __builtin_amdgcn_mfma_f32_16x16x32_bf16(Bt[n][k], At[m][k], acc[ai][bj][m][n], 0, 0, 0); __builtin_amdgcn_s_setprio(0); } while (0)
; #define PG8_WAIT_V(n) asm volatile("s_waitcnt vmcnt(" #n ")" ::: "memory")
; #define PG8_WAIT_L(n) asm volatile("s_waitcnt lgkmcnt(" #n ")" ::: "memory")
; #define PG8_BAR __builtin_amdgcn_s_barrier()
; #define PG8_SCHED __builtin_amdgcn_sched_barrier(0)
; template <class Epi, class Sched, bool ALIGN_EPI = false, bool SP2 = false>
; __device__ __forceinline__ void gemm_phase(PG8_LAS unsigned char* lds, const Gemm g, const Sched& S, const Epi& E) {
;     ...
;             PG8_WAIT_V(8); PG8_WAIT_L(0); PG8_BAR; PG8_MMA(1, 0, At, B0); PG8_MMA(1, 1, At, B1); PG8_BAR; PG8_SCHED;
;             PG8_LDB(B0, 1, 0); PG8_LDB(B1, 1, 1); PG8_SCHED; PG8_LDA(At, 1, 0); PG8_STAGE(PG8_SA(0, 1), a2 + hstep, voffA);
;             PG8_WAIT_V(8); PG8_WAIT_L(0); PG8_BAR; PG8_MMA(0, 0, At, B0); PG8_MMA(0, 1, At, B1); PG8_BAR; PG8_SCHED;
	s_setprio 1
	s_waitcnt lgkmcnt(0)
	v_mfma_f32_16x16x32_bf16 v[60:63], v[96:99], v[160:163], 0
	v_mfma_f32_16x16x32_bf16 v[56:59], v[120:123], v[160:163], 0
	v_mfma_f32_16x16x32_bf16 v[44:47], v[96:99], v[168:171], 0
	v_mfma_f32_16x16x32_bf16 v[40:43], v[120:123], v[168:171], 0
	v_mfma_f32_16x16x32_bf16 v[28:31], v[96:99], v[176:179], 0
	v_mfma_f32_16x16x32_bf16 v[24:27], v[120:123], v[176:179], 0
	v_mfma_f32_16x16x32_bf16 v[12:15], v[96:99], v[202:205], 0
	v_mfma_f32_16x16x32_bf16 v[8:11], v[120:123], v[202:205], 0
	v_mfma_f32_16x16x32_bf16 v[60:63], v[108:111], v[164:167], v[60:63]
	v_mfma_f32_16x16x32_bf16 v[56:59], v[128:131], v[164:167], v[56:59]
	v_mfma_f32_16x16x32_bf16 v[44:47], v[108:111], v[172:175], v[44:47]
	v_mfma_f32_16x16x32_bf16 v[40:43], v[128:131], v[172:175], v[40:43]
	v_mfma_f32_16x16x32_bf16 v[28:31], v[108:111], v[180:183], v[28:31]
	v_mfma_f32_16x16x32_bf16 v[24:27], v[128:131], v[180:183], v[24:27]
	v_mfma_f32_16x16x32_bf16 v[12:15], v[108:111], v[206:209], v[12:15]
	v_mfma_f32_16x16x32_bf16 v[8:11], v[128:131], v[206:209], v[8:11]
	s_setprio 0
	s_setprio 1
	v_mfma_f32_16x16x32_bf16 v[52:55], v[144:147], v[160:163], 0
	v_mfma_f32_16x16x32_bf16 v[48:51], v[152:155], v[160:163], 0
	v_mfma_f32_16x16x32_bf16 v[36:39], v[144:147], v[168:171], 0
	v_mfma_f32_16x16x32_bf16 v[32:35], v[152:155], v[168:171], 0
	v_mfma_f32_16x16x32_bf16 v[20:23], v[144:147], v[176:179], 0
	v_mfma_f32_16x16x32_bf16 v[16:19], v[152:155], v[176:179], 0
	v_mfma_f32_16x16x32_bf16 v[4:7], v[144:147], v[202:205], 0
	v_mfma_f32_16x16x32_bf16 v[0:3], v[152:155], v[202:205], 0
	v_mfma_f32_16x16x32_bf16 v[52:55], v[148:151], v[164:167], v[52:55]
	v_mfma_f32_16x16x32_bf16 v[48:51], v[156:159], v[164:167], v[48:51]
	v_mfma_f32_16x16x32_bf16 v[36:39], v[148:151], v[172:175], v[36:39]
	v_mfma_f32_16x16x32_bf16 v[32:35], v[156:159], v[172:175], v[32:35]
	v_mfma_f32_16x16x32_bf16 v[20:23], v[148:151], v[180:183], v[20:23]
	v_mfma_f32_16x16x32_bf16 v[16:19], v[156:159], v[180:183], v[16:19]
	v_mfma_f32_16x16x32_bf16 v[4:7], v[148:151], v[206:209], v[4:7]
	v_mfma_f32_16x16x32_bf16 v[0:3], v[156:159], v[206:209], v[0:3]
	s_setprio 0
	s_barrier
	s_add_i32 s77, 0, 0x18000
	s_add_i32 s78, 0, 0x1c000
	v_add_u32_e32 v128, s77, v221
	v_add_u32_e32 v156, s78, v221
	ds_read_b128 v[96:99], v128
	ds_read_b128 v[108:111], v128 offset:1024
	ds_read_b128 v[120:123], v128 offset:2048
	ds_read_b128 v[128:131], v128 offset:3072
	ds_read_b128 v[144:147], v156
	ds_read_b128 v[148:151], v156 offset:1024
	ds_read_b128 v[152:155], v156 offset:2048
	ds_read_b128 v[156:159], v156 offset:3072
	s_add_u32 s56, s56, 0x40000
	s_addc_u32 s57, s57, 0
	s_mov_b32 m0, s60
	v_lshl_add_u64 v[218:219], s[56:57], 0, v[184:185]
	ds_read_b128 v[160:163], v225 offset:32768
	ds_read_b128 v[164:167], v225 offset:33792
	ds_read_b128 v[168:171], v225 offset:34816
	ds_read_b128 v[172:175], v225 offset:35840
	ds_read_b128 v[176:179], v225 offset:36864
	ds_read_b128 v[180:183], v225 offset:37888
	ds_read_b128 v[202:205], v225 offset:38912
	ds_read_b128 v[206:209], v225 offset:39936
	global_load_lds_dwordx4 v[218:219], off
	v_lshl_add_u64 v[218:219], s[56:57], 0, v[188:189]
	s_mov_b32 m0, s61
	s_nop 0
	global_load_lds_dwordx4 v[218:219], off
	s_waitcnt vmcnt(8)
	s_waitcnt lgkmcnt(0)
	s_barrier
	s_setprio 1
	s_waitcnt lgkmcnt(0)
	v_mfma_f32_16x16x32_bf16 v[140:143], v[96:99], v[160:163], v[140:143]
	v_mfma_f32_16x16x32_bf16 v[136:139], v[120:123], v[160:163], v[136:139]
	v_mfma_f32_16x16x32_bf16 v[116:119], v[96:99], v[168:171], v[116:119]
	v_mfma_f32_16x16x32_bf16 v[112:115], v[120:123], v[168:171], v[112:115]
	v_mfma_f32_16x16x32_bf16 v[92:95], v[96:99], v[176:179], v[92:95]
	v_mfma_f32_16x16x32_bf16 v[88:91], v[120:123], v[176:179], v[88:91]
	v_mfma_f32_16x16x32_bf16 v[76:79], v[96:99], v[202:205], v[76:79]
	v_mfma_f32_16x16x32_bf16 v[72:75], v[120:123], v[202:205], v[72:75]
	v_mfma_f32_16x16x32_bf16 v[140:143], v[108:111], v[164:167], v[140:143]
	v_mfma_f32_16x16x32_bf16 v[136:139], v[128:131], v[164:167], v[136:139]
	v_mfma_f32_16x16x32_bf16 v[116:119], v[108:111], v[172:175], v[116:119]
	v_mfma_f32_16x16x32_bf16 v[112:115], v[128:131], v[172:175], v[112:115]
	v_mfma_f32_16x16x32_bf16 v[92:95], v[108:111], v[180:183], v[92:95]
	v_mfma_f32_16x16x32_bf16 v[88:91], v[128:131], v[180:183], v[88:91]
	v_mfma_f32_16x16x32_bf16 v[76:79], v[108:111], v[206:209], v[76:79]
	v_mfma_f32_16x16x32_bf16 v[72:75], v[128:131], v[206:209], v[72:75]
	s_setprio 0
	s_setprio 1
	v_mfma_f32_16x16x32_bf16 v[132:135], v[144:147], v[160:163], v[132:135]
	v_mfma_f32_16x16x32_bf16 v[124:127], v[152:155], v[160:163], v[124:127]
	v_mfma_f32_16x16x32_bf16 v[104:107], v[144:147], v[168:171], v[104:107]
	v_mfma_f32_16x16x32_bf16 v[100:103], v[152:155], v[168:171], v[100:103]
	v_mfma_f32_16x16x32_bf16 v[84:87], v[144:147], v[176:179], v[84:87]
	v_mfma_f32_16x16x32_bf16 v[80:83], v[152:155], v[176:179], v[80:83]
	v_mfma_f32_16x16x32_bf16 v[68:71], v[144:147], v[202:205], v[68:71]
	v_mfma_f32_16x16x32_bf16 v[64:67], v[152:155], v[202:205], v[64:67]
	v_mfma_f32_16x16x32_bf16 v[132:135], v[148:151], v[164:167], v[132:135]
	v_mfma_f32_16x16x32_bf16 v[124:127], v[156:159], v[164:167], v[124:127]
	v_mfma_f32_16x16x32_bf16 v[104:107], v[148:151], v[172:175], v[104:107]
	v_mfma_f32_16x16x32_bf16 v[100:103], v[156:159], v[172:175], v[100:103]
	v_mfma_f32_16x16x32_bf16 v[84:87], v[148:151], v[180:183], v[84:87]
	v_mfma_f32_16x16x32_bf16 v[80:83], v[156:159], v[180:183], v[80:83]
	v_mfma_f32_16x16x32_bf16 v[68:71], v[148:151], v[206:209], v[68:71]
	v_mfma_f32_16x16x32_bf16 v[64:67], v[156:159], v[206:209], v[64:67]
	s_setprio 0
	s_barrier
; #define PG8_STAGE(bufoff, gbase, voff) do { _Pragma("unroll") for (int _i = 0; _i < 2; ++_i) \
;         __builtin_amdgcn_global_load_lds((const unsigned*)((const char*)(gbase) + (voff)[_i]), (PG8_LAS unsigned*)(lds + (bufoff) + ldsw + _i * 8192), 16, 0, 0); } while (0)
; #define PG8_LDA(dst, b, h) do { _Pragma("unroll") for (int m = 0; m < 4; ++m) _Pragma("unroll") for (int k = 0; k < 2; ++k) dst[m][k] = *(const PG8_LAS bf16x8*)(lds + PG8_SA(b, h) + aoff + m * 2048 + k * 1024); } while (0)
; #define PG8_MMA(ai, bj, At, Bt) do { __builtin_amdgcn_s_setprio(1); _Pragma("unroll") for (int m = 0; m < 4; ++m) _Pragma("unroll") for (int n = 0; n < 2; ++n) _Pragma("unroll") for (int k = 0; k < 2; ++k) \
;         acc[ai][bj][m][n] = __builtin_amdgcn_mfma_f32_16x16x32_bf16(Bt[n][k], At[m][k], acc[ai][bj][m][n], 0, 0, 0); __builtin_amdgcn_s_setprio(0); } while (0)
; #define PG8_WAIT_V(n) asm volatile("s_waitcnt vmcnt(" #n ")" ::: "memory")
; #define PG8_WAIT_L(n) asm volatile("s_waitcnt lgkmcnt(" #n ")" ::: "memory")
; #define PG8_BAR __builtin_amdgcn_s_barrier()
; #define PG8_SCHED __builtin_amdgcn_sched_barrier(0)
; template <class Epi, class Sched, bool ALIGN_EPI = false, bool SP2 = false>
; __device__ __forceinline__ void gemm_phase(PG8_LAS unsigned char* lds, const Gemm g, const Sched& S, const Epi& E) {
;     ...
;         for (int t = 0; t < nt; t += 2) {
;     ...
;             PG8_LDA(At, 1, 1); PG8_STAGE(PG8_SB(1, 0), b3, voffB); PG8_STAGE(PG8_SB(1, 1), b3 + hstep, voffB); PG8_STAGE(PG8_SA(1, 0), a3, voffA);
;             PG8_WAIT_V(8); PG8_WAIT_L(0); PG8_BAR; PG8_MMA(1, 0, At, B0); PG8_MMA(1, 1, At, B1); PG8_BAR; PG8_SCHED;
	s_add_i32 s56, s77, s58
	v_lshl_add_u64 v[210:211], v[210:211], 0, s[12:13]
	s_mov_b32 m0, s56
	ds_read_b128 v[160:163], v225 offset:49152
	ds_read_b128 v[164:167], v225 offset:50176
	ds_read_b128 v[168:171], v225 offset:51200
	ds_read_b128 v[172:175], v225 offset:52224
	ds_read_b128 v[176:179], v225 offset:53248
	ds_read_b128 v[180:183], v225 offset:54272
	ds_read_b128 v[202:205], v225 offset:55296
	ds_read_b128 v[206:209], v225 offset:56320
	global_load_lds_dwordx4 v[210:211], off
	s_add_i32 m0, s56, 0x2000
	s_add_u32 s54, s54, 0x40080
	v_lshl_add_u64 v[210:211], v[212:213], 0, s[12:13]
	s_addc_u32 s55, s55, 0
	s_add_i32 s56, s78, s58
	global_load_lds_dwordx4 v[210:211], off
	v_lshl_add_u64 v[210:211], s[54:55], 0, v[186:187]
	s_mov_b32 m0, s56
	s_nop 0
	global_load_lds_dwordx4 v[210:211], off
	v_lshl_add_u64 v[210:211], s[54:55], 0, v[190:191]
	s_add_i32 m0, s56, 0x2000
	s_nop 0
	global_load_lds_dwordx4 v[210:211], off
	v_lshl_add_u64 v[210:211], v[214:215], 0, s[12:13]
	s_mov_b32 m0, s66
	s_nop 0
	global_load_lds_dwordx4 v[210:211], off
	v_lshl_add_u64 v[210:211], v[216:217], 0, s[12:13]
	s_mov_b32 m0, s67
	s_nop 0
	global_load_lds_dwordx4 v[210:211], off
	s_waitcnt vmcnt(8)
	s_waitcnt lgkmcnt(0)
	s_barrier
	s_setprio 1
	s_waitcnt lgkmcnt(0)
	v_mfma_f32_16x16x32_bf16 v[60:63], v[96:99], v[160:163], v[60:63]
	v_mfma_f32_16x16x32_bf16 v[56:59], v[120:123], v[160:163], v[56:59]
	v_mfma_f32_16x16x32_bf16 v[44:47], v[96:99], v[168:171], v[44:47]
	v_mfma_f32_16x16x32_bf16 v[40:43], v[120:123], v[168:171], v[40:43]
	v_mfma_f32_16x16x32_bf16 v[28:31], v[96:99], v[176:179], v[28:31]
	v_mfma_f32_16x16x32_bf16 v[24:27], v[120:123], v[176:179], v[24:27]
	v_mfma_f32_16x16x32_bf16 v[12:15], v[96:99], v[202:205], v[12:15]
	v_mfma_f32_16x16x32_bf16 v[8:11], v[120:123], v[202:205], v[8:11]
	v_mfma_f32_16x16x32_bf16 v[60:63], v[108:111], v[164:167], v[60:63]
	v_mfma_f32_16x16x32_bf16 v[56:59], v[128:131], v[164:167], v[56:59]
	v_mfma_f32_16x16x32_bf16 v[44:47], v[108:111], v[172:175], v[44:47]
	v_mfma_f32_16x16x32_bf16 v[40:43], v[128:131], v[172:175], v[40:43]
	v_mfma_f32_16x16x32_bf16 v[28:31], v[108:111], v[180:183], v[28:31]
	v_mfma_f32_16x16x32_bf16 v[24:27], v[128:131], v[180:183], v[24:27]
	v_mfma_f32_16x16x32_bf16 v[12:15], v[108:111], v[206:209], v[12:15]
	v_mfma_f32_16x16x32_bf16 v[8:11], v[128:131], v[206:209], v[8:11]
	s_setprio 0
	s_setprio 1
	v_mfma_f32_16x16x32_bf16 v[52:55], v[144:147], v[160:163], v[52:55]
	v_mfma_f32_16x16x32_bf16 v[48:51], v[152:155], v[160:163], v[48:51]
	v_mfma_f32_16x16x32_bf16 v[36:39], v[144:147], v[168:171], v[36:39]
	v_mfma_f32_16x16x32_bf16 v[32:35], v[152:155], v[168:171], v[32:35]
	v_mfma_f32_16x16x32_bf16 v[20:23], v[144:147], v[176:179], v[20:23]
	v_mfma_f32_16x16x32_bf16 v[16:19], v[152:155], v[176:179], v[16:19]
	v_mfma_f32_16x16x32_bf16 v[4:7], v[144:147], v[202:205], v[4:7]
	v_mfma_f32_16x16x32_bf16 v[0:3], v[152:155], v[202:205], v[0:3]
	v_mfma_f32_16x16x32_bf16 v[52:55], v[148:151], v[164:167], v[52:55]
	v_mfma_f32_16x16x32_bf16 v[48:51], v[156:159], v[164:167], v[48:51]
	v_mfma_f32_16x16x32_bf16 v[36:39], v[148:151], v[172:175], v[36:39]
	v_mfma_f32_16x16x32_bf16 v[32:35], v[156:159], v[172:175], v[32:35]
	v_mfma_f32_16x16x32_bf16 v[20:23], v[148:151], v[180:183], v[20:23]
	v_mfma_f32_16x16x32_bf16 v[16:19], v[156:159], v[180:183], v[16:19]
	v_mfma_f32_16x16x32_bf16 v[4:7], v[148:151], v[206:209], v[4:7]
	v_mfma_f32_16x16x32_bf16 v[0:3], v[156:159], v[206:209], v[0:3]
	s_setprio 0
	s_barrier
	s_add_i32 s76, s76, 2
	s_add_u32 s20, s20, 0x100
	s_addc_u32 s21, s21, 0
	s_add_u32 s74, s74, 0x100
	s_addc_u32 s75, s75, 0
	s_cmp_gt_u32 s76, 13

; #define PG8_STAGE(bufoff, gbase, voff) do { _Pragma("unroll") for (int _i = 0; _i < 2; ++_i) \
;         __builtin_amdgcn_global_load_lds((const unsigned*)((const char*)(gbase) + (voff)[_i]), (PG8_LAS unsigned*)(lds + (bufoff) + ldsw + _i * 8192), 16, 0, 0); } while (0)
; #define PG8_LDA(dst, b, h) do { _Pragma("unroll") for (int m = 0; m < 4; ++m) _Pragma("unroll") for (int k = 0; k < 2; ++k) dst[m][k] = *(const PG8_LAS bf16x8*)(lds + PG8_SA(b, h) + aoff + m * 2048 + k * 1024); } while (0)
; #define PG8_LDB(dst, b, h) do { _Pragma("unroll") for (int n = 0; n < 2; ++n) _Pragma("unroll") for (int k = 0; k < 2; ++k) dst[n][k] = *(const PG8_LAS bf16x8*)(lds + PG8_SB(b, h) + boff + n * 2048 + k * 1024); } while (0)
; #define PG8_WAIT_V(n) asm volatile("s_waitcnt vmcnt(" #n ")" ::: "memory")
; #define PG8_WAIT_L(n) asm volatile("s_waitcnt lgkmcnt(" #n ")" ::: "memory")
; #define PG8_BAR __builtin_amdgcn_s_barrier()
; #define PG8_SCHED __builtin_amdgcn_sched_barrier(0)
; template <class Epi, class Sched, bool ALIGN_EPI = false, bool SP2 = false>
; __device__ __forceinline__ void gemm_phase(PG8_LAS unsigned char* lds, const Gemm g, const Sched& S, const Epi& E) {
;     ...
;         const bool has_next = S.next(ui + 1, nxt);
;         const char* nA = has_next ? (const char*)g.A + (size_t)nxt.pm * tstep : cA; const char* nB = has_next ? (const char*)g.Bt + (size_t)nxt.pn * tstep : cB;
;         for (int t = 0; t < nt; t += 2) {
;             const bool last = (t == nt - 2);
;             const char* a1 = cA + (size_t)(t + 1) * kstep;
;             const char* a2 = last ? nA : cA + (size_t)(t + 2) * kstep; const char* b2 = last ? nB : cB + (size_t)(t + 2) * kstep;
;             const char* a3 = a2 + kstep; const char* b3 = b2 + kstep;
;             if (last && has_next) S.a_ready(nxt);
;             if constexpr (SP2) {
;             PG8_LDB(B0, 0, 0); PG8_LDB(B1, 0, 1); PG8_SCHED; PG8_LDA(At, 0, 0); PG8_STAGE(PG8_SA(1, 1), a1 + hstep, voffA);
;             PG8_WAIT_V(8); PG8_WAIT_L(0); PG8_BAR; PG8_MMA(0, 0, At, B0); PG8_MMA(0, 1, At, B1); PG8_BAR; PG8_SCHED;
;             PG8_LDA(At, 0, 1); PG8_STAGE(PG8_SB(0, 0), b2, voffB); PG8_STAGE(PG8_SB(0, 1), b2 + hstep, voffB); PG8_STAGE(PG8_SA(0, 0), a2, voffA);
;             PG8_WAIT_V(8); PG8_WAIT_L(0); PG8_BAR; PG8_MMA(1, 0, At, B0); PG8_MMA(1, 1, At, B1); PG8_BAR; PG8_SCHED;
.LBB0_809:
	s_ashr_i32 s15, s14, 31
	s_lshl_b64 s[16:17], s[14:15], 19
	s_add_u32 s16, s36, s16
	s_addc_u32 s17, s37, s17
	s_and_b64 s[18:19], s[4:5], exec
	s_cselect_b32 s15, s17, s21
	s_cselect_b32 s65, s16, s20
	s_ashr_i32 s13, s12, 31
	s_lshl_b64 s[18:19], s[12:13], 19
	s_add_u32 s18, s50, s18
	s_addc_u32 s19, s51, s19
	s_and_b64 s[44:45], s[4:5], exec
	s_cselect_b32 s13, s19, s39
	s_cselect_b32 s66, s18, s38
	s_add_u32 s20, s20, 0x40080
	s_addc_u32 s21, s21, 0
	s_add_u32 s67, s38, 0x100
	s_addc_u32 s68, s39, 0
	s_mov_b32 s69, -2
	ds_read_b128 v[154:157], v150
	ds_read_b128 v[158:161], v150 offset:1024
	ds_read_b128 v[162:165], v150 offset:2048
	ds_read_b128 v[166:169], v150 offset:3072
	ds_read_b128 v[170:173], v151
	ds_read_b128 v[174:177], v151 offset:1024
	ds_read_b128 v[178:181], v151 offset:2048
	ds_read_b128 v[182:185], v151 offset:3072
	s_add_u32 s38, s20, 0xfffc0080
	s_addc_u32 s39, s21, -1
	s_cmp_eq_u32 s69, 12
	s_cselect_b32 s45, s15, s39
	s_cselect_b32 s44, s65, s38
	s_cselect_b32 s39, s13, s68
	s_cselect_b32 s38, s66, s67
	v_lshl_add_u64 v[144:145], s[20:21], 0, v[136:137]
	s_add_i32 m0, s35, 0xc000
	ds_read_b128 v[186:189], v152
	ds_read_b128 v[190:193], v152 offset:1024
	ds_read_b128 v[198:201], v152 offset:2048
	ds_read_b128 v[202:205], v152 offset:3072
	ds_read_b128 v[206:209], v152 offset:4096
	ds_read_b128 v[210:213], v152 offset:5120
	ds_read_b128 v[214:217], v152 offset:6144
	ds_read_b128 v[218:221], v152 offset:7168
	global_load_lds_dwordx4 v[144:145], off
	v_lshl_add_u64 v[144:145], s[20:21], 0, v[138:139]
	s_add_i32 m0, s35, 0xe000
	s_nop 0
	global_load_lds_dwordx4 v[144:145], off
	s_waitcnt vmcnt(8)
	s_waitcnt lgkmcnt(0)
	s_barrier
	s_setprio 1
	s_waitcnt lgkmcnt(0)
	v_mfma_f32_16x16x32_bf16 v[124:127], v[154:157], v[186:189], 0
	v_mfma_f32_16x16x32_bf16 v[116:119], v[162:165], v[186:189], 0
	v_mfma_f32_16x16x32_bf16 v[108:111], v[154:157], v[198:201], 0
	v_mfma_f32_16x16x32_bf16 v[100:103], v[162:165], v[198:201], 0
	v_mfma_f32_16x16x32_bf16 v[92:95], v[154:157], v[206:209], 0
	v_mfma_f32_16x16x32_bf16 v[84:87], v[162:165], v[206:209], 0
	v_mfma_f32_16x16x32_bf16 v[76:79], v[154:157], v[214:217], 0
	v_mfma_f32_16x16x32_bf16 v[68:71], v[162:165], v[214:217], 0
	v_mfma_f32_16x16x32_bf16 v[124:127], v[158:161], v[190:193], v[124:127]
	v_mfma_f32_16x16x32_bf16 v[116:119], v[166:169], v[190:193], v[116:119]
	v_mfma_f32_16x16x32_bf16 v[108:111], v[158:161], v[202:205], v[108:111]
	v_mfma_f32_16x16x32_bf16 v[100:103], v[166:169], v[202:205], v[100:103]
	v_mfma_f32_16x16x32_bf16 v[92:95], v[158:161], v[210:213], v[92:95]
	v_mfma_f32_16x16x32_bf16 v[84:87], v[166:169], v[210:213], v[84:87]
	v_mfma_f32_16x16x32_bf16 v[76:79], v[158:161], v[218:221], v[76:79]
	v_mfma_f32_16x16x32_bf16 v[68:71], v[166:169], v[218:221], v[68:71]
	s_setprio 0
	s_setprio 1
	v_mfma_f32_16x16x32_bf16 v[120:123], v[170:173], v[186:189], 0
	v_mfma_f32_16x16x32_bf16 v[112:115], v[178:181], v[186:189], 0
	v_mfma_f32_16x16x32_bf16 v[104:107], v[170:173], v[198:201], 0
	v_mfma_f32_16x16x32_bf16 v[96:99], v[178:181], v[198:201], 0
	v_mfma_f32_16x16x32_bf16 v[88:91], v[170:173], v[206:209], 0
	v_mfma_f32_16x16x32_bf16 v[80:83], v[178:181], v[206:209], 0
	v_mfma_f32_16x16x32_bf16 v[72:75], v[170:173], v[214:217], 0
	v_mfma_f32_16x16x32_bf16 v[64:67], v[178:181], v[214:217], 0
	v_mfma_f32_16x16x32_bf16 v[120:123], v[174:177], v[190:193], v[120:123]
	v_mfma_f32_16x16x32_bf16 v[112:115], v[182:185], v[190:193], v[112:115]
	v_mfma_f32_16x16x32_bf16 v[104:107], v[174:177], v[202:205], v[104:107]
	v_mfma_f32_16x16x32_bf16 v[96:99], v[182:185], v[202:205], v[96:99]
	v_mfma_f32_16x16x32_bf16 v[88:91], v[174:177], v[210:213], v[88:91]
	v_mfma_f32_16x16x32_bf16 v[80:83], v[182:185], v[210:213], v[80:83]
	v_mfma_f32_16x16x32_bf16 v[72:75], v[174:177], v[218:221], v[72:75]
	v_mfma_f32_16x16x32_bf16 v[64:67], v[182:185], v[218:221], v[64:67]
	s_setprio 0
	s_barrier
	s_add_i32 s70, s60, s52
	v_lshl_add_u64 v[144:145], s[38:39], 0, v[132:133]
	s_mov_b32 m0, s70
	ds_read_b128 v[186:189], v152 offset:16384
	ds_read_b128 v[190:193], v152 offset:17408
	ds_read_b128 v[198:201], v152 offset:18432
	ds_read_b128 v[202:205], v152 offset:19456
	ds_read_b128 v[206:209], v152 offset:20480
	ds_read_b128 v[210:213], v152 offset:21504
	ds_read_b128 v[214:217], v152 offset:22528
	ds_read_b128 v[218:221], v152 offset:23552
	global_load_lds_dwordx4 v[144:145], off
	s_add_i32 m0, s70, 0x2000
	s_add_u32 s70, s38, 0x40000
	v_lshl_add_u64 v[194:195], s[38:39], 0, v[128:129]
	s_addc_u32 s71, s39, 0
	s_add_i32 s72, s61, s52
	global_load_lds_dwordx4 v[194:195], off
	v_lshl_add_u64 v[222:223], s[70:71], 0, v[132:133]
	s_mov_b32 m0, s72
	v_lshl_add_u64 v[224:225], s[44:45], 0, v[130:131]
	global_load_lds_dwordx4 v[222:223], off
	v_lshl_add_u64 v[222:223], s[70:71], 0, v[128:129]
	s_add_i32 m0, s72, 0x2000
	s_nop 0
	global_load_lds_dwordx4 v[222:223], off
	v_lshl_add_u64 v[222:223], s[44:45], 0, v[134:135]
	s_mov_b32 m0, s35
	s_nop 0
	global_load_lds_dwordx4 v[222:223], off
	s_mov_b32 m0, s54
	s_nop 0
	global_load_lds_dwordx4 v[224:225], off
	s_waitcnt vmcnt(8)
	s_waitcnt lgkmcnt(0)
	s_barrier
; #define PG8_STAGE(bufoff, gbase, voff) do { _Pragma("unroll") for (int _i = 0; _i < 2; ++_i) \
;         __builtin_amdgcn_global_load_lds((const unsigned*)((const char*)(gbase) + (voff)[_i]), (PG8_LAS unsigned*)(lds + (bufoff) + ldsw + _i * 8192), 16, 0, 0); } while (0)
; #define PG8_LDA(dst, b, h) do { _Pragma("unroll") for (int m = 0; m < 4; ++m) _Pragma("unroll") for (int k = 0; k < 2; ++k) dst[m][k] = *(const PG8_LAS bf16x8*)(lds + PG8_SA(b, h) + aoff + m * 2048 + k * 1024); } while (0)
; #define PG8_LDB(dst, b, h) do { _Pragma("unroll") for (int n = 0; n < 2; ++n) _Pragma("unroll") for (int k = 0; k < 2; ++k) dst[n][k] = *(const PG8_LAS bf16x8*)(lds + PG8_SB(b, h) + boff + n * 2048 + k * 1024); } while (0)
; #define PG8_MMA(ai, bj, At, Bt) do { __builtin_amdgcn_s_setprio(1); _Pragma("unroll") for (int m = 0; m < 4; ++m) _Pragma("unroll") for (int n = 0; n < 2; ++n) _Pragma("unroll") for (int k = 0; k < 2; ++k) \
;         acc[ai][bj][m][n] = __builtin_amdgcn_mfma_f32_16x16x32_bf16(Bt[n][k], At[m][k], acc[ai][bj][m][n], 0, 0, 0); __builtin_amdgcn_s_setprio(0); } while (0)
; #define PG8_WAIT_V(n) asm volatile("s_waitcnt vmcnt(" #n ")" ::: "memory")
; #define PG8_WAIT_L(n) asm volatile("s_waitcnt lgkmcnt(" #n ")" ::: "memory")
; #define PG8_BAR __builtin_amdgcn_s_barrier()
; #define PG8_SCHED __builtin_amdgcn_sched_barrier(0)
; template <class Epi, class Sched, bool ALIGN_EPI = false, bool SP2 = false>
; __device__ __forceinline__ void gemm_phase(PG8_LAS unsigned char* lds, const Gemm g, const Sched& S, const Epi& E) {
;     ...
;             PG8_WAIT_V(8); PG8_WAIT_L(0); PG8_BAR; PG8_MMA(1, 0, At, B0); PG8_MMA(1, 1, At, B1); PG8_BAR; PG8_SCHED;
;             PG8_LDB(B0, 1, 0); PG8_LDB(B1, 1, 1); PG8_SCHED; PG8_LDA(At, 1, 0); PG8_STAGE(PG8_SA(0, 1), a2 + hstep, voffA);
;             PG8_WAIT_V(8); PG8_WAIT_L(0); PG8_BAR; PG8_MMA(0, 0, At, B0); PG8_MMA(0, 1, At, B1); PG8_BAR; PG8_SCHED;
	s_setprio 1
	s_waitcnt lgkmcnt(0)
	v_mfma_f32_16x16x32_bf16 v[60:63], v[154:157], v[186:189], 0
	v_mfma_f32_16x16x32_bf16 v[52:55], v[162:165], v[186:189], 0
	v_mfma_f32_16x16x32_bf16 v[44:47], v[154:157], v[198:201], 0
	v_mfma_f32_16x16x32_bf16 v[36:39], v[162:165], v[198:201], 0
	v_mfma_f32_16x16x32_bf16 v[28:31], v[154:157], v[206:209], 0
	v_mfma_f32_16x16x32_bf16 v[20:23], v[162:165], v[206:209], 0
	v_mfma_f32_16x16x32_bf16 v[12:15], v[154:157], v[214:217], 0
	v_mfma_f32_16x16x32_bf16 v[4:7], v[162:165], v[214:217], 0
	v_mfma_f32_16x16x32_bf16 v[60:63], v[158:161], v[190:193], v[60:63]
	v_mfma_f32_16x16x32_bf16 v[52:55], v[166:169], v[190:193], v[52:55]
	v_mfma_f32_16x16x32_bf16 v[44:47], v[158:161], v[202:205], v[44:47]
	v_mfma_f32_16x16x32_bf16 v[36:39], v[166:169], v[202:205], v[36:39]
	v_mfma_f32_16x16x32_bf16 v[28:31], v[158:161], v[210:213], v[28:31]
	v_mfma_f32_16x16x32_bf16 v[20:23], v[166:169], v[210:213], v[20:23]
	v_mfma_f32_16x16x32_bf16 v[12:15], v[158:161], v[218:221], v[12:15]
	v_mfma_f32_16x16x32_bf16 v[4:7], v[166:169], v[218:221], v[4:7]
	s_setprio 0
	s_setprio 1
	v_mfma_f32_16x16x32_bf16 v[56:59], v[170:173], v[186:189], 0
	v_mfma_f32_16x16x32_bf16 v[48:51], v[178:181], v[186:189], 0
	v_mfma_f32_16x16x32_bf16 v[40:43], v[170:173], v[198:201], 0
	v_mfma_f32_16x16x32_bf16 v[32:35], v[178:181], v[198:201], 0
	v_mfma_f32_16x16x32_bf16 v[24:27], v[170:173], v[206:209], 0
	v_mfma_f32_16x16x32_bf16 v[16:19], v[178:181], v[206:209], 0
	v_mfma_f32_16x16x32_bf16 v[8:11], v[170:173], v[214:217], 0
	v_mfma_f32_16x16x32_bf16 v[0:3], v[178:181], v[214:217], 0
	v_mfma_f32_16x16x32_bf16 v[56:59], v[174:177], v[190:193], v[56:59]
	v_mfma_f32_16x16x32_bf16 v[48:51], v[182:185], v[190:193], v[48:51]
	v_mfma_f32_16x16x32_bf16 v[40:43], v[174:177], v[202:205], v[40:43]
	v_mfma_f32_16x16x32_bf16 v[32:35], v[182:185], v[202:205], v[32:35]
	v_mfma_f32_16x16x32_bf16 v[24:27], v[174:177], v[210:213], v[24:27]
	v_mfma_f32_16x16x32_bf16 v[16:19], v[182:185], v[210:213], v[16:19]
	v_mfma_f32_16x16x32_bf16 v[8:11], v[174:177], v[218:221], v[8:11]
	v_mfma_f32_16x16x32_bf16 v[0:3], v[182:185], v[218:221], v[0:3]
	s_setprio 0
	s_barrier
	s_add_i32 s70, 0, 0x18000
	v_add_u32_e32 v153, s70, v147
	s_add_i32 s71, 0, 0x1c000
	ds_read_b128 v[154:157], v153
	ds_read_b128 v[158:161], v153 offset:1024
	ds_read_b128 v[162:165], v153 offset:2048
	ds_read_b128 v[166:169], v153 offset:3072
	v_add_u32_e32 v153, s71, v147
	ds_read_b128 v[170:173], v153
	ds_read_b128 v[174:177], v153 offset:1024
	ds_read_b128 v[178:181], v153 offset:2048
	ds_read_b128 v[182:185], v153 offset:3072
	s_add_u32 s44, s44, 0x40000
	s_addc_u32 s45, s45, 0
	s_mov_b32 m0, s55
	v_lshl_add_u64 v[226:227], s[44:45], 0, v[134:135]
	ds_read_b128 v[186:189], v152 offset:32768
	ds_read_b128 v[190:193], v152 offset:33792
	ds_read_b128 v[198:201], v152 offset:34816
	ds_read_b128 v[202:205], v152 offset:35840
	ds_read_b128 v[206:209], v152 offset:36864
	ds_read_b128 v[210:213], v152 offset:37888
	ds_read_b128 v[214:217], v152 offset:38912
	ds_read_b128 v[218:221], v152 offset:39936
	global_load_lds_dwordx4 v[226:227], off
	v_lshl_add_u64 v[226:227], s[44:45], 0, v[130:131]
	s_mov_b32 m0, s56
	s_nop 0
	global_load_lds_dwordx4 v[226:227], off
	s_waitcnt vmcnt(8)
	s_waitcnt lgkmcnt(0)
	s_barrier
	s_setprio 1
	s_waitcnt lgkmcnt(0)
	v_mfma_f32_16x16x32_bf16 v[124:127], v[154:157], v[186:189], v[124:127]
	v_mfma_f32_16x16x32_bf16 v[116:119], v[162:165], v[186:189], v[116:119]
	v_mfma_f32_16x16x32_bf16 v[108:111], v[154:157], v[198:201], v[108:111]
	v_mfma_f32_16x16x32_bf16 v[100:103], v[162:165], v[198:201], v[100:103]
	v_mfma_f32_16x16x32_bf16 v[92:95], v[154:157], v[206:209], v[92:95]
	v_mfma_f32_16x16x32_bf16 v[84:87], v[162:165], v[206:209], v[84:87]
	v_mfma_f32_16x16x32_bf16 v[76:79], v[154:157], v[214:217], v[76:79]
	v_mfma_f32_16x16x32_bf16 v[68:71], v[162:165], v[214:217], v[68:71]
	v_mfma_f32_16x16x32_bf16 v[124:127], v[158:161], v[190:193], v[124:127]
	v_mfma_f32_16x16x32_bf16 v[116:119], v[166:169], v[190:193], v[116:119]
	v_mfma_f32_16x16x32_bf16 v[108:111], v[158:161], v[202:205], v[108:111]
	v_mfma_f32_16x16x32_bf16 v[100:103], v[166:169], v[202:205], v[100:103]
	v_mfma_f32_16x16x32_bf16 v[92:95], v[158:161], v[210:213], v[92:95]
	v_mfma_f32_16x16x32_bf16 v[84:87], v[166:169], v[210:213], v[84:87]
	v_mfma_f32_16x16x32_bf16 v[76:79], v[158:161], v[218:221], v[76:79]
	v_mfma_f32_16x16x32_bf16 v[68:71], v[166:169], v[218:221], v[68:71]
	s_setprio 0
	s_setprio 1
	v_mfma_f32_16x16x32_bf16 v[120:123], v[170:173], v[186:189], v[120:123]
	v_mfma_f32_16x16x32_bf16 v[112:115], v[178:181], v[186:189], v[112:115]
	v_mfma_f32_16x16x32_bf16 v[104:107], v[170:173], v[198:201], v[104:107]
	v_mfma_f32_16x16x32_bf16 v[96:99], v[178:181], v[198:201], v[96:99]
	v_mfma_f32_16x16x32_bf16 v[88:91], v[170:173], v[206:209], v[88:91]
	v_mfma_f32_16x16x32_bf16 v[80:83], v[178:181], v[206:209], v[80:83]
	v_mfma_f32_16x16x32_bf16 v[72:75], v[170:173], v[214:217], v[72:75]
	v_mfma_f32_16x16x32_bf16 v[64:67], v[178:181], v[214:217], v[64:67]
	v_mfma_f32_16x16x32_bf16 v[120:123], v[174:177], v[190:193], v[120:123]
	v_mfma_f32_16x16x32_bf16 v[112:115], v[182:185], v[190:193], v[112:115]
	v_mfma_f32_16x16x32_bf16 v[104:107], v[174:177], v[202:205], v[104:107]
	v_mfma_f32_16x16x32_bf16 v[96:99], v[182:185], v[202:205], v[96:99]
	v_mfma_f32_16x16x32_bf16 v[88:91], v[174:177], v[210:213], v[88:91]
	v_mfma_f32_16x16x32_bf16 v[80:83], v[182:185], v[210:213], v[80:83]
	v_mfma_f32_16x16x32_bf16 v[72:75], v[174:177], v[218:221], v[72:75]
	v_mfma_f32_16x16x32_bf16 v[64:67], v[182:185], v[218:221], v[64:67]
	s_setprio 0
	s_barrier
; #define PG8_STAGE(bufoff, gbase, voff) do { _Pragma("unroll") for (int _i = 0; _i < 2; ++_i) \
;         __builtin_amdgcn_global_load_lds((const unsigned*)((const char*)(gbase) + (voff)[_i]), (PG8_LAS unsigned*)(lds + (bufoff) + ldsw + _i * 8192), 16, 0, 0); } while (0)
; #define PG8_LDA(dst, b, h) do { _Pragma("unroll") for (int m = 0; m < 4; ++m) _Pragma("unroll") for (int k = 0; k < 2; ++k) dst[m][k] = *(const PG8_LAS bf16x8*)(lds + PG8_SA(b, h) + aoff + m * 2048 + k * 1024); } while (0)
; #define PG8_MMA(ai, bj, At, Bt) do { __builtin_amdgcn_s_setprio(1); _Pragma("unroll") for (int m = 0; m < 4; ++m) _Pragma("unroll") for (int n = 0; n < 2; ++n) _Pragma("unroll") for (int k = 0; k < 2; ++k) \
;         acc[ai][bj][m][n] = __builtin_amdgcn_mfma_f32_16x16x32_bf16(Bt[n][k], At[m][k], acc[ai][bj][m][n], 0, 0, 0); __builtin_amdgcn_s_setprio(0); } while (0)
; #define PG8_WAIT_V(n) asm volatile("s_waitcnt vmcnt(" #n ")" ::: "memory")
; #define PG8_WAIT_L(n) asm volatile("s_waitcnt lgkmcnt(" #n ")" ::: "memory")
; #define PG8_BAR __builtin_amdgcn_s_barrier()
; #define PG8_SCHED __builtin_amdgcn_sched_barrier(0)
; template <class Epi, class Sched, bool ALIGN_EPI = false, bool SP2 = false>
; __device__ __forceinline__ void gemm_phase(PG8_LAS unsigned char* lds, const Gemm g, const Sched& S, const Epi& E) {
;     ...
;         for (int t = 0; t < nt; t += 2) {
;     ...
;             PG8_LDA(At, 1, 1); PG8_STAGE(PG8_SB(1, 0), b3, voffB); PG8_STAGE(PG8_SB(1, 1), b3 + hstep, voffB); PG8_STAGE(PG8_SA(1, 0), a3, voffA);
;             PG8_WAIT_V(8); PG8_WAIT_L(0); PG8_BAR; PG8_MMA(1, 0, At, B0); PG8_MMA(1, 1, At, B1); PG8_BAR; PG8_SCHED;
	s_add_i32 s44, s70, s52
	v_lshl_add_u64 v[144:145], v[144:145], 0, s[8:9]
	s_mov_b32 m0, s44
	ds_read_b128 v[186:189], v152 offset:49152
	ds_read_b128 v[190:193], v152 offset:50176
	ds_read_b128 v[198:201], v152 offset:51200
	ds_read_b128 v[202:205], v152 offset:52224
	ds_read_b128 v[206:209], v152 offset:53248
	ds_read_b128 v[210:213], v152 offset:54272
	ds_read_b128 v[214:217], v152 offset:55296
	ds_read_b128 v[218:221], v152 offset:56320
	global_load_lds_dwordx4 v[144:145], off
	s_add_i32 m0, s44, 0x2000
	s_add_u32 s38, s38, 0x40080
	v_lshl_add_u64 v[144:145], v[194:195], 0, s[8:9]
	s_addc_u32 s39, s39, 0
	s_add_i32 s44, s71, s52
	global_load_lds_dwordx4 v[144:145], off
	v_lshl_add_u64 v[144:145], s[38:39], 0, v[132:133]
	s_mov_b32 m0, s44
	s_nop 0
	global_load_lds_dwordx4 v[144:145], off
	v_lshl_add_u64 v[144:145], s[38:39], 0, v[128:129]
	s_add_i32 m0, s44, 0x2000
	s_nop 0
	global_load_lds_dwordx4 v[144:145], off
	v_lshl_add_u64 v[144:145], v[222:223], 0, s[8:9]
	s_mov_b32 m0, s58
	s_nop 0
	global_load_lds_dwordx4 v[144:145], off
	v_lshl_add_u64 v[144:145], v[224:225], 0, s[8:9]
	s_mov_b32 m0, s59
	s_nop 0
	global_load_lds_dwordx4 v[144:145], off
	s_waitcnt vmcnt(8)
	s_waitcnt lgkmcnt(0)
	s_barrier
	s_setprio 1
	s_waitcnt lgkmcnt(0)
	v_mfma_f32_16x16x32_bf16 v[60:63], v[154:157], v[186:189], v[60:63]
	v_mfma_f32_16x16x32_bf16 v[52:55], v[162:165], v[186:189], v[52:55]
	v_mfma_f32_16x16x32_bf16 v[44:47], v[154:157], v[198:201], v[44:47]
	v_mfma_f32_16x16x32_bf16 v[36:39], v[162:165], v[198:201], v[36:39]
	v_mfma_f32_16x16x32_bf16 v[28:31], v[154:157], v[206:209], v[28:31]
	v_mfma_f32_16x16x32_bf16 v[20:23], v[162:165], v[206:209], v[20:23]
	v_mfma_f32_16x16x32_bf16 v[12:15], v[154:157], v[214:217], v[12:15]
	v_mfma_f32_16x16x32_bf16 v[4:7], v[162:165], v[214:217], v[4:7]
	v_mfma_f32_16x16x32_bf16 v[60:63], v[158:161], v[190:193], v[60:63]
	v_mfma_f32_16x16x32_bf16 v[52:55], v[166:169], v[190:193], v[52:55]
	v_mfma_f32_16x16x32_bf16 v[44:47], v[158:161], v[202:205], v[44:47]
	v_mfma_f32_16x16x32_bf16 v[36:39], v[166:169], v[202:205], v[36:39]
	v_mfma_f32_16x16x32_bf16 v[28:31], v[158:161], v[210:213], v[28:31]
	v_mfma_f32_16x16x32_bf16 v[20:23], v[166:169], v[210:213], v[20:23]
	v_mfma_f32_16x16x32_bf16 v[12:15], v[158:161], v[218:221], v[12:15]
	v_mfma_f32_16x16x32_bf16 v[4:7], v[166:169], v[218:221], v[4:7]
	s_setprio 0
	s_setprio 1
	v_mfma_f32_16x16x32_bf16 v[56:59], v[170:173], v[186:189], v[56:59]
	v_mfma_f32_16x16x32_bf16 v[48:51], v[178:181], v[186:189], v[48:51]
	v_mfma_f32_16x16x32_bf16 v[40:43], v[170:173], v[198:201], v[40:43]
	v_mfma_f32_16x16x32_bf16 v[32:35], v[178:181], v[198:201], v[32:35]
	v_mfma_f32_16x16x32_bf16 v[24:27], v[170:173], v[206:209], v[24:27]
	v_mfma_f32_16x16x32_bf16 v[16:19], v[178:181], v[206:209], v[16:19]
	v_mfma_f32_16x16x32_bf16 v[8:11], v[170:173], v[214:217], v[8:11]
	v_mfma_f32_16x16x32_bf16 v[0:3], v[178:181], v[214:217], v[0:3]
	v_mfma_f32_16x16x32_bf16 v[56:59], v[174:177], v[190:193], v[56:59]
	v_mfma_f32_16x16x32_bf16 v[48:51], v[182:185], v[190:193], v[48:51]
	v_mfma_f32_16x16x32_bf16 v[40:43], v[174:177], v[202:205], v[40:43]
	v_mfma_f32_16x16x32_bf16 v[32:35], v[182:185], v[202:205], v[32:35]
	v_mfma_f32_16x16x32_bf16 v[24:27], v[174:177], v[210:213], v[24:27]
	v_mfma_f32_16x16x32_bf16 v[16:19], v[182:185], v[210:213], v[16:19]
	v_mfma_f32_16x16x32_bf16 v[8:11], v[174:177], v[218:221], v[8:11]
	v_mfma_f32_16x16x32_bf16 v[0:3], v[182:185], v[218:221], v[0:3]
	s_setprio 0
	s_barrier
	s_add_i32 s69, s69, 2
	s_add_u32 s20, s20, 0x100
	s_addc_u32 s21, s21, 0
	s_add_u32 s67, s67, 0x100
	s_addc_u32 s68, s68, 0
	s_cmp_gt_u32 s69, 13

; #define PG8_STAGE(bufoff, gbase, voff) do { _Pragma("unroll") for (int _i = 0; _i < 2; ++_i) \
;         __builtin_amdgcn_global_load_lds((const unsigned*)((const char*)(gbase) + (voff)[_i]), (PG8_LAS unsigned*)(lds + (bufoff) + ldsw + _i * 8192), 16, 0, 0); } while (0)
; #define PG8_LDA(dst, b, h) do { _Pragma("unroll") for (int m = 0; m < 4; ++m) _Pragma("unroll") for (int k = 0; k < 2; ++k) dst[m][k] = *(const PG8_LAS bf16x8*)(lds + PG8_SA(b, h) + aoff + m * 2048 + k * 1024); } while (0)
; #define PG8_LDB(dst, b, h) do { _Pragma("unroll") for (int n = 0; n < 2; ++n) _Pragma("unroll") for (int k = 0; k < 2; ++k) dst[n][k] = *(const PG8_LAS bf16x8*)(lds + PG8_SB(b, h) + boff + n * 2048 + k * 1024); } while (0)
; #define PG8_MMA(ai, bj, At, Bt) do { __builtin_amdgcn_s_setprio(1); _Pragma("unroll") for (int m = 0; m < 4; ++m) _Pragma("unroll") for (int n = 0; n < 2; ++n) _Pragma("unroll") for (int k = 0; k < 2; ++k) \
;         acc[ai][bj][m][n] = __builtin_amdgcn_mfma_f32_16x16x32_bf16(Bt[n][k], At[m][k], acc[ai][bj][m][n], 0, 0, 0); __builtin_amdgcn_s_setprio(0); } while (0)
; #define PG8_WAIT_V(n) asm volatile("s_waitcnt vmcnt(" #n ")" ::: "memory")
; #define PG8_WAIT_L(n) asm volatile("s_waitcnt lgkmcnt(" #n ")" ::: "memory")
; template <class Epi, class Sched, bool ALIGN_EPI = false, bool SP2 = false>
; __device__ __forceinline__ void gemm_phase(PG8_LAS unsigned char* lds, const Gemm g, const Sched& S, const Epi& E) {
;     ...
;             const bool last = (t == nt - 2);
;             const char* a1 = cA + (size_t)(t + 1) * kstep;
;             const char* a2 = last ? nA : cA + (size_t)(t + 2) * kstep; const char* b2 = last ? nB : cB + (size_t)(t + 2) * kstep;
;             const char* a3 = a2 + kstep; const char* b3 = b2 + kstep;
;             if (last && has_next) S.a_ready(nxt);
;             if constexpr (SP2) {
;             PG8_LDB(B0, 0, 0); PG8_LDB(B1, 0, 1); PG8_SCHED; PG8_LDA(At, 0, 0); PG8_STAGE(PG8_SA(1, 1), a1 + hstep, voffA);
;             PG8_WAIT_V(8); PG8_WAIT_L(0); PG8_BAR; PG8_MMA(0, 0, At, B0); PG8_MMA(0, 1, At, B1); PG8_BAR; PG8_SCHED;
;             PG8_LDA(At, 0, 1); PG8_STAGE(PG8_SB(0, 0), b2, voffB); PG8_STAGE(PG8_SB(0, 1), b2 + hstep, voffB); PG8_STAGE(PG8_SA(0, 0), a2, voffA);
;             PG8_WAIT_V(8); PG8_WAIT_L(0); PG8_BAR; PG8_MMA(1, 0, At, B0); PG8_MMA(1, 1, At, B1); PG8_BAR; PG8_SCHED;
.LBB0_894:
	s_add_u32 s20, s20, 0xb0080
	s_addc_u32 s21, s21, 0
	s_add_u32 s70, s34, 0x100
	s_addc_u32 s71, s35, 0
	s_mov_b32 s72, -2
	s_waitcnt lgkmcnt(0)
	ds_read_b128 v[96:99], v223
	ds_read_b128 v[108:111], v223 offset:1024
	ds_read_b128 v[120:123], v223 offset:2048
	ds_read_b128 v[128:131], v223 offset:3072
	ds_read_b128 v[144:147], v224
	ds_read_b128 v[148:151], v224 offset:1024
	ds_read_b128 v[152:155], v224 offset:2048
	ds_read_b128 v[156:159], v224 offset:3072
	s_add_u32 s34, s20, 0xfff50080
	s_addc_u32 s35, s21, -1
	s_cmp_eq_u32 s72, 40
	s_cselect_b32 s49, s1, s35
	s_cselect_b32 s48, s0, s34
	s_cselect_b32 s35, s47, s71
	s_cselect_b32 s34, s46, s70
	v_lshl_add_u64 v[210:211], s[20:21], 0, v[192:193]
	s_add_i32 m0, s51, 0xc000
	ds_read_b128 v[160:163], v225
	ds_read_b128 v[164:167], v225 offset:1024
	ds_read_b128 v[168:171], v225 offset:2048
	ds_read_b128 v[172:175], v225 offset:3072
	ds_read_b128 v[176:179], v225 offset:4096
	ds_read_b128 v[180:183], v225 offset:5120
	ds_read_b128 v[202:205], v225 offset:6144
	ds_read_b128 v[206:209], v225 offset:7168
	global_load_lds_dwordx4 v[210:211], off
	v_lshl_add_u64 v[210:211], s[20:21], 0, v[194:195]
	s_add_i32 m0, s51, 0xe000
	s_nop 0
	global_load_lds_dwordx4 v[210:211], off
	s_waitcnt vmcnt(8)
	s_waitcnt lgkmcnt(0)
	s_barrier
	s_setprio 1
	s_waitcnt lgkmcnt(0)
	v_mfma_f32_16x16x32_bf16 v[140:143], v[96:99], v[160:163], 0
	v_mfma_f32_16x16x32_bf16 v[136:139], v[120:123], v[160:163], 0
	v_mfma_f32_16x16x32_bf16 v[116:119], v[96:99], v[168:171], 0
	v_mfma_f32_16x16x32_bf16 v[112:115], v[120:123], v[168:171], 0
	v_mfma_f32_16x16x32_bf16 v[92:95], v[96:99], v[176:179], 0
	v_mfma_f32_16x16x32_bf16 v[88:91], v[120:123], v[176:179], 0
	v_mfma_f32_16x16x32_bf16 v[76:79], v[96:99], v[202:205], 0
	v_mfma_f32_16x16x32_bf16 v[72:75], v[120:123], v[202:205], 0
	v_mfma_f32_16x16x32_bf16 v[140:143], v[108:111], v[164:167], v[140:143]
	v_mfma_f32_16x16x32_bf16 v[136:139], v[128:131], v[164:167], v[136:139]
	v_mfma_f32_16x16x32_bf16 v[116:119], v[108:111], v[172:175], v[116:119]
	v_mfma_f32_16x16x32_bf16 v[112:115], v[128:131], v[172:175], v[112:115]
	v_mfma_f32_16x16x32_bf16 v[92:95], v[108:111], v[180:183], v[92:95]
	v_mfma_f32_16x16x32_bf16 v[88:91], v[128:131], v[180:183], v[88:91]
	v_mfma_f32_16x16x32_bf16 v[76:79], v[108:111], v[206:209], v[76:79]
	v_mfma_f32_16x16x32_bf16 v[72:75], v[128:131], v[206:209], v[72:75]
	s_setprio 0
	s_setprio 1
	v_mfma_f32_16x16x32_bf16 v[132:135], v[144:147], v[160:163], 0
	v_mfma_f32_16x16x32_bf16 v[124:127], v[152:155], v[160:163], 0
	v_mfma_f32_16x16x32_bf16 v[104:107], v[144:147], v[168:171], 0
	v_mfma_f32_16x16x32_bf16 v[100:103], v[152:155], v[168:171], 0
	v_mfma_f32_16x16x32_bf16 v[84:87], v[144:147], v[176:179], 0
	v_mfma_f32_16x16x32_bf16 v[80:83], v[152:155], v[176:179], 0
	v_mfma_f32_16x16x32_bf16 v[68:71], v[144:147], v[202:205], 0
	v_mfma_f32_16x16x32_bf16 v[64:67], v[152:155], v[202:205], 0
	v_mfma_f32_16x16x32_bf16 v[132:135], v[148:151], v[164:167], v[132:135]
	v_mfma_f32_16x16x32_bf16 v[124:127], v[156:159], v[164:167], v[124:127]
	v_mfma_f32_16x16x32_bf16 v[104:107], v[148:151], v[172:175], v[104:107]
	v_mfma_f32_16x16x32_bf16 v[100:103], v[156:159], v[172:175], v[100:103]
	v_mfma_f32_16x16x32_bf16 v[84:87], v[148:151], v[180:183], v[84:87]
	v_mfma_f32_16x16x32_bf16 v[80:83], v[156:159], v[180:183], v[80:83]
	v_mfma_f32_16x16x32_bf16 v[68:71], v[148:151], v[206:209], v[68:71]
	v_mfma_f32_16x16x32_bf16 v[64:67], v[156:159], v[206:209], v[64:67]
	s_setprio 0
	s_barrier
	s_add_i32 s73, s64, s50
	v_lshl_add_u64 v[210:211], s[34:35], 0, v[186:187]
	s_mov_b32 m0, s73
	ds_read_b128 v[160:163], v225 offset:16384
	ds_read_b128 v[164:167], v225 offset:17408
	ds_read_b128 v[168:171], v225 offset:18432
	ds_read_b128 v[172:175], v225 offset:19456
	ds_read_b128 v[176:179], v225 offset:20480
	ds_read_b128 v[180:183], v225 offset:21504
	ds_read_b128 v[202:205], v225 offset:22528
	ds_read_b128 v[206:209], v225 offset:23552
	global_load_lds_dwordx4 v[210:211], off
	s_add_i32 m0, s73, 0x2000
	s_add_u32 s74, s34, 0xb0000
	v_lshl_add_u64 v[212:213], s[34:35], 0, v[190:191]
	s_addc_u32 s75, s35, 0
	s_add_i32 s73, s65, s50
	global_load_lds_dwordx4 v[212:213], off
	v_lshl_add_u64 v[214:215], s[74:75], 0, v[186:187]
	s_mov_b32 m0, s73
	v_lshl_add_u64 v[216:217], s[48:49], 0, v[188:189]
	global_load_lds_dwordx4 v[214:215], off
	v_lshl_add_u64 v[214:215], s[74:75], 0, v[190:191]
	s_add_i32 m0, s73, 0x2000
	s_nop 0
	global_load_lds_dwordx4 v[214:215], off
	v_lshl_add_u64 v[214:215], s[48:49], 0, v[184:185]
	s_mov_b32 m0, s51
	s_nop 0
	global_load_lds_dwordx4 v[214:215], off
	s_mov_b32 m0, s52
	s_nop 0
	global_load_lds_dwordx4 v[216:217], off
	s_waitcnt vmcnt(8)
	s_waitcnt lgkmcnt(0)
	s_barrier
; #define PG8_STAGE(bufoff, gbase, voff) do { _Pragma("unroll") for (int _i = 0; _i < 2; ++_i) \
;         __builtin_amdgcn_global_load_lds((const unsigned*)((const char*)(gbase) + (voff)[_i]), (PG8_LAS unsigned*)(lds + (bufoff) + ldsw + _i * 8192), 16, 0, 0); } while (0)
; #define PG8_LDA(dst, b, h) do { _Pragma("unroll") for (int m = 0; m < 4; ++m) _Pragma("unroll") for (int k = 0; k < 2; ++k) dst[m][k] = *(const PG8_LAS bf16x8*)(lds + PG8_SA(b, h) + aoff + m * 2048 + k * 1024); } while (0)
; #define PG8_LDB(dst, b, h) do { _Pragma("unroll") for (int n = 0; n < 2; ++n) _Pragma("unroll") for (int k = 0; k < 2; ++k) dst[n][k] = *(const PG8_LAS bf16x8*)(lds + PG8_SB(b, h) + boff + n * 2048 + k * 1024); } while (0)
; #define PG8_MMA(ai, bj, At, Bt) do { __builtin_amdgcn_s_setprio(1); _Pragma("unroll") for (int m = 0; m < 4; ++m) _Pragma("unroll") for (int n = 0; n < 2; ++n) _Pragma("unroll") for (int k = 0; k < 2; ++k) \
;         acc[ai][bj][m][n] = __builtin_amdgcn_mfma_f32_16x16x32_bf16(Bt[n][k], At[m][k], acc[ai][bj][m][n], 0, 0, 0); __builtin_amdgcn_s_setprio(0); } while (0)
; #define PG8_WAIT_V(n) asm volatile("s_waitcnt vmcnt(" #n ")" ::: "memory")
; #define PG8_WAIT_L(n) asm volatile("s_waitcnt lgkmcnt(" #n ")" ::: "memory")
; #define PG8_BAR __builtin_amdgcn_s_barrier()
; #define PG8_SCHED __builtin_amdgcn_sched_barrier(0)
; template <class Epi, class Sched, bool ALIGN_EPI = false, bool SP2 = false>
; __device__ __forceinline__ void gemm_phase(PG8_LAS unsigned char* lds, const Gemm g, const Sched& S, const Epi& E) {
;     ...
;             PG8_WAIT_V(8); PG8_WAIT_L(0); PG8_BAR; PG8_MMA(1, 0, At, B0); PG8_MMA(1, 1, At, B1); PG8_BAR; PG8_SCHED;
;             PG8_LDB(B0, 1, 0); PG8_LDB(B1, 1, 1); PG8_SCHED; PG8_LDA(At, 1, 0); PG8_STAGE(PG8_SA(0, 1), a2 + hstep, voffA);
;             PG8_WAIT_V(8); PG8_WAIT_L(0); PG8_BAR; PG8_MMA(0, 0, At, B0); PG8_MMA(0, 1, At, B1); PG8_BAR; PG8_SCHED;
	s_setprio 1
	s_waitcnt lgkmcnt(0)
	v_mfma_f32_16x16x32_bf16 v[60:63], v[96:99], v[160:163], 0
	v_mfma_f32_16x16x32_bf16 v[56:59], v[120:123], v[160:163], 0
	v_mfma_f32_16x16x32_bf16 v[44:47], v[96:99], v[168:171], 0
	v_mfma_f32_16x16x32_bf16 v[40:43], v[120:123], v[168:171], 0
	v_mfma_f32_16x16x32_bf16 v[28:31], v[96:99], v[176:179], 0
	v_mfma_f32_16x16x32_bf16 v[24:27], v[120:123], v[176:179], 0
	v_mfma_f32_16x16x32_bf16 v[12:15], v[96:99], v[202:205], 0
	v_mfma_f32_16x16x32_bf16 v[8:11], v[120:123], v[202:205], 0
	v_mfma_f32_16x16x32_bf16 v[60:63], v[108:111], v[164:167], v[60:63]
	v_mfma_f32_16x16x32_bf16 v[56:59], v[128:131], v[164:167], v[56:59]
	v_mfma_f32_16x16x32_bf16 v[44:47], v[108:111], v[172:175], v[44:47]
	v_mfma_f32_16x16x32_bf16 v[40:43], v[128:131], v[172:175], v[40:43]
	v_mfma_f32_16x16x32_bf16 v[28:31], v[108:111], v[180:183], v[28:31]
	v_mfma_f32_16x16x32_bf16 v[24:27], v[128:131], v[180:183], v[24:27]
	v_mfma_f32_16x16x32_bf16 v[12:15], v[108:111], v[206:209], v[12:15]
	v_mfma_f32_16x16x32_bf16 v[8:11], v[128:131], v[206:209], v[8:11]
	s_setprio 0
	s_setprio 1
	v_mfma_f32_16x16x32_bf16 v[52:55], v[144:147], v[160:163], 0
	v_mfma_f32_16x16x32_bf16 v[48:51], v[152:155], v[160:163], 0
	v_mfma_f32_16x16x32_bf16 v[36:39], v[144:147], v[168:171], 0
	v_mfma_f32_16x16x32_bf16 v[32:35], v[152:155], v[168:171], 0
	v_mfma_f32_16x16x32_bf16 v[20:23], v[144:147], v[176:179], 0
	v_mfma_f32_16x16x32_bf16 v[16:19], v[152:155], v[176:179], 0
	v_mfma_f32_16x16x32_bf16 v[4:7], v[144:147], v[202:205], 0
	v_mfma_f32_16x16x32_bf16 v[0:3], v[152:155], v[202:205], 0
	v_mfma_f32_16x16x32_bf16 v[52:55], v[148:151], v[164:167], v[52:55]
	v_mfma_f32_16x16x32_bf16 v[48:51], v[156:159], v[164:167], v[48:51]
	v_mfma_f32_16x16x32_bf16 v[36:39], v[148:151], v[172:175], v[36:39]
	v_mfma_f32_16x16x32_bf16 v[32:35], v[156:159], v[172:175], v[32:35]
	v_mfma_f32_16x16x32_bf16 v[20:23], v[148:151], v[180:183], v[20:23]
	v_mfma_f32_16x16x32_bf16 v[16:19], v[156:159], v[180:183], v[16:19]
	v_mfma_f32_16x16x32_bf16 v[4:7], v[148:151], v[206:209], v[4:7]
	v_mfma_f32_16x16x32_bf16 v[0:3], v[156:159], v[206:209], v[0:3]
	s_setprio 0
	s_barrier
	s_add_i32 s73, 0, 0x18000
	s_add_i32 s74, 0, 0x1c000
	v_add_u32_e32 v128, s73, v221
	v_add_u32_e32 v156, s74, v221
	ds_read_b128 v[96:99], v128
	ds_read_b128 v[108:111], v128 offset:1024
	ds_read_b128 v[120:123], v128 offset:2048
	ds_read_b128 v[128:131], v128 offset:3072
	ds_read_b128 v[144:147], v156
	ds_read_b128 v[148:151], v156 offset:1024
	ds_read_b128 v[152:155], v156 offset:2048
	ds_read_b128 v[156:159], v156 offset:3072
	s_add_u32 s48, s48, 0xb0000
	s_addc_u32 s49, s49, 0
	s_mov_b32 m0, s53
	v_lshl_add_u64 v[218:219], s[48:49], 0, v[184:185]
	ds_read_b128 v[160:163], v225 offset:32768
	ds_read_b128 v[164:167], v225 offset:33792
	ds_read_b128 v[168:171], v225 offset:34816
	ds_read_b128 v[172:175], v225 offset:35840
	ds_read_b128 v[176:179], v225 offset:36864
	ds_read_b128 v[180:183], v225 offset:37888
	ds_read_b128 v[202:205], v225 offset:38912
	ds_read_b128 v[206:209], v225 offset:39936
	global_load_lds_dwordx4 v[218:219], off
	v_lshl_add_u64 v[218:219], s[48:49], 0, v[188:189]
	s_mov_b32 m0, s54
	s_nop 0
	global_load_lds_dwordx4 v[218:219], off
	s_waitcnt vmcnt(8)
	s_waitcnt lgkmcnt(0)
	s_barrier
	s_setprio 1
	s_waitcnt lgkmcnt(0)
	v_mfma_f32_16x16x32_bf16 v[140:143], v[96:99], v[160:163], v[140:143]
	v_mfma_f32_16x16x32_bf16 v[136:139], v[120:123], v[160:163], v[136:139]
	v_mfma_f32_16x16x32_bf16 v[116:119], v[96:99], v[168:171], v[116:119]
	v_mfma_f32_16x16x32_bf16 v[112:115], v[120:123], v[168:171], v[112:115]
	v_mfma_f32_16x16x32_bf16 v[92:95], v[96:99], v[176:179], v[92:95]
	v_mfma_f32_16x16x32_bf16 v[88:91], v[120:123], v[176:179], v[88:91]
	v_mfma_f32_16x16x32_bf16 v[76:79], v[96:99], v[202:205], v[76:79]
	v_mfma_f32_16x16x32_bf16 v[72:75], v[120:123], v[202:205], v[72:75]
	v_mfma_f32_16x16x32_bf16 v[140:143], v[108:111], v[164:167], v[140:143]
	v_mfma_f32_16x16x32_bf16 v[136:139], v[128:131], v[164:167], v[136:139]
	v_mfma_f32_16x16x32_bf16 v[116:119], v[108:111], v[172:175], v[116:119]
	v_mfma_f32_16x16x32_bf16 v[112:115], v[128:131], v[172:175], v[112:115]
	v_mfma_f32_16x16x32_bf16 v[92:95], v[108:111], v[180:183], v[92:95]
	v_mfma_f32_16x16x32_bf16 v[88:91], v[128:131], v[180:183], v[88:91]
	v_mfma_f32_16x16x32_bf16 v[76:79], v[108:111], v[206:209], v[76:79]
	v_mfma_f32_16x16x32_bf16 v[72:75], v[128:131], v[206:209], v[72:75]
	s_setprio 0
	s_setprio 1
	v_mfma_f32_16x16x32_bf16 v[132:135], v[144:147], v[160:163], v[132:135]
	v_mfma_f32_16x16x32_bf16 v[124:127], v[152:155], v[160:163], v[124:127]
	v_mfma_f32_16x16x32_bf16 v[104:107], v[144:147], v[168:171], v[104:107]
	v_mfma_f32_16x16x32_bf16 v[100:103], v[152:155], v[168:171], v[100:103]
	v_mfma_f32_16x16x32_bf16 v[84:87], v[144:147], v[176:179], v[84:87]
	v_mfma_f32_16x16x32_bf16 v[80:83], v[152:155], v[176:179], v[80:83]
	v_mfma_f32_16x16x32_bf16 v[68:71], v[144:147], v[202:205], v[68:71]
	v_mfma_f32_16x16x32_bf16 v[64:67], v[152:155], v[202:205], v[64:67]
	v_mfma_f32_16x16x32_bf16 v[132:135], v[148:151], v[164:167], v[132:135]
	v_mfma_f32_16x16x32_bf16 v[124:127], v[156:159], v[164:167], v[124:127]
	v_mfma_f32_16x16x32_bf16 v[104:107], v[148:151], v[172:175], v[104:107]
	v_mfma_f32_16x16x32_bf16 v[100:103], v[156:159], v[172:175], v[100:103]
	v_mfma_f32_16x16x32_bf16 v[84:87], v[148:151], v[180:183], v[84:87]
	v_mfma_f32_16x16x32_bf16 v[80:83], v[156:159], v[180:183], v[80:83]
	v_mfma_f32_16x16x32_bf16 v[68:71], v[148:151], v[206:209], v[68:71]
	v_mfma_f32_16x16x32_bf16 v[64:67], v[156:159], v[206:209], v[64:67]
	s_setprio 0
	s_barrier
; #define PG8_STAGE(bufoff, gbase, voff) do { _Pragma("unroll") for (int _i = 0; _i < 2; ++_i) \
;         __builtin_amdgcn_global_load_lds((const unsigned*)((const char*)(gbase) + (voff)[_i]), (PG8_LAS unsigned*)(lds + (bufoff) + ldsw + _i * 8192), 16, 0, 0); } while (0)
; #define PG8_LDA(dst, b, h) do { _Pragma("unroll") for (int m = 0; m < 4; ++m) _Pragma("unroll") for (int k = 0; k < 2; ++k) dst[m][k] = *(const PG8_LAS bf16x8*)(lds + PG8_SA(b, h) + aoff + m * 2048 + k * 1024); } while (0)
; #define PG8_MMA(ai, bj, At, Bt) do { __builtin_amdgcn_s_setprio(1); _Pragma("unroll") for (int m = 0; m < 4; ++m) _Pragma("unroll") for (int n = 0; n < 2; ++n) _Pragma("unroll") for (int k = 0; k < 2; ++k) \
;         acc[ai][bj][m][n] = __builtin_amdgcn_mfma_f32_16x16x32_bf16(Bt[n][k], At[m][k], acc[ai][bj][m][n], 0, 0, 0); __builtin_amdgcn_s_setprio(0); } while (0)
; #define PG8_WAIT_V(n) asm volatile("s_waitcnt vmcnt(" #n ")" ::: "memory")
; #define PG8_WAIT_L(n) asm volatile("s_waitcnt lgkmcnt(" #n ")" ::: "memory")
; #define PG8_BAR __builtin_amdgcn_s_barrier()
; #define PG8_SCHED __builtin_amdgcn_sched_barrier(0)
; template <class Epi, class Sched, bool ALIGN_EPI = false, bool SP2 = false>
; __device__ __forceinline__ void gemm_phase(PG8_LAS unsigned char* lds, const Gemm g, const Sched& S, const Epi& E) {
;     ...
;         for (int t = 0; t < nt; t += 2) {
;     ...
;             PG8_LDA(At, 1, 1); PG8_STAGE(PG8_SB(1, 0), b3, voffB); PG8_STAGE(PG8_SB(1, 1), b3 + hstep, voffB); PG8_STAGE(PG8_SA(1, 0), a3, voffA);
;             PG8_WAIT_V(8); PG8_WAIT_L(0); PG8_BAR; PG8_MMA(1, 0, At, B0); PG8_MMA(1, 1, At, B1); PG8_BAR; PG8_SCHED;
	s_add_i32 s48, s73, s50
	v_lshl_add_u64 v[210:211], v[210:211], 0, s[12:13]
	s_mov_b32 m0, s48
	ds_read_b128 v[160:163], v225 offset:49152
	ds_read_b128 v[164:167], v225 offset:50176
	ds_read_b128 v[168:171], v225 offset:51200
	ds_read_b128 v[172:175], v225 offset:52224
	ds_read_b128 v[176:179], v225 offset:53248
	ds_read_b128 v[180:183], v225 offset:54272
	ds_read_b128 v[202:205], v225 offset:55296
	ds_read_b128 v[206:209], v225 offset:56320
	global_load_lds_dwordx4 v[210:211], off
	s_add_i32 m0, s48, 0x2000
	s_add_u32 s34, s34, 0xb0080
	v_lshl_add_u64 v[210:211], v[212:213], 0, s[12:13]
	s_addc_u32 s35, s35, 0
	s_add_i32 s48, s74, s50
	global_load_lds_dwordx4 v[210:211], off
	v_lshl_add_u64 v[210:211], s[34:35], 0, v[186:187]
	s_mov_b32 m0, s48
	s_nop 0
	global_load_lds_dwordx4 v[210:211], off
	v_lshl_add_u64 v[210:211], s[34:35], 0, v[190:191]
	s_add_i32 m0, s48, 0x2000
	s_nop 0
	global_load_lds_dwordx4 v[210:211], off
	v_lshl_add_u64 v[210:211], v[214:215], 0, s[12:13]
	s_mov_b32 m0, s59
	s_nop 0
	global_load_lds_dwordx4 v[210:211], off
	v_lshl_add_u64 v[210:211], v[216:217], 0, s[12:13]
	s_mov_b32 m0, s60
	s_nop 0
	global_load_lds_dwordx4 v[210:211], off
	s_waitcnt vmcnt(8)
	s_waitcnt lgkmcnt(0)
	s_barrier
	s_setprio 1
	s_waitcnt lgkmcnt(0)
	v_mfma_f32_16x16x32_bf16 v[60:63], v[96:99], v[160:163], v[60:63]
	v_mfma_f32_16x16x32_bf16 v[56:59], v[120:123], v[160:163], v[56:59]
	v_mfma_f32_16x16x32_bf16 v[44:47], v[96:99], v[168:171], v[44:47]
	v_mfma_f32_16x16x32_bf16 v[40:43], v[120:123], v[168:171], v[40:43]
	v_mfma_f32_16x16x32_bf16 v[28:31], v[96:99], v[176:179], v[28:31]
	v_mfma_f32_16x16x32_bf16 v[24:27], v[120:123], v[176:179], v[24:27]
	v_mfma_f32_16x16x32_bf16 v[12:15], v[96:99], v[202:205], v[12:15]
	v_mfma_f32_16x16x32_bf16 v[8:11], v[120:123], v[202:205], v[8:11]
	v_mfma_f32_16x16x32_bf16 v[60:63], v[108:111], v[164:167], v[60:63]
	v_mfma_f32_16x16x32_bf16 v[56:59], v[128:131], v[164:167], v[56:59]
	v_mfma_f32_16x16x32_bf16 v[44:47], v[108:111], v[172:175], v[44:47]
	v_mfma_f32_16x16x32_bf16 v[40:43], v[128:131], v[172:175], v[40:43]
	v_mfma_f32_16x16x32_bf16 v[28:31], v[108:111], v[180:183], v[28:31]
	v_mfma_f32_16x16x32_bf16 v[24:27], v[128:131], v[180:183], v[24:27]
	v_mfma_f32_16x16x32_bf16 v[12:15], v[108:111], v[206:209], v[12:15]
	v_mfma_f32_16x16x32_bf16 v[8:11], v[128:131], v[206:209], v[8:11]
	s_setprio 0
	s_setprio 1
	v_mfma_f32_16x16x32_bf16 v[52:55], v[144:147], v[160:163], v[52:55]
	v_mfma_f32_16x16x32_bf16 v[48:51], v[152:155], v[160:163], v[48:51]
	v_mfma_f32_16x16x32_bf16 v[36:39], v[144:147], v[168:171], v[36:39]
	v_mfma_f32_16x16x32_bf16 v[32:35], v[152:155], v[168:171], v[32:35]
	v_mfma_f32_16x16x32_bf16 v[20:23], v[144:147], v[176:179], v[20:23]
	v_mfma_f32_16x16x32_bf16 v[16:19], v[152:155], v[176:179], v[16:19]
	v_mfma_f32_16x16x32_bf16 v[4:7], v[144:147], v[202:205], v[4:7]
	v_mfma_f32_16x16x32_bf16 v[0:3], v[152:155], v[202:205], v[0:3]
	v_mfma_f32_16x16x32_bf16 v[52:55], v[148:151], v[164:167], v[52:55]
	v_mfma_f32_16x16x32_bf16 v[48:51], v[156:159], v[164:167], v[48:51]
	v_mfma_f32_16x16x32_bf16 v[36:39], v[148:151], v[172:175], v[36:39]
	v_mfma_f32_16x16x32_bf16 v[32:35], v[156:159], v[172:175], v[32:35]
	v_mfma_f32_16x16x32_bf16 v[20:23], v[148:151], v[180:183], v[20:23]
	v_mfma_f32_16x16x32_bf16 v[16:19], v[156:159], v[180:183], v[16:19]
	v_mfma_f32_16x16x32_bf16 v[4:7], v[148:151], v[206:209], v[4:7]
	v_mfma_f32_16x16x32_bf16 v[0:3], v[156:159], v[206:209], v[0:3]
	s_setprio 0
	s_barrier
	s_add_i32 s72, s72, 2
	s_add_u32 s20, s20, 0x100
	s_addc_u32 s21, s21, 0
	s_add_u32 s70, s70, 0x100
	s_addc_u32 s71, s71, 0
	s_cmp_gt_u32 s72, 41

; #define PG8_STAGE(bufoff, gbase, voff) do { _Pragma("unroll") for (int _i = 0; _i < 2; ++_i) \
;         __builtin_amdgcn_global_load_lds((const unsigned*)((const char*)(gbase) + (voff)[_i]), (PG8_LAS unsigned*)(lds + (bufoff) + ldsw + _i * 8192), 16, 0, 0); } while (0)
; #define PG8_LDA(dst, b, h) do { _Pragma("unroll") for (int m = 0; m < 4; ++m) _Pragma("unroll") for (int k = 0; k < 2; ++k) dst[m][k] = *(const PG8_LAS bf16x8*)(lds + PG8_SA(b, h) + aoff + m * 2048 + k * 1024); } while (0)
; #define PG8_LDB(dst, b, h) do { _Pragma("unroll") for (int n = 0; n < 2; ++n) _Pragma("unroll") for (int k = 0; k < 2; ++k) dst[n][k] = *(const PG8_LAS bf16x8*)(lds + PG8_SB(b, h) + boff + n * 2048 + k * 1024); } while (0)
; #define PG8_WAIT_V(n) asm volatile("s_waitcnt vmcnt(" #n ")" ::: "memory")
; #define PG8_WAIT_L(n) asm volatile("s_waitcnt lgkmcnt(" #n ")" ::: "memory")
; #define PG8_BAR __builtin_amdgcn_s_barrier()
; #define PG8_SCHED __builtin_amdgcn_sched_barrier(0)
; template <class Epi, class Sched, bool ALIGN_EPI = false, bool SP2 = false>
; __device__ __forceinline__ void gemm_phase(PG8_LAS unsigned char* lds, const Gemm g, const Sched& S, const Epi& E) {
;     ...
;         const bool has_next = S.next(ui + 1, nxt);
;         const char* nA = has_next ? (const char*)g.A + (size_t)nxt.pm * tstep : cA; const char* nB = has_next ? (const char*)g.Bt + (size_t)nxt.pn * tstep : cB;
;         for (int t = 0; t < nt; t += 2) {
;             const bool last = (t == nt - 2);
;             const char* a1 = cA + (size_t)(t + 1) * kstep;
;             const char* a2 = last ? nA : cA + (size_t)(t + 2) * kstep; const char* b2 = last ? nB : cB + (size_t)(t + 2) * kstep;
;             const char* a3 = a2 + kstep; const char* b3 = b2 + kstep;
;             if (last && has_next) S.a_ready(nxt);
;             if constexpr (SP2) {
;             PG8_LDB(B0, 0, 0); PG8_LDB(B1, 0, 1); PG8_SCHED; PG8_LDA(At, 0, 0); PG8_STAGE(PG8_SA(1, 1), a1 + hstep, voffA);
;             PG8_WAIT_V(8); PG8_WAIT_L(0); PG8_BAR; PG8_MMA(0, 0, At, B0); PG8_MMA(0, 1, At, B1); PG8_BAR; PG8_SCHED;
;             PG8_LDA(At, 0, 1); PG8_STAGE(PG8_SB(0, 0), b2, voffB); PG8_STAGE(PG8_SB(0, 1), b2 + hstep, voffB); PG8_STAGE(PG8_SA(0, 0), a2, voffA);
;             PG8_WAIT_V(8); PG8_WAIT_L(0); PG8_BAR; PG8_MMA(1, 0, At, B0); PG8_MMA(1, 1, At, B1); PG8_BAR; PG8_SCHED;
.LBB0_1199:
	s_ashr_i32 s57, s56, 31
	s_lshl_b64 s[58:59], s[56:57], 19
	s_add_u32 s58, s36, s58
	s_addc_u32 s59, s37, s59
	s_and_b64 s[60:61], s[8:9], exec
	s_cselect_b32 s1, s59, s21
	s_cselect_b32 s57, s58, s20
	s_ashr_i32 s55, s54, 31
	s_lshl_b64 s[60:61], s[54:55], 19
	s_add_u32 s60, s68, s60
	s_addc_u32 s61, s69, s61
	s_and_b64 s[62:63], s[8:9], exec
	s_cselect_b32 s55, s61, s35
	s_cselect_b32 s85, s60, s34
	s_add_u32 s20, s20, 0x40080
	s_addc_u32 s21, s21, 0
	s_add_u32 s86, s34, 0x100
	s_addc_u32 s87, s35, 0
	s_mov_b32 s88, -2
	s_waitcnt lgkmcnt(0)
	ds_read_b128 v[140:143], v163
	ds_read_b128 v[168:171], v163 offset:1024
	ds_read_b128 v[172:175], v163 offset:2048
	ds_read_b128 v[176:179], v163 offset:3072
	ds_read_b128 v[180:183], v164
	ds_read_b128 v[184:187], v164 offset:1024
	ds_read_b128 v[188:191], v164 offset:2048
	ds_read_b128 v[192:195], v164 offset:3072
	s_add_u32 s34, s20, 0xfffc0080
	s_addc_u32 s35, s21, -1
	s_cmp_eq_u32 s88, 12
	s_cselect_b32 s63, s1, s35
	s_cselect_b32 s62, s57, s34
	s_cselect_b32 s35, s55, s87
	s_cselect_b32 s34, s85, s86
	v_lshl_add_u64 v[230:231], s[20:21], 0, v[132:133]
	s_add_i32 m0, s71, 0xc000
	ds_read_b128 v[198:201], v165
	ds_read_b128 v[202:205], v165 offset:1024
	ds_read_b128 v[206:209], v165 offset:2048
	ds_read_b128 v[210:213], v165 offset:3072
	ds_read_b128 v[214:217], v165 offset:4096
	ds_read_b128 v[218:221], v165 offset:5120
	ds_read_b128 v[222:225], v165 offset:6144
	ds_read_b128 v[226:229], v165 offset:7168
	global_load_lds_dwordx4 v[230:231], off
	v_lshl_add_u64 v[230:231], s[20:21], 0, v[134:135]
	s_add_i32 m0, s71, 0xe000
	s_nop 0
	global_load_lds_dwordx4 v[230:231], off
	s_waitcnt vmcnt(8)
	s_waitcnt lgkmcnt(0)
	s_barrier
	s_setprio 1
	s_waitcnt lgkmcnt(0)
	v_mfma_f32_16x16x32_bf16 v[124:127], v[140:143], v[198:201], 0
	v_mfma_f32_16x16x32_bf16 v[120:123], v[172:175], v[198:201], 0
	v_mfma_f32_16x16x32_bf16 v[108:111], v[140:143], v[206:209], 0
	v_mfma_f32_16x16x32_bf16 v[104:107], v[172:175], v[206:209], 0
	v_mfma_f32_16x16x32_bf16 v[92:95], v[140:143], v[214:217], 0
	v_mfma_f32_16x16x32_bf16 v[88:91], v[172:175], v[214:217], 0
	v_mfma_f32_16x16x32_bf16 v[76:79], v[140:143], v[222:225], 0
	v_mfma_f32_16x16x32_bf16 v[72:75], v[172:175], v[222:225], 0
	v_mfma_f32_16x16x32_bf16 v[124:127], v[168:171], v[202:205], v[124:127]
	v_mfma_f32_16x16x32_bf16 v[120:123], v[176:179], v[202:205], v[120:123]
	v_mfma_f32_16x16x32_bf16 v[108:111], v[168:171], v[210:213], v[108:111]
	v_mfma_f32_16x16x32_bf16 v[104:107], v[176:179], v[210:213], v[104:107]
	v_mfma_f32_16x16x32_bf16 v[92:95], v[168:171], v[218:221], v[92:95]
	v_mfma_f32_16x16x32_bf16 v[88:91], v[176:179], v[218:221], v[88:91]
	v_mfma_f32_16x16x32_bf16 v[76:79], v[168:171], v[226:229], v[76:79]
	v_mfma_f32_16x16x32_bf16 v[72:75], v[176:179], v[226:229], v[72:75]
	s_setprio 0
	s_setprio 1
	v_mfma_f32_16x16x32_bf16 v[116:119], v[180:183], v[198:201], 0
	v_mfma_f32_16x16x32_bf16 v[112:115], v[188:191], v[198:201], 0
	v_mfma_f32_16x16x32_bf16 v[100:103], v[180:183], v[206:209], 0
	v_mfma_f32_16x16x32_bf16 v[96:99], v[188:191], v[206:209], 0
	v_mfma_f32_16x16x32_bf16 v[84:87], v[180:183], v[214:217], 0
	v_mfma_f32_16x16x32_bf16 v[80:83], v[188:191], v[214:217], 0
	v_mfma_f32_16x16x32_bf16 v[68:71], v[180:183], v[222:225], 0
	v_mfma_f32_16x16x32_bf16 v[64:67], v[188:191], v[222:225], 0
	v_mfma_f32_16x16x32_bf16 v[116:119], v[184:187], v[202:205], v[116:119]
	v_mfma_f32_16x16x32_bf16 v[112:115], v[192:195], v[202:205], v[112:115]
	v_mfma_f32_16x16x32_bf16 v[100:103], v[184:187], v[210:213], v[100:103]
	v_mfma_f32_16x16x32_bf16 v[96:99], v[192:195], v[210:213], v[96:99]
	v_mfma_f32_16x16x32_bf16 v[84:87], v[184:187], v[218:221], v[84:87]
	v_mfma_f32_16x16x32_bf16 v[80:83], v[192:195], v[218:221], v[80:83]
	v_mfma_f32_16x16x32_bf16 v[68:71], v[184:187], v[226:229], v[68:71]
	v_mfma_f32_16x16x32_bf16 v[64:67], v[192:195], v[226:229], v[64:67]
	s_setprio 0
	s_barrier
	s_add_i32 s89, s77, s70
	v_lshl_add_u64 v[230:231], s[34:35], 0, v[146:147]
	s_mov_b32 m0, s89
	ds_read_b128 v[198:201], v165 offset:16384
	ds_read_b128 v[202:205], v165 offset:17408
	ds_read_b128 v[206:209], v165 offset:18432
	ds_read_b128 v[210:213], v165 offset:19456
	ds_read_b128 v[214:217], v165 offset:20480
	ds_read_b128 v[218:221], v165 offset:21504
	ds_read_b128 v[222:225], v165 offset:22528
	ds_read_b128 v[226:229], v165 offset:23552
	global_load_lds_dwordx4 v[230:231], off
	s_add_i32 m0, s89, 0x2000
	s_add_u32 s90, s34, 0x40000
	v_lshl_add_u64 v[232:233], s[34:35], 0, v[150:151]
	s_addc_u32 s91, s35, 0
	s_add_i32 s89, s78, s70
	global_load_lds_dwordx4 v[232:233], off
	v_lshl_add_u64 v[234:235], s[90:91], 0, v[146:147]
	s_mov_b32 m0, s89
	v_lshl_add_u64 v[236:237], s[62:63], 0, v[148:149]
	global_load_lds_dwordx4 v[234:235], off
	v_lshl_add_u64 v[234:235], s[90:91], 0, v[150:151]
	s_add_i32 m0, s89, 0x2000
	s_nop 0
	global_load_lds_dwordx4 v[234:235], off
	v_lshl_add_u64 v[234:235], s[62:63], 0, v[144:145]
	s_mov_b32 m0, s71
	s_nop 0
	global_load_lds_dwordx4 v[234:235], off
	s_mov_b32 m0, s72
	s_nop 0
	global_load_lds_dwordx4 v[236:237], off
	s_waitcnt vmcnt(8)
	s_waitcnt lgkmcnt(0)
	s_barrier
; #define PG8_STAGE(bufoff, gbase, voff) do { _Pragma("unroll") for (int _i = 0; _i < 2; ++_i) \
;         __builtin_amdgcn_global_load_lds((const unsigned*)((const char*)(gbase) + (voff)[_i]), (PG8_LAS unsigned*)(lds + (bufoff) + ldsw + _i * 8192), 16, 0, 0); } while (0)
; #define PG8_LDA(dst, b, h) do { _Pragma("unroll") for (int m = 0; m < 4; ++m) _Pragma("unroll") for (int k = 0; k < 2; ++k) dst[m][k] = *(const PG8_LAS bf16x8*)(lds + PG8_SA(b, h) + aoff + m * 2048 + k * 1024); } while (0)
; #define PG8_LDB(dst, b, h) do { _Pragma("unroll") for (int n = 0; n < 2; ++n) _Pragma("unroll") for (int k = 0; k < 2; ++k) dst[n][k] = *(const PG8_LAS bf16x8*)(lds + PG8_SB(b, h) + boff + n * 2048 + k * 1024); } while (0)
; #define PG8_MMA(ai, bj, At, Bt) do { __builtin_amdgcn_s_setprio(1); _Pragma("unroll") for (int m = 0; m < 4; ++m) _Pragma("unroll") for (int n = 0; n < 2; ++n) _Pragma("unroll") for (int k = 0; k < 2; ++k) \
;         acc[ai][bj][m][n] = __builtin_amdgcn_mfma_f32_16x16x32_bf16(Bt[n][k], At[m][k], acc[ai][bj][m][n], 0, 0, 0); __builtin_amdgcn_s_setprio(0); } while (0)
; #define PG8_WAIT_V(n) asm volatile("s_waitcnt vmcnt(" #n ")" ::: "memory")
; #define PG8_WAIT_L(n) asm volatile("s_waitcnt lgkmcnt(" #n ")" ::: "memory")
; #define PG8_BAR __builtin_amdgcn_s_barrier()
; #define PG8_SCHED __builtin_amdgcn_sched_barrier(0)
; template <class Epi, class Sched, bool ALIGN_EPI = false, bool SP2 = false>
; __device__ __forceinline__ void gemm_phase(PG8_LAS unsigned char* lds, const Gemm g, const Sched& S, const Epi& E) {
;     ...
;             PG8_WAIT_V(8); PG8_WAIT_L(0); PG8_BAR; PG8_MMA(1, 0, At, B0); PG8_MMA(1, 1, At, B1); PG8_BAR; PG8_SCHED;
;             PG8_LDB(B0, 1, 0); PG8_LDB(B1, 1, 1); PG8_SCHED; PG8_LDA(At, 1, 0); PG8_STAGE(PG8_SA(0, 1), a2 + hstep, voffA);
;             PG8_WAIT_V(8); PG8_WAIT_L(0); PG8_BAR; PG8_MMA(0, 0, At, B0); PG8_MMA(0, 1, At, B1); PG8_BAR; PG8_SCHED;
	s_setprio 1
	s_waitcnt lgkmcnt(0)
	v_mfma_f32_16x16x32_bf16 v[60:63], v[140:143], v[198:201], 0
	v_mfma_f32_16x16x32_bf16 v[56:59], v[172:175], v[198:201], 0
	v_mfma_f32_16x16x32_bf16 v[48:51], v[140:143], v[206:209], 0
	v_mfma_f32_16x16x32_bf16 v[40:43], v[172:175], v[206:209], 0
	v_mfma_f32_16x16x32_bf16 v[32:35], v[140:143], v[214:217], 0
	v_mfma_f32_16x16x32_bf16 v[24:27], v[172:175], v[214:217], 0
	v_mfma_f32_16x16x32_bf16 v[16:19], v[140:143], v[222:225], 0
	v_mfma_f32_16x16x32_bf16 v[8:11], v[172:175], v[222:225], 0
	v_mfma_f32_16x16x32_bf16 v[60:63], v[168:171], v[202:205], v[60:63]
	v_mfma_f32_16x16x32_bf16 v[56:59], v[176:179], v[202:205], v[56:59]
	v_mfma_f32_16x16x32_bf16 v[48:51], v[168:171], v[210:213], v[48:51]
	v_mfma_f32_16x16x32_bf16 v[40:43], v[176:179], v[210:213], v[40:43]
	v_mfma_f32_16x16x32_bf16 v[32:35], v[168:171], v[218:221], v[32:35]
	v_mfma_f32_16x16x32_bf16 v[24:27], v[176:179], v[218:221], v[24:27]
	v_mfma_f32_16x16x32_bf16 v[16:19], v[168:171], v[226:229], v[16:19]
	v_mfma_f32_16x16x32_bf16 v[8:11], v[176:179], v[226:229], v[8:11]
	s_setprio 0
	s_setprio 1
	v_mfma_f32_16x16x32_bf16 v[52:55], v[180:183], v[198:201], 0
	v_mfma_f32_16x16x32_bf16 v[44:47], v[188:191], v[198:201], 0
	v_mfma_f32_16x16x32_bf16 v[36:39], v[180:183], v[206:209], 0
	v_mfma_f32_16x16x32_bf16 v[28:31], v[188:191], v[206:209], 0
	v_mfma_f32_16x16x32_bf16 v[20:23], v[180:183], v[214:217], 0
	v_mfma_f32_16x16x32_bf16 v[12:15], v[188:191], v[214:217], 0
	v_mfma_f32_16x16x32_bf16 v[4:7], v[180:183], v[222:225], 0
	v_mfma_f32_16x16x32_bf16 v[0:3], v[188:191], v[222:225], 0
	v_mfma_f32_16x16x32_bf16 v[52:55], v[184:187], v[202:205], v[52:55]
	v_mfma_f32_16x16x32_bf16 v[44:47], v[192:195], v[202:205], v[44:47]
	v_mfma_f32_16x16x32_bf16 v[36:39], v[184:187], v[210:213], v[36:39]
	v_mfma_f32_16x16x32_bf16 v[28:31], v[192:195], v[210:213], v[28:31]
	v_mfma_f32_16x16x32_bf16 v[20:23], v[184:187], v[218:221], v[20:23]
	v_mfma_f32_16x16x32_bf16 v[12:15], v[192:195], v[218:221], v[12:15]
	v_mfma_f32_16x16x32_bf16 v[4:7], v[184:187], v[226:229], v[4:7]
	v_mfma_f32_16x16x32_bf16 v[0:3], v[192:195], v[226:229], v[0:3]
	s_setprio 0
	s_barrier
	s_add_i32 s89, 0, 0x18000
	v_add_u32_e32 v128, s89, v161
	s_add_i32 s90, 0, 0x1c000
	ds_read_b128 v[140:143], v128
	ds_read_b128 v[168:171], v128 offset:1024
	ds_read_b128 v[172:175], v128 offset:2048
	ds_read_b128 v[176:179], v128 offset:3072
	v_add_u32_e32 v128, s90, v161
	ds_read_b128 v[180:183], v128
	ds_read_b128 v[184:187], v128 offset:1024
	ds_read_b128 v[188:191], v128 offset:2048
	ds_read_b128 v[192:195], v128 offset:3072
	s_add_u32 s62, s62, 0x40000
	s_addc_u32 s63, s63, 0
	s_mov_b32 m0, s73
	v_lshl_add_u64 v[238:239], s[62:63], 0, v[144:145]
	ds_read_b128 v[198:201], v165 offset:32768
	ds_read_b128 v[202:205], v165 offset:33792
	ds_read_b128 v[206:209], v165 offset:34816
	ds_read_b128 v[210:213], v165 offset:35840
	ds_read_b128 v[214:217], v165 offset:36864
	ds_read_b128 v[218:221], v165 offset:37888
	ds_read_b128 v[222:225], v165 offset:38912
	ds_read_b128 v[226:229], v165 offset:39936
	global_load_lds_dwordx4 v[238:239], off
	v_lshl_add_u64 v[238:239], s[62:63], 0, v[148:149]
	s_mov_b32 m0, s74
	s_nop 0
	global_load_lds_dwordx4 v[238:239], off
	s_waitcnt vmcnt(8)
	s_waitcnt lgkmcnt(0)
	s_barrier
	s_setprio 1
	s_waitcnt lgkmcnt(0)
	v_mfma_f32_16x16x32_bf16 v[124:127], v[140:143], v[198:201], v[124:127]
	v_mfma_f32_16x16x32_bf16 v[120:123], v[172:175], v[198:201], v[120:123]
	v_mfma_f32_16x16x32_bf16 v[108:111], v[140:143], v[206:209], v[108:111]
	v_mfma_f32_16x16x32_bf16 v[104:107], v[172:175], v[206:209], v[104:107]
	v_mfma_f32_16x16x32_bf16 v[92:95], v[140:143], v[214:217], v[92:95]
	v_mfma_f32_16x16x32_bf16 v[88:91], v[172:175], v[214:217], v[88:91]
	v_mfma_f32_16x16x32_bf16 v[76:79], v[140:143], v[222:225], v[76:79]
	v_mfma_f32_16x16x32_bf16 v[72:75], v[172:175], v[222:225], v[72:75]
	v_mfma_f32_16x16x32_bf16 v[124:127], v[168:171], v[202:205], v[124:127]
	v_mfma_f32_16x16x32_bf16 v[120:123], v[176:179], v[202:205], v[120:123]
	v_mfma_f32_16x16x32_bf16 v[108:111], v[168:171], v[210:213], v[108:111]
	v_mfma_f32_16x16x32_bf16 v[104:107], v[176:179], v[210:213], v[104:107]
	v_mfma_f32_16x16x32_bf16 v[92:95], v[168:171], v[218:221], v[92:95]
	v_mfma_f32_16x16x32_bf16 v[88:91], v[176:179], v[218:221], v[88:91]
	v_mfma_f32_16x16x32_bf16 v[76:79], v[168:171], v[226:229], v[76:79]
	v_mfma_f32_16x16x32_bf16 v[72:75], v[176:179], v[226:229], v[72:75]
	s_setprio 0
	s_setprio 1
	v_mfma_f32_16x16x32_bf16 v[116:119], v[180:183], v[198:201], v[116:119]
	v_mfma_f32_16x16x32_bf16 v[112:115], v[188:191], v[198:201], v[112:115]
	v_mfma_f32_16x16x32_bf16 v[100:103], v[180:183], v[206:209], v[100:103]
	v_mfma_f32_16x16x32_bf16 v[96:99], v[188:191], v[206:209], v[96:99]
	v_mfma_f32_16x16x32_bf16 v[84:87], v[180:183], v[214:217], v[84:87]
	v_mfma_f32_16x16x32_bf16 v[80:83], v[188:191], v[214:217], v[80:83]
	v_mfma_f32_16x16x32_bf16 v[68:71], v[180:183], v[222:225], v[68:71]
	v_mfma_f32_16x16x32_bf16 v[64:67], v[188:191], v[222:225], v[64:67]
	v_mfma_f32_16x16x32_bf16 v[116:119], v[184:187], v[202:205], v[116:119]
	v_mfma_f32_16x16x32_bf16 v[112:115], v[192:195], v[202:205], v[112:115]
	v_mfma_f32_16x16x32_bf16 v[100:103], v[184:187], v[210:213], v[100:103]
	v_mfma_f32_16x16x32_bf16 v[96:99], v[192:195], v[210:213], v[96:99]
	v_mfma_f32_16x16x32_bf16 v[84:87], v[184:187], v[218:221], v[84:87]
	v_mfma_f32_16x16x32_bf16 v[80:83], v[192:195], v[218:221], v[80:83]
	v_mfma_f32_16x16x32_bf16 v[68:71], v[184:187], v[226:229], v[68:71]
	v_mfma_f32_16x16x32_bf16 v[64:67], v[192:195], v[226:229], v[64:67]
	s_setprio 0
	s_barrier
; #define PG8_STAGE(bufoff, gbase, voff) do { _Pragma("unroll") for (int _i = 0; _i < 2; ++_i) \
;         __builtin_amdgcn_global_load_lds((const unsigned*)((const char*)(gbase) + (voff)[_i]), (PG8_LAS unsigned*)(lds + (bufoff) + ldsw + _i * 8192), 16, 0, 0); } while (0)
; #define PG8_LDA(dst, b, h) do { _Pragma("unroll") for (int m = 0; m < 4; ++m) _Pragma("unroll") for (int k = 0; k < 2; ++k) dst[m][k] = *(const PG8_LAS bf16x8*)(lds + PG8_SA(b, h) + aoff + m * 2048 + k * 1024); } while (0)
; #define PG8_MMA(ai, bj, At, Bt) do { __builtin_amdgcn_s_setprio(1); _Pragma("unroll") for (int m = 0; m < 4; ++m) _Pragma("unroll") for (int n = 0; n < 2; ++n) _Pragma("unroll") for (int k = 0; k < 2; ++k) \
;         acc[ai][bj][m][n] = __builtin_amdgcn_mfma_f32_16x16x32_bf16(Bt[n][k], At[m][k], acc[ai][bj][m][n], 0, 0, 0); __builtin_amdgcn_s_setprio(0); } while (0)
; #define PG8_WAIT_V(n) asm volatile("s_waitcnt vmcnt(" #n ")" ::: "memory")
; #define PG8_WAIT_L(n) asm volatile("s_waitcnt lgkmcnt(" #n ")" ::: "memory")
; #define PG8_BAR __builtin_amdgcn_s_barrier()
; #define PG8_SCHED __builtin_amdgcn_sched_barrier(0)
; template <class Epi, class Sched, bool ALIGN_EPI = false, bool SP2 = false>
; __device__ __forceinline__ void gemm_phase(PG8_LAS unsigned char* lds, const Gemm g, const Sched& S, const Epi& E) {
;     ...
;         for (int t = 0; t < nt; t += 2) {
;     ...
;             PG8_LDA(At, 1, 1); PG8_STAGE(PG8_SB(1, 0), b3, voffB); PG8_STAGE(PG8_SB(1, 1), b3 + hstep, voffB); PG8_STAGE(PG8_SA(1, 0), a3, voffA);
;             PG8_WAIT_V(8); PG8_WAIT_L(0); PG8_BAR; PG8_MMA(1, 0, At, B0); PG8_MMA(1, 1, At, B1); PG8_BAR; PG8_SCHED;
	s_add_i32 s62, s89, s70
	v_lshl_add_u64 v[230:231], v[230:231], 0, s[18:19]
	s_mov_b32 m0, s62
	ds_read_b128 v[198:201], v165 offset:49152
	ds_read_b128 v[202:205], v165 offset:50176
	ds_read_b128 v[206:209], v165 offset:51200
	ds_read_b128 v[210:213], v165 offset:52224
	ds_read_b128 v[214:217], v165 offset:53248
	ds_read_b128 v[218:221], v165 offset:54272
	ds_read_b128 v[222:225], v165 offset:55296
	ds_read_b128 v[226:229], v165 offset:56320
	global_load_lds_dwordx4 v[230:231], off
	s_add_i32 m0, s62, 0x2000
	s_add_u32 s34, s34, 0x40080
	v_lshl_add_u64 v[230:231], v[232:233], 0, s[18:19]
	s_addc_u32 s35, s35, 0
	s_add_i32 s62, s90, s70
	global_load_lds_dwordx4 v[230:231], off
	v_lshl_add_u64 v[230:231], s[34:35], 0, v[146:147]
	s_mov_b32 m0, s62
	s_nop 0
	global_load_lds_dwordx4 v[230:231], off
	v_lshl_add_u64 v[230:231], s[34:35], 0, v[150:151]
	s_add_i32 m0, s62, 0x2000
	s_nop 0
	global_load_lds_dwordx4 v[230:231], off
	v_lshl_add_u64 v[230:231], v[234:235], 0, s[18:19]
	s_mov_b32 m0, s75
	s_nop 0
	global_load_lds_dwordx4 v[230:231], off
	v_lshl_add_u64 v[230:231], v[236:237], 0, s[18:19]
	s_mov_b32 m0, s76
	s_nop 0
	global_load_lds_dwordx4 v[230:231], off
	s_waitcnt vmcnt(8)
	s_waitcnt lgkmcnt(0)
	s_barrier
	s_setprio 1
	s_waitcnt lgkmcnt(0)
	v_mfma_f32_16x16x32_bf16 v[60:63], v[140:143], v[198:201], v[60:63]
	v_mfma_f32_16x16x32_bf16 v[56:59], v[172:175], v[198:201], v[56:59]
	v_mfma_f32_16x16x32_bf16 v[48:51], v[140:143], v[206:209], v[48:51]
	v_mfma_f32_16x16x32_bf16 v[40:43], v[172:175], v[206:209], v[40:43]
	v_mfma_f32_16x16x32_bf16 v[32:35], v[140:143], v[214:217], v[32:35]
	v_mfma_f32_16x16x32_bf16 v[24:27], v[172:175], v[214:217], v[24:27]
	v_mfma_f32_16x16x32_bf16 v[16:19], v[140:143], v[222:225], v[16:19]
	v_mfma_f32_16x16x32_bf16 v[8:11], v[172:175], v[222:225], v[8:11]
	v_mfma_f32_16x16x32_bf16 v[60:63], v[168:171], v[202:205], v[60:63]
	v_mfma_f32_16x16x32_bf16 v[56:59], v[176:179], v[202:205], v[56:59]
	v_mfma_f32_16x16x32_bf16 v[48:51], v[168:171], v[210:213], v[48:51]
	v_mfma_f32_16x16x32_bf16 v[40:43], v[176:179], v[210:213], v[40:43]
	v_mfma_f32_16x16x32_bf16 v[32:35], v[168:171], v[218:221], v[32:35]
	v_mfma_f32_16x16x32_bf16 v[24:27], v[176:179], v[218:221], v[24:27]
	v_mfma_f32_16x16x32_bf16 v[16:19], v[168:171], v[226:229], v[16:19]
	v_mfma_f32_16x16x32_bf16 v[8:11], v[176:179], v[226:229], v[8:11]
	s_setprio 0
	s_setprio 1
	v_mfma_f32_16x16x32_bf16 v[52:55], v[180:183], v[198:201], v[52:55]
	v_mfma_f32_16x16x32_bf16 v[44:47], v[188:191], v[198:201], v[44:47]
	v_mfma_f32_16x16x32_bf16 v[36:39], v[180:183], v[206:209], v[36:39]
	v_mfma_f32_16x16x32_bf16 v[28:31], v[188:191], v[206:209], v[28:31]
	v_mfma_f32_16x16x32_bf16 v[20:23], v[180:183], v[214:217], v[20:23]
	v_mfma_f32_16x16x32_bf16 v[12:15], v[188:191], v[214:217], v[12:15]
	v_mfma_f32_16x16x32_bf16 v[4:7], v[180:183], v[222:225], v[4:7]
	v_mfma_f32_16x16x32_bf16 v[0:3], v[188:191], v[222:225], v[0:3]
	v_mfma_f32_16x16x32_bf16 v[52:55], v[184:187], v[202:205], v[52:55]
	v_mfma_f32_16x16x32_bf16 v[44:47], v[192:195], v[202:205], v[44:47]
	v_mfma_f32_16x16x32_bf16 v[36:39], v[184:187], v[210:213], v[36:39]
	v_mfma_f32_16x16x32_bf16 v[28:31], v[192:195], v[210:213], v[28:31]
	v_mfma_f32_16x16x32_bf16 v[20:23], v[184:187], v[218:221], v[20:23]
	v_mfma_f32_16x16x32_bf16 v[12:15], v[192:195], v[218:221], v[12:15]
	v_mfma_f32_16x16x32_bf16 v[4:7], v[184:187], v[226:229], v[4:7]
	v_mfma_f32_16x16x32_bf16 v[0:3], v[192:195], v[226:229], v[0:3]
	s_setprio 0
	s_barrier
	s_add_i32 s88, s88, 2
	s_add_u32 s20, s20, 0x100
	s_addc_u32 s21, s21, 0
	s_add_u32 s86, s86, 0x100
	s_addc_u32 s87, s87, 0
	s_cmp_gt_u32 s88, 13

; #define PG8_STAGE(bufoff, gbase, voff) do { _Pragma("unroll") for (int _i = 0; _i < 2; ++_i) \
;         __builtin_amdgcn_global_load_lds((const unsigned*)((const char*)(gbase) + (voff)[_i]), (PG8_LAS unsigned*)(lds + (bufoff) + ldsw + _i * 8192), 16, 0, 0); } while (0)
; #define PG8_LDA(dst, b, h) do { _Pragma("unroll") for (int m = 0; m < 4; ++m) _Pragma("unroll") for (int k = 0; k < 2; ++k) dst[m][k] = *(const PG8_LAS bf16x8*)(lds + PG8_SA(b, h) + aoff + m * 2048 + k * 1024); } while (0)
; #define PG8_LDB(dst, b, h) do { _Pragma("unroll") for (int n = 0; n < 2; ++n) _Pragma("unroll") for (int k = 0; k < 2; ++k) dst[n][k] = *(const PG8_LAS bf16x8*)(lds + PG8_SB(b, h) + boff + n * 2048 + k * 1024); } while (0)
; #define PG8_WAIT_V(n) asm volatile("s_waitcnt vmcnt(" #n ")" ::: "memory")
; #define PG8_WAIT_L(n) asm volatile("s_waitcnt lgkmcnt(" #n ")" ::: "memory")
; #define PG8_BAR __builtin_amdgcn_s_barrier()
; #define PG8_SCHED __builtin_amdgcn_sched_barrier(0)
; template <class Epi, class Sched, bool ALIGN_EPI = false, bool SP2 = false>
; __device__ __forceinline__ void gemm_phase(PG8_LAS unsigned char* lds, const Gemm g, const Sched& S, const Epi& E) {
;     ...
;         const bool has_next = S.next(ui + 1, nxt);
;         const char* nA = has_next ? (const char*)g.A + (size_t)nxt.pm * tstep : cA; const char* nB = has_next ? (const char*)g.Bt + (size_t)nxt.pn * tstep : cB;
;         for (int t = 0; t < nt; t += 2) {
;             const bool last = (t == nt - 2);
;             const char* a1 = cA + (size_t)(t + 1) * kstep;
;             const char* a2 = last ? nA : cA + (size_t)(t + 2) * kstep; const char* b2 = last ? nB : cB + (size_t)(t + 2) * kstep;
;             const char* a3 = a2 + kstep; const char* b3 = b2 + kstep;
;             if (last && has_next) S.a_ready(nxt);
;             if constexpr (SP2) {
;             PG8_LDB(B0, 0, 0); PG8_LDB(B1, 0, 1); PG8_SCHED; PG8_LDA(At, 0, 0); PG8_STAGE(PG8_SA(1, 1), a1 + hstep, voffA);
;             PG8_WAIT_V(8); PG8_WAIT_L(0); PG8_BAR; PG8_MMA(0, 0, At, B0); PG8_MMA(0, 1, At, B1); PG8_BAR; PG8_SCHED;
;             PG8_LDA(At, 0, 1); PG8_STAGE(PG8_SB(0, 0), b2, voffB); PG8_STAGE(PG8_SB(0, 1), b2 + hstep, voffB); PG8_STAGE(PG8_SA(0, 0), a2, voffA);
;             PG8_WAIT_V(8); PG8_WAIT_L(0); PG8_BAR; PG8_MMA(1, 0, At, B0); PG8_MMA(1, 1, At, B1); PG8_BAR; PG8_SCHED;
.LBB0_1445:
	s_ashr_i32 s15, s14, 31
	s_lshl_b64 s[16:17], s[14:15], 19
	s_add_u32 s16, s49, s16
	s_addc_u32 s17, s50, s17
	s_and_b64 s[18:19], s[4:5], exec
	s_cselect_b32 s15, s17, s21
	s_cselect_b32 s65, s16, s20
	s_ashr_i32 s13, s12, 31
	s_lshl_b64 s[18:19], s[12:13], 19
	s_add_u32 s18, s36, s18
	s_addc_u32 s19, s37, s19
	s_and_b64 s[44:45], s[4:5], exec
	s_cselect_b32 s13, s19, s39
	s_cselect_b32 s66, s18, s38
	s_add_u32 s20, s20, 0x40080
	s_addc_u32 s21, s21, 0
	s_add_u32 s67, s38, 0x100
	s_addc_u32 s68, s39, 0
	s_mov_b32 s69, -2
	ds_read_b128 v[128:131], v153
	ds_read_b128 v[132:135], v153 offset:1024
	ds_read_b128 v[136:139], v153 offset:2048
	ds_read_b128 v[140:143], v153 offset:3072
	ds_read_b128 v[172:175], v155
	ds_read_b128 v[176:179], v155 offset:1024
	ds_read_b128 v[180:183], v155 offset:2048
	ds_read_b128 v[184:187], v155 offset:3072
	s_add_u32 s38, s20, 0xfffc0080
	s_addc_u32 s39, s21, -1
	s_cmp_eq_u32 s69, 12
	s_cselect_b32 s45, s15, s39
	s_cselect_b32 s44, s65, s38
	s_cselect_b32 s39, s13, s68
	s_cselect_b32 s38, s66, s67
	v_lshl_add_u64 v[222:223], s[20:21], 0, v[162:163]
	s_add_i32 m0, s35, 0xc000
	ds_read_b128 v[188:191], v157
	ds_read_b128 v[192:195], v157 offset:1024
	ds_read_b128 v[198:201], v157 offset:2048
	ds_read_b128 v[202:205], v157 offset:3072
	ds_read_b128 v[206:209], v157 offset:4096
	ds_read_b128 v[210:213], v157 offset:5120
	ds_read_b128 v[214:217], v157 offset:6144
	ds_read_b128 v[218:221], v157 offset:7168
	global_load_lds_dwordx4 v[222:223], off
	v_lshl_add_u64 v[222:223], s[20:21], 0, v[164:165]
	s_add_i32 m0, s35, 0xe000
	s_nop 0
	global_load_lds_dwordx4 v[222:223], off
	s_waitcnt vmcnt(8)
	s_waitcnt lgkmcnt(0)
	s_barrier
	s_setprio 1
	s_waitcnt lgkmcnt(0)
	v_mfma_f32_16x16x32_bf16 v[124:127], v[128:131], v[188:191], 0
	v_mfma_f32_16x16x32_bf16 v[120:123], v[136:139], v[188:191], 0
	v_mfma_f32_16x16x32_bf16 v[108:111], v[128:131], v[198:201], 0
	v_mfma_f32_16x16x32_bf16 v[104:107], v[136:139], v[198:201], 0
	v_mfma_f32_16x16x32_bf16 v[96:99], v[128:131], v[206:209], 0
	v_mfma_f32_16x16x32_bf16 v[88:91], v[136:139], v[206:209], 0
	v_mfma_f32_16x16x32_bf16 v[80:83], v[128:131], v[214:217], 0
	v_mfma_f32_16x16x32_bf16 v[72:75], v[136:139], v[214:217], 0
	v_mfma_f32_16x16x32_bf16 v[124:127], v[132:135], v[192:195], v[124:127]
	v_mfma_f32_16x16x32_bf16 v[120:123], v[140:143], v[192:195], v[120:123]
	v_mfma_f32_16x16x32_bf16 v[108:111], v[132:135], v[202:205], v[108:111]
	v_mfma_f32_16x16x32_bf16 v[104:107], v[140:143], v[202:205], v[104:107]
	v_mfma_f32_16x16x32_bf16 v[96:99], v[132:135], v[210:213], v[96:99]
	v_mfma_f32_16x16x32_bf16 v[88:91], v[140:143], v[210:213], v[88:91]
	v_mfma_f32_16x16x32_bf16 v[80:83], v[132:135], v[218:221], v[80:83]
	v_mfma_f32_16x16x32_bf16 v[72:75], v[140:143], v[218:221], v[72:75]
	s_setprio 0
	s_setprio 1
	v_mfma_f32_16x16x32_bf16 v[116:119], v[172:175], v[188:191], 0
	v_mfma_f32_16x16x32_bf16 v[112:115], v[180:183], v[188:191], 0
	v_mfma_f32_16x16x32_bf16 v[100:103], v[172:175], v[198:201], 0
	v_mfma_f32_16x16x32_bf16 v[92:95], v[180:183], v[198:201], 0
	v_mfma_f32_16x16x32_bf16 v[84:87], v[172:175], v[206:209], 0
	v_mfma_f32_16x16x32_bf16 v[76:79], v[180:183], v[206:209], 0
	v_mfma_f32_16x16x32_bf16 v[68:71], v[172:175], v[214:217], 0
	v_mfma_f32_16x16x32_bf16 v[64:67], v[180:183], v[214:217], 0
	v_mfma_f32_16x16x32_bf16 v[116:119], v[176:179], v[192:195], v[116:119]
	v_mfma_f32_16x16x32_bf16 v[112:115], v[184:187], v[192:195], v[112:115]
	v_mfma_f32_16x16x32_bf16 v[100:103], v[176:179], v[202:205], v[100:103]
	v_mfma_f32_16x16x32_bf16 v[92:95], v[184:187], v[202:205], v[92:95]
	v_mfma_f32_16x16x32_bf16 v[84:87], v[176:179], v[210:213], v[84:87]
	v_mfma_f32_16x16x32_bf16 v[76:79], v[184:187], v[210:213], v[76:79]
	v_mfma_f32_16x16x32_bf16 v[68:71], v[176:179], v[218:221], v[68:71]
	v_mfma_f32_16x16x32_bf16 v[64:67], v[184:187], v[218:221], v[64:67]
	s_setprio 0
	s_barrier
	s_add_i32 s70, s60, s51
	v_lshl_add_u64 v[222:223], s[38:39], 0, v[146:147]
	s_mov_b32 m0, s70
	ds_read_b128 v[188:191], v157 offset:16384
	ds_read_b128 v[192:195], v157 offset:17408
	ds_read_b128 v[198:201], v157 offset:18432
	ds_read_b128 v[202:205], v157 offset:19456
	ds_read_b128 v[206:209], v157 offset:20480
	ds_read_b128 v[210:213], v157 offset:21504
	ds_read_b128 v[214:217], v157 offset:22528
	ds_read_b128 v[218:221], v157 offset:23552
	global_load_lds_dwordx4 v[222:223], off
	s_add_i32 m0, s70, 0x2000
	s_add_u32 s70, s38, 0x40000
	v_lshl_add_u64 v[224:225], s[38:39], 0, v[150:151]
	s_addc_u32 s71, s39, 0
	s_add_i32 s72, s61, s51
	global_load_lds_dwordx4 v[224:225], off
	v_lshl_add_u64 v[226:227], s[70:71], 0, v[146:147]
	s_mov_b32 m0, s72
	v_lshl_add_u64 v[228:229], s[44:45], 0, v[148:149]
	global_load_lds_dwordx4 v[226:227], off
	v_lshl_add_u64 v[226:227], s[70:71], 0, v[150:151]
	s_add_i32 m0, s72, 0x2000
	s_nop 0
	global_load_lds_dwordx4 v[226:227], off
	v_lshl_add_u64 v[226:227], s[44:45], 0, v[144:145]
	s_mov_b32 m0, s35
	s_nop 0
	global_load_lds_dwordx4 v[226:227], off
	s_mov_b32 m0, s52
	s_nop 0
	global_load_lds_dwordx4 v[228:229], off
	s_waitcnt vmcnt(8)
	s_waitcnt lgkmcnt(0)
	s_barrier
; #define PG8_STAGE(bufoff, gbase, voff) do { _Pragma("unroll") for (int _i = 0; _i < 2; ++_i) \
;         __builtin_amdgcn_global_load_lds((const unsigned*)((const char*)(gbase) + (voff)[_i]), (PG8_LAS unsigned*)(lds + (bufoff) + ldsw + _i * 8192), 16, 0, 0); } while (0)
; #define PG8_LDA(dst, b, h) do { _Pragma("unroll") for (int m = 0; m < 4; ++m) _Pragma("unroll") for (int k = 0; k < 2; ++k) dst[m][k] = *(const PG8_LAS bf16x8*)(lds + PG8_SA(b, h) + aoff + m * 2048 + k * 1024); } while (0)
; #define PG8_LDB(dst, b, h) do { _Pragma("unroll") for (int n = 0; n < 2; ++n) _Pragma("unroll") for (int k = 0; k < 2; ++k) dst[n][k] = *(const PG8_LAS bf16x8*)(lds + PG8_SB(b, h) + boff + n * 2048 + k * 1024); } while (0)
; #define PG8_MMA(ai, bj, At, Bt) do { __builtin_amdgcn_s_setprio(1); _Pragma("unroll") for (int m = 0; m < 4; ++m) _Pragma("unroll") for (int n = 0; n < 2; ++n) _Pragma("unroll") for (int k = 0; k < 2; ++k) \
;         acc[ai][bj][m][n] = __builtin_amdgcn_mfma_f32_16x16x32_bf16(Bt[n][k], At[m][k], acc[ai][bj][m][n], 0, 0, 0); __builtin_amdgcn_s_setprio(0); } while (0)
; #define PG8_WAIT_V(n) asm volatile("s_waitcnt vmcnt(" #n ")" ::: "memory")
; #define PG8_WAIT_L(n) asm volatile("s_waitcnt lgkmcnt(" #n ")" ::: "memory")
; #define PG8_BAR __builtin_amdgcn_s_barrier()
; #define PG8_SCHED __builtin_amdgcn_sched_barrier(0)
; template <class Epi, class Sched, bool ALIGN_EPI = false, bool SP2 = false>
; __device__ __forceinline__ void gemm_phase(PG8_LAS unsigned char* lds, const Gemm g, const Sched& S, const Epi& E) {
;     ...
;             PG8_WAIT_V(8); PG8_WAIT_L(0); PG8_BAR; PG8_MMA(1, 0, At, B0); PG8_MMA(1, 1, At, B1); PG8_BAR; PG8_SCHED;
;             PG8_LDB(B0, 1, 0); PG8_LDB(B1, 1, 1); PG8_SCHED; PG8_LDA(At, 1, 0); PG8_STAGE(PG8_SA(0, 1), a2 + hstep, voffA);
;             PG8_WAIT_V(8); PG8_WAIT_L(0); PG8_BAR; PG8_MMA(0, 0, At, B0); PG8_MMA(0, 1, At, B1); PG8_BAR; PG8_SCHED;
	s_setprio 1
	s_waitcnt lgkmcnt(0)
	v_mfma_f32_16x16x32_bf16 v[60:63], v[128:131], v[188:191], 0
	v_mfma_f32_16x16x32_bf16 v[56:59], v[136:139], v[188:191], 0
	v_mfma_f32_16x16x32_bf16 v[48:51], v[128:131], v[198:201], 0
	v_mfma_f32_16x16x32_bf16 v[40:43], v[136:139], v[198:201], 0
	v_mfma_f32_16x16x32_bf16 v[32:35], v[128:131], v[206:209], 0
	v_mfma_f32_16x16x32_bf16 v[24:27], v[136:139], v[206:209], 0
	v_mfma_f32_16x16x32_bf16 v[16:19], v[128:131], v[214:217], 0
	v_mfma_f32_16x16x32_bf16 v[8:11], v[136:139], v[214:217], 0
	v_mfma_f32_16x16x32_bf16 v[60:63], v[132:135], v[192:195], v[60:63]
	v_mfma_f32_16x16x32_bf16 v[56:59], v[140:143], v[192:195], v[56:59]
	v_mfma_f32_16x16x32_bf16 v[48:51], v[132:135], v[202:205], v[48:51]
	v_mfma_f32_16x16x32_bf16 v[40:43], v[140:143], v[202:205], v[40:43]
	v_mfma_f32_16x16x32_bf16 v[32:35], v[132:135], v[210:213], v[32:35]
	v_mfma_f32_16x16x32_bf16 v[24:27], v[140:143], v[210:213], v[24:27]
	v_mfma_f32_16x16x32_bf16 v[16:19], v[132:135], v[218:221], v[16:19]
	v_mfma_f32_16x16x32_bf16 v[8:11], v[140:143], v[218:221], v[8:11]
	s_setprio 0
	s_setprio 1
	v_mfma_f32_16x16x32_bf16 v[52:55], v[172:175], v[188:191], 0
	v_mfma_f32_16x16x32_bf16 v[44:47], v[180:183], v[188:191], 0
	v_mfma_f32_16x16x32_bf16 v[36:39], v[172:175], v[198:201], 0
	v_mfma_f32_16x16x32_bf16 v[28:31], v[180:183], v[198:201], 0
	v_mfma_f32_16x16x32_bf16 v[20:23], v[172:175], v[206:209], 0
	v_mfma_f32_16x16x32_bf16 v[12:15], v[180:183], v[206:209], 0
	v_mfma_f32_16x16x32_bf16 v[4:7], v[172:175], v[214:217], 0
	v_mfma_f32_16x16x32_bf16 v[0:3], v[180:183], v[214:217], 0
	v_mfma_f32_16x16x32_bf16 v[52:55], v[176:179], v[192:195], v[52:55]
	v_mfma_f32_16x16x32_bf16 v[44:47], v[184:187], v[192:195], v[44:47]
	v_mfma_f32_16x16x32_bf16 v[36:39], v[176:179], v[202:205], v[36:39]
	v_mfma_f32_16x16x32_bf16 v[28:31], v[184:187], v[202:205], v[28:31]
	v_mfma_f32_16x16x32_bf16 v[20:23], v[176:179], v[210:213], v[20:23]
	v_mfma_f32_16x16x32_bf16 v[12:15], v[184:187], v[210:213], v[12:15]
	v_mfma_f32_16x16x32_bf16 v[4:7], v[176:179], v[218:221], v[4:7]
	v_mfma_f32_16x16x32_bf16 v[0:3], v[184:187], v[218:221], v[0:3]
	s_setprio 0
	s_barrier
	s_add_i32 s70, 0, 0x18000
	s_add_i32 s71, 0, 0x1c000
	v_add_u32_e32 v140, s70, v170
	v_add_u32_e32 v159, s71, v170
	ds_read_b128 v[128:131], v140
	ds_read_b128 v[132:135], v140 offset:1024
	ds_read_b128 v[136:139], v140 offset:2048
	ds_read_b128 v[140:143], v140 offset:3072
	ds_read_b128 v[172:175], v159
	ds_read_b128 v[176:179], v159 offset:1024
	ds_read_b128 v[180:183], v159 offset:2048
	ds_read_b128 v[184:187], v159 offset:3072
	s_add_u32 s44, s44, 0x40000
	s_addc_u32 s45, s45, 0
	s_mov_b32 m0, s53
	v_lshl_add_u64 v[230:231], s[44:45], 0, v[144:145]
	ds_read_b128 v[188:191], v157 offset:32768
	ds_read_b128 v[192:195], v157 offset:33792
	ds_read_b128 v[198:201], v157 offset:34816
	ds_read_b128 v[202:205], v157 offset:35840
	ds_read_b128 v[206:209], v157 offset:36864
	ds_read_b128 v[210:213], v157 offset:37888
	ds_read_b128 v[214:217], v157 offset:38912
	ds_read_b128 v[218:221], v157 offset:39936
	global_load_lds_dwordx4 v[230:231], off
	v_lshl_add_u64 v[230:231], s[44:45], 0, v[148:149]
	s_mov_b32 m0, s54
	s_nop 0
	global_load_lds_dwordx4 v[230:231], off
	s_waitcnt vmcnt(8)
	s_waitcnt lgkmcnt(0)
	s_barrier
	s_setprio 1
	s_waitcnt lgkmcnt(0)
	v_mfma_f32_16x16x32_bf16 v[124:127], v[128:131], v[188:191], v[124:127]
	v_mfma_f32_16x16x32_bf16 v[120:123], v[136:139], v[188:191], v[120:123]
	v_mfma_f32_16x16x32_bf16 v[108:111], v[128:131], v[198:201], v[108:111]
	v_mfma_f32_16x16x32_bf16 v[104:107], v[136:139], v[198:201], v[104:107]
	v_mfma_f32_16x16x32_bf16 v[96:99], v[128:131], v[206:209], v[96:99]
	v_mfma_f32_16x16x32_bf16 v[88:91], v[136:139], v[206:209], v[88:91]
	v_mfma_f32_16x16x32_bf16 v[80:83], v[128:131], v[214:217], v[80:83]
	v_mfma_f32_16x16x32_bf16 v[72:75], v[136:139], v[214:217], v[72:75]
	v_mfma_f32_16x16x32_bf16 v[124:127], v[132:135], v[192:195], v[124:127]
	v_mfma_f32_16x16x32_bf16 v[120:123], v[140:143], v[192:195], v[120:123]
	v_mfma_f32_16x16x32_bf16 v[108:111], v[132:135], v[202:205], v[108:111]
	v_mfma_f32_16x16x32_bf16 v[104:107], v[140:143], v[202:205], v[104:107]
	v_mfma_f32_16x16x32_bf16 v[96:99], v[132:135], v[210:213], v[96:99]
	v_mfma_f32_16x16x32_bf16 v[88:91], v[140:143], v[210:213], v[88:91]
	v_mfma_f32_16x16x32_bf16 v[80:83], v[132:135], v[218:221], v[80:83]
	v_mfma_f32_16x16x32_bf16 v[72:75], v[140:143], v[218:221], v[72:75]
	s_setprio 0
	s_setprio 1
	v_mfma_f32_16x16x32_bf16 v[116:119], v[172:175], v[188:191], v[116:119]
	v_mfma_f32_16x16x32_bf16 v[112:115], v[180:183], v[188:191], v[112:115]
	v_mfma_f32_16x16x32_bf16 v[100:103], v[172:175], v[198:201], v[100:103]
	v_mfma_f32_16x16x32_bf16 v[92:95], v[180:183], v[198:201], v[92:95]
	v_mfma_f32_16x16x32_bf16 v[84:87], v[172:175], v[206:209], v[84:87]
	v_mfma_f32_16x16x32_bf16 v[76:79], v[180:183], v[206:209], v[76:79]
	v_mfma_f32_16x16x32_bf16 v[68:71], v[172:175], v[214:217], v[68:71]
	v_mfma_f32_16x16x32_bf16 v[64:67], v[180:183], v[214:217], v[64:67]
	v_mfma_f32_16x16x32_bf16 v[116:119], v[176:179], v[192:195], v[116:119]
	v_mfma_f32_16x16x32_bf16 v[112:115], v[184:187], v[192:195], v[112:115]
	v_mfma_f32_16x16x32_bf16 v[100:103], v[176:179], v[202:205], v[100:103]
	v_mfma_f32_16x16x32_bf16 v[92:95], v[184:187], v[202:205], v[92:95]
	v_mfma_f32_16x16x32_bf16 v[84:87], v[176:179], v[210:213], v[84:87]
	v_mfma_f32_16x16x32_bf16 v[76:79], v[184:187], v[210:213], v[76:79]
	v_mfma_f32_16x16x32_bf16 v[68:71], v[176:179], v[218:221], v[68:71]
	v_mfma_f32_16x16x32_bf16 v[64:67], v[184:187], v[218:221], v[64:67]
	s_setprio 0
	s_barrier
; #define PG8_STAGE(bufoff, gbase, voff) do { _Pragma("unroll") for (int _i = 0; _i < 2; ++_i) \
;         __builtin_amdgcn_global_load_lds((const unsigned*)((const char*)(gbase) + (voff)[_i]), (PG8_LAS unsigned*)(lds + (bufoff) + ldsw + _i * 8192), 16, 0, 0); } while (0)
; #define PG8_LDA(dst, b, h) do { _Pragma("unroll") for (int m = 0; m < 4; ++m) _Pragma("unroll") for (int k = 0; k < 2; ++k) dst[m][k] = *(const PG8_LAS bf16x8*)(lds + PG8_SA(b, h) + aoff + m * 2048 + k * 1024); } while (0)
; #define PG8_MMA(ai, bj, At, Bt) do { __builtin_amdgcn_s_setprio(1); _Pragma("unroll") for (int m = 0; m < 4; ++m) _Pragma("unroll") for (int n = 0; n < 2; ++n) _Pragma("unroll") for (int k = 0; k < 2; ++k) \
;         acc[ai][bj][m][n] = __builtin_amdgcn_mfma_f32_16x16x32_bf16(Bt[n][k], At[m][k], acc[ai][bj][m][n], 0, 0, 0); __builtin_amdgcn_s_setprio(0); } while (0)
; #define PG8_WAIT_V(n) asm volatile("s_waitcnt vmcnt(" #n ")" ::: "memory")
; #define PG8_WAIT_L(n) asm volatile("s_waitcnt lgkmcnt(" #n ")" ::: "memory")
; #define PG8_BAR __builtin_amdgcn_s_barrier()
; #define PG8_SCHED __builtin_amdgcn_sched_barrier(0)
; template <class Epi, class Sched, bool ALIGN_EPI = false, bool SP2 = false>
; __device__ __forceinline__ void gemm_phase(PG8_LAS unsigned char* lds, const Gemm g, const Sched& S, const Epi& E) {
;     ...
;         for (int t = 0; t < nt; t += 2) {
;     ...
;             PG8_LDA(At, 1, 1); PG8_STAGE(PG8_SB(1, 0), b3, voffB); PG8_STAGE(PG8_SB(1, 1), b3 + hstep, voffB); PG8_STAGE(PG8_SA(1, 0), a3, voffA);
;             PG8_WAIT_V(8); PG8_WAIT_L(0); PG8_BAR; PG8_MMA(1, 0, At, B0); PG8_MMA(1, 1, At, B1); PG8_BAR; PG8_SCHED;
	s_add_i32 s44, s70, s51
	v_lshl_add_u64 v[222:223], v[222:223], 0, s[6:7]
	s_mov_b32 m0, s44
	ds_read_b128 v[188:191], v157 offset:49152
	ds_read_b128 v[192:195], v157 offset:50176
	ds_read_b128 v[198:201], v157 offset:51200
	ds_read_b128 v[202:205], v157 offset:52224
	ds_read_b128 v[206:209], v157 offset:53248
	ds_read_b128 v[210:213], v157 offset:54272
	ds_read_b128 v[214:217], v157 offset:55296
	ds_read_b128 v[218:221], v157 offset:56320
	global_load_lds_dwordx4 v[222:223], off
	s_add_i32 m0, s44, 0x2000
	s_add_u32 s38, s38, 0x40080
	v_lshl_add_u64 v[222:223], v[224:225], 0, s[6:7]
	s_addc_u32 s39, s39, 0
	s_add_i32 s44, s71, s51
	global_load_lds_dwordx4 v[222:223], off
	v_lshl_add_u64 v[222:223], s[38:39], 0, v[146:147]
	s_mov_b32 m0, s44
	s_nop 0
	global_load_lds_dwordx4 v[222:223], off
	v_lshl_add_u64 v[222:223], s[38:39], 0, v[150:151]
	s_add_i32 m0, s44, 0x2000
	s_nop 0
	global_load_lds_dwordx4 v[222:223], off
	v_lshl_add_u64 v[222:223], v[226:227], 0, s[6:7]
	s_mov_b32 m0, s58
	s_nop 0
	global_load_lds_dwordx4 v[222:223], off
	v_lshl_add_u64 v[222:223], v[228:229], 0, s[6:7]
	s_mov_b32 m0, s59
	s_nop 0
	global_load_lds_dwordx4 v[222:223], off
	s_waitcnt vmcnt(8)
	s_waitcnt lgkmcnt(0)
	s_barrier
	s_setprio 1
	s_waitcnt lgkmcnt(0)
	v_mfma_f32_16x16x32_bf16 v[60:63], v[128:131], v[188:191], v[60:63]
	v_mfma_f32_16x16x32_bf16 v[56:59], v[136:139], v[188:191], v[56:59]
	v_mfma_f32_16x16x32_bf16 v[48:51], v[128:131], v[198:201], v[48:51]
	v_mfma_f32_16x16x32_bf16 v[40:43], v[136:139], v[198:201], v[40:43]
	v_mfma_f32_16x16x32_bf16 v[32:35], v[128:131], v[206:209], v[32:35]
	v_mfma_f32_16x16x32_bf16 v[24:27], v[136:139], v[206:209], v[24:27]
	v_mfma_f32_16x16x32_bf16 v[16:19], v[128:131], v[214:217], v[16:19]
	v_mfma_f32_16x16x32_bf16 v[8:11], v[136:139], v[214:217], v[8:11]
	v_mfma_f32_16x16x32_bf16 v[60:63], v[132:135], v[192:195], v[60:63]
	v_mfma_f32_16x16x32_bf16 v[56:59], v[140:143], v[192:195], v[56:59]
	v_mfma_f32_16x16x32_bf16 v[48:51], v[132:135], v[202:205], v[48:51]
	v_mfma_f32_16x16x32_bf16 v[40:43], v[140:143], v[202:205], v[40:43]
	v_mfma_f32_16x16x32_bf16 v[32:35], v[132:135], v[210:213], v[32:35]
	v_mfma_f32_16x16x32_bf16 v[24:27], v[140:143], v[210:213], v[24:27]
	v_mfma_f32_16x16x32_bf16 v[16:19], v[132:135], v[218:221], v[16:19]
	v_mfma_f32_16x16x32_bf16 v[8:11], v[140:143], v[218:221], v[8:11]
	s_setprio 0
	s_setprio 1
	v_mfma_f32_16x16x32_bf16 v[52:55], v[172:175], v[188:191], v[52:55]
	v_mfma_f32_16x16x32_bf16 v[44:47], v[180:183], v[188:191], v[44:47]
	v_mfma_f32_16x16x32_bf16 v[36:39], v[172:175], v[198:201], v[36:39]
	v_mfma_f32_16x16x32_bf16 v[28:31], v[180:183], v[198:201], v[28:31]
	v_mfma_f32_16x16x32_bf16 v[20:23], v[172:175], v[206:209], v[20:23]
	v_mfma_f32_16x16x32_bf16 v[12:15], v[180:183], v[206:209], v[12:15]
	v_mfma_f32_16x16x32_bf16 v[4:7], v[172:175], v[214:217], v[4:7]
	v_mfma_f32_16x16x32_bf16 v[0:3], v[180:183], v[214:217], v[0:3]
	v_mfma_f32_16x16x32_bf16 v[52:55], v[176:179], v[192:195], v[52:55]
	v_mfma_f32_16x16x32_bf16 v[44:47], v[184:187], v[192:195], v[44:47]
	v_mfma_f32_16x16x32_bf16 v[36:39], v[176:179], v[202:205], v[36:39]
	v_mfma_f32_16x16x32_bf16 v[28:31], v[184:187], v[202:205], v[28:31]
	v_mfma_f32_16x16x32_bf16 v[20:23], v[176:179], v[210:213], v[20:23]
	v_mfma_f32_16x16x32_bf16 v[12:15], v[184:187], v[210:213], v[12:15]
	v_mfma_f32_16x16x32_bf16 v[4:7], v[176:179], v[218:221], v[4:7]
	v_mfma_f32_16x16x32_bf16 v[0:3], v[184:187], v[218:221], v[0:3]
	s_setprio 0
	s_barrier
	s_add_i32 s69, s69, 2
	s_add_u32 s20, s20, 0x100
	s_addc_u32 s21, s21, 0
	s_add_u32 s67, s67, 0x100
	s_addc_u32 s68, s68, 0
	s_cmp_gt_u32 s69, 13

; #define PG8_STAGE(bufoff, gbase, voff) do { _Pragma("unroll") for (int _i = 0; _i < 2; ++_i) \
;         __builtin_amdgcn_global_load_lds((const unsigned*)((const char*)(gbase) + (voff)[_i]), (PG8_LAS unsigned*)(lds + (bufoff) + ldsw + _i * 8192), 16, 0, 0); } while (0)
; #define PG8_LDA(dst, b, h) do { _Pragma("unroll") for (int m = 0; m < 4; ++m) _Pragma("unroll") for (int k = 0; k < 2; ++k) dst[m][k] = *(const PG8_LAS bf16x8*)(lds + PG8_SA(b, h) + aoff + m * 2048 + k * 1024); } while (0)
; #define PG8_LDB(dst, b, h) do { _Pragma("unroll") for (int n = 0; n < 2; ++n) _Pragma("unroll") for (int k = 0; k < 2; ++k) dst[n][k] = *(const PG8_LAS bf16x8*)(lds + PG8_SB(b, h) + boff + n * 2048 + k * 1024); } while (0)
; #define PG8_WAIT_V(n) asm volatile("s_waitcnt vmcnt(" #n ")" ::: "memory")
; #define PG8_WAIT_L(n) asm volatile("s_waitcnt lgkmcnt(" #n ")" ::: "memory")
; #define PG8_BAR __builtin_amdgcn_s_barrier()
; #define PG8_SCHED __builtin_amdgcn_sched_barrier(0)
; template <class Epi, class Sched, bool ALIGN_EPI = false, bool SP2 = false>
; __device__ __forceinline__ void gemm_phase(PG8_LAS unsigned char* lds, const Gemm g, const Sched& S, const Epi& E) {
;     ...
;         const bool has_next = S.next(ui + 1, nxt);
;         const char* nA = has_next ? (const char*)g.A + (size_t)nxt.pm * tstep : cA; const char* nB = has_next ? (const char*)g.Bt + (size_t)nxt.pn * tstep : cB;
;         for (int t = 0; t < nt; t += 2) {
;             const bool last = (t == nt - 2);
;             const char* a1 = cA + (size_t)(t + 1) * kstep;
;             const char* a2 = last ? nA : cA + (size_t)(t + 2) * kstep; const char* b2 = last ? nB : cB + (size_t)(t + 2) * kstep;
;             const char* a3 = a2 + kstep; const char* b3 = b2 + kstep;
;             if (last && has_next) S.a_ready(nxt);
;             if constexpr (SP2) {
;             PG8_LDB(B0, 0, 0); PG8_LDB(B1, 0, 1); PG8_SCHED; PG8_LDA(At, 0, 0); PG8_STAGE(PG8_SA(1, 1), a1 + hstep, voffA);
;             PG8_WAIT_V(8); PG8_WAIT_L(0); PG8_BAR; PG8_MMA(0, 0, At, B0); PG8_MMA(0, 1, At, B1); PG8_BAR; PG8_SCHED;
;             PG8_LDA(At, 0, 1); PG8_STAGE(PG8_SB(0, 0), b2, voffB); PG8_STAGE(PG8_SB(0, 1), b2 + hstep, voffB); PG8_STAGE(PG8_SA(0, 0), a2, voffA);
;             PG8_WAIT_V(8); PG8_WAIT_L(0); PG8_BAR; PG8_MMA(1, 0, At, B0); PG8_MMA(1, 1, At, B1); PG8_BAR; PG8_SCHED;
.LBB0_1634:
	s_ashr_i32 s47, s46, 31
	s_lshl_b64 s[48:49], s[46:47], 19
	s_add_u32 s48, s18, s48
	s_addc_u32 s49, s19, s49
	s_and_b64 s[50:51], s[6:7], exec
	s_cselect_b32 s35, s49, s21
	s_cselect_b32 s47, s48, s20
	s_ashr_i32 s45, s44, 31
	s_lshl_b64 s[50:51], s[44:45], 19
	s_add_u32 s50, s3, s50
	s_addc_u32 s51, s33, s51
	s_and_b64 s[56:57], s[6:7], exec
	s_cselect_b32 s45, s51, s55
	s_cselect_b32 s73, s50, s54
	s_add_u32 s20, s20, 0x40080
	s_addc_u32 s21, s21, 0
	s_add_u32 s74, s54, 0x100
	s_addc_u32 s75, s55, 0
	s_mov_b32 s76, -2
	s_waitcnt lgkmcnt(0)
	ds_read_b128 v[96:99], v223
	ds_read_b128 v[108:111], v223 offset:1024
	ds_read_b128 v[120:123], v223 offset:2048
	ds_read_b128 v[128:131], v223 offset:3072
	ds_read_b128 v[144:147], v224
	ds_read_b128 v[148:151], v224 offset:1024
	ds_read_b128 v[152:155], v224 offset:2048
	ds_read_b128 v[156:159], v224 offset:3072
	s_add_u32 s54, s20, 0xfffc0080
	s_addc_u32 s55, s21, -1
	s_cmp_eq_u32 s76, 12
	s_cselect_b32 s57, s35, s55
	s_cselect_b32 s56, s47, s54
	s_cselect_b32 s55, s45, s75
	s_cselect_b32 s54, s73, s74
	v_lshl_add_u64 v[210:211], s[20:21], 0, v[192:193]
	s_add_i32 m0, s53, 0xc000
	ds_read_b128 v[160:163], v225
	ds_read_b128 v[164:167], v225 offset:1024
	ds_read_b128 v[168:171], v225 offset:2048
	ds_read_b128 v[172:175], v225 offset:3072
	ds_read_b128 v[176:179], v225 offset:4096
	ds_read_b128 v[180:183], v225 offset:5120
	ds_read_b128 v[202:205], v225 offset:6144
	ds_read_b128 v[206:209], v225 offset:7168
	global_load_lds_dwordx4 v[210:211], off
	v_lshl_add_u64 v[210:211], s[20:21], 0, v[194:195]
	s_add_i32 m0, s53, 0xe000
	s_nop 0
	global_load_lds_dwordx4 v[210:211], off
	s_waitcnt vmcnt(8)
	s_waitcnt lgkmcnt(0)
	s_barrier
	s_setprio 1
	s_waitcnt lgkmcnt(0)
	v_mfma_f32_16x16x32_bf16 v[140:143], v[96:99], v[160:163], 0
	v_mfma_f32_16x16x32_bf16 v[136:139], v[120:123], v[160:163], 0
	v_mfma_f32_16x16x32_bf16 v[116:119], v[96:99], v[168:171], 0
	v_mfma_f32_16x16x32_bf16 v[112:115], v[120:123], v[168:171], 0
	v_mfma_f32_16x16x32_bf16 v[92:95], v[96:99], v[176:179], 0
	v_mfma_f32_16x16x32_bf16 v[88:91], v[120:123], v[176:179], 0
	v_mfma_f32_16x16x32_bf16 v[76:79], v[96:99], v[202:205], 0
	v_mfma_f32_16x16x32_bf16 v[72:75], v[120:123], v[202:205], 0
	v_mfma_f32_16x16x32_bf16 v[140:143], v[108:111], v[164:167], v[140:143]
	v_mfma_f32_16x16x32_bf16 v[136:139], v[128:131], v[164:167], v[136:139]
	v_mfma_f32_16x16x32_bf16 v[116:119], v[108:111], v[172:175], v[116:119]
	v_mfma_f32_16x16x32_bf16 v[112:115], v[128:131], v[172:175], v[112:115]
	v_mfma_f32_16x16x32_bf16 v[92:95], v[108:111], v[180:183], v[92:95]
	v_mfma_f32_16x16x32_bf16 v[88:91], v[128:131], v[180:183], v[88:91]
	v_mfma_f32_16x16x32_bf16 v[76:79], v[108:111], v[206:209], v[76:79]
	v_mfma_f32_16x16x32_bf16 v[72:75], v[128:131], v[206:209], v[72:75]
	s_setprio 0
	s_setprio 1
	v_mfma_f32_16x16x32_bf16 v[132:135], v[144:147], v[160:163], 0
	v_mfma_f32_16x16x32_bf16 v[124:127], v[152:155], v[160:163], 0
	v_mfma_f32_16x16x32_bf16 v[104:107], v[144:147], v[168:171], 0
	v_mfma_f32_16x16x32_bf16 v[100:103], v[152:155], v[168:171], 0
	v_mfma_f32_16x16x32_bf16 v[84:87], v[144:147], v[176:179], 0
	v_mfma_f32_16x16x32_bf16 v[80:83], v[152:155], v[176:179], 0
	v_mfma_f32_16x16x32_bf16 v[68:71], v[144:147], v[202:205], 0
	v_mfma_f32_16x16x32_bf16 v[64:67], v[152:155], v[202:205], 0
	v_mfma_f32_16x16x32_bf16 v[132:135], v[148:151], v[164:167], v[132:135]
	v_mfma_f32_16x16x32_bf16 v[124:127], v[156:159], v[164:167], v[124:127]
	v_mfma_f32_16x16x32_bf16 v[104:107], v[148:151], v[172:175], v[104:107]
	v_mfma_f32_16x16x32_bf16 v[100:103], v[156:159], v[172:175], v[100:103]
	v_mfma_f32_16x16x32_bf16 v[84:87], v[148:151], v[180:183], v[84:87]
	v_mfma_f32_16x16x32_bf16 v[80:83], v[156:159], v[180:183], v[80:83]
	v_mfma_f32_16x16x32_bf16 v[68:71], v[148:151], v[206:209], v[68:71]
	v_mfma_f32_16x16x32_bf16 v[64:67], v[156:159], v[206:209], v[64:67]
	s_setprio 0
	s_barrier
	s_add_i32 s77, s71, s58
	v_lshl_add_u64 v[210:211], s[54:55], 0, v[186:187]
	s_mov_b32 m0, s77
	ds_read_b128 v[160:163], v225 offset:16384
	ds_read_b128 v[164:167], v225 offset:17408
	ds_read_b128 v[168:171], v225 offset:18432
	ds_read_b128 v[172:175], v225 offset:19456
	ds_read_b128 v[176:179], v225 offset:20480
	ds_read_b128 v[180:183], v225 offset:21504
	ds_read_b128 v[202:205], v225 offset:22528
	ds_read_b128 v[206:209], v225 offset:23552
	global_load_lds_dwordx4 v[210:211], off
	s_add_i32 m0, s77, 0x2000
	s_add_u32 s78, s54, 0x40000
	v_lshl_add_u64 v[212:213], s[54:55], 0, v[190:191]
	s_addc_u32 s79, s55, 0
	s_add_i32 s77, s72, s58
	global_load_lds_dwordx4 v[212:213], off
	v_lshl_add_u64 v[214:215], s[78:79], 0, v[186:187]
	s_mov_b32 m0, s77
	v_lshl_add_u64 v[216:217], s[56:57], 0, v[188:189]
	global_load_lds_dwordx4 v[214:215], off
	v_lshl_add_u64 v[214:215], s[78:79], 0, v[190:191]
	s_add_i32 m0, s77, 0x2000
	s_nop 0
	global_load_lds_dwordx4 v[214:215], off
	v_lshl_add_u64 v[214:215], s[56:57], 0, v[184:185]
	s_mov_b32 m0, s53
	s_nop 0
	global_load_lds_dwordx4 v[214:215], off
	s_mov_b32 m0, s59
	s_nop 0
	global_load_lds_dwordx4 v[216:217], off
	s_waitcnt vmcnt(8)
	s_waitcnt lgkmcnt(0)
	s_barrier
; #define PG8_STAGE(bufoff, gbase, voff) do { _Pragma("unroll") for (int _i = 0; _i < 2; ++_i) \
;         __builtin_amdgcn_global_load_lds((const unsigned*)((const char*)(gbase) + (voff)[_i]), (PG8_LAS unsigned*)(lds + (bufoff) + ldsw + _i * 8192), 16, 0, 0); } while (0)
; #define PG8_LDA(dst, b, h) do { _Pragma("unroll") for (int m = 0; m < 4; ++m) _Pragma("unroll") for (int k = 0; k < 2; ++k) dst[m][k] = *(const PG8_LAS bf16x8*)(lds + PG8_SA(b, h) + aoff + m * 2048 + k * 1024); } while (0)
; #define PG8_LDB(dst, b, h) do { _Pragma("unroll") for (int n = 0; n < 2; ++n) _Pragma("unroll") for (int k = 0; k < 2; ++k) dst[n][k] = *(const PG8_LAS bf16x8*)(lds + PG8_SB(b, h) + boff + n * 2048 + k * 1024); } while (0)
; #define PG8_MMA(ai, bj, At, Bt) do { __builtin_amdgcn_s_setprio(1); _Pragma("unroll") for (int m = 0; m < 4; ++m) _Pragma("unroll") for (int n = 0; n < 2; ++n) _Pragma("unroll") for (int k = 0; k < 2; ++k) \
;         acc[ai][bj][m][n] = __builtin_amdgcn_mfma_f32_16x16x32_bf16(Bt[n][k], At[m][k], acc[ai][bj][m][n], 0, 0, 0); __builtin_amdgcn_s_setprio(0); } while (0)
; #define PG8_WAIT_V(n) asm volatile("s_waitcnt vmcnt(" #n ")" ::: "memory")
; #define PG8_WAIT_L(n) asm volatile("s_waitcnt lgkmcnt(" #n ")" ::: "memory")
; #define PG8_BAR __builtin_amdgcn_s_barrier()
; #define PG8_SCHED __builtin_amdgcn_sched_barrier(0)
; template <class Epi, class Sched, bool ALIGN_EPI = false, bool SP2 = false>
; __device__ __forceinline__ void gemm_phase(PG8_LAS unsigned char* lds, const Gemm g, const Sched& S, const Epi& E) {
;     ...
;             PG8_WAIT_V(8); PG8_WAIT_L(0); PG8_BAR; PG8_MMA(1, 0, At, B0); PG8_MMA(1, 1, At, B1); PG8_BAR; PG8_SCHED;
;             PG8_LDB(B0, 1, 0); PG8_LDB(B1, 1, 1); PG8_SCHED; PG8_LDA(At, 1, 0); PG8_STAGE(PG8_SA(0, 1), a2 + hstep, voffA);
;             PG8_WAIT_V(8); PG8_WAIT_L(0); PG8_BAR; PG8_MMA(0, 0, At, B0); PG8_MMA(0, 1, At, B1); PG8_BAR; PG8_SCHED;
	s_setprio 1
	s_waitcnt lgkmcnt(0)
	v_mfma_f32_16x16x32_bf16 v[60:63], v[96:99], v[160:163], 0
	v_mfma_f32_16x16x32_bf16 v[56:59], v[120:123], v[160:163], 0
	v_mfma_f32_16x16x32_bf16 v[44:47], v[96:99], v[168:171], 0
	v_mfma_f32_16x16x32_bf16 v[40:43], v[120:123], v[168:171], 0
	v_mfma_f32_16x16x32_bf16 v[28:31], v[96:99], v[176:179], 0
	v_mfma_f32_16x16x32_bf16 v[24:27], v[120:123], v[176:179], 0
	v_mfma_f32_16x16x32_bf16 v[12:15], v[96:99], v[202:205], 0
	v_mfma_f32_16x16x32_bf16 v[8:11], v[120:123], v[202:205], 0
	v_mfma_f32_16x16x32_bf16 v[60:63], v[108:111], v[164:167], v[60:63]
	v_mfma_f32_16x16x32_bf16 v[56:59], v[128:131], v[164:167], v[56:59]
	v_mfma_f32_16x16x32_bf16 v[44:47], v[108:111], v[172:175], v[44:47]
	v_mfma_f32_16x16x32_bf16 v[40:43], v[128:131], v[172:175], v[40:43]
	v_mfma_f32_16x16x32_bf16 v[28:31], v[108:111], v[180:183], v[28:31]
	v_mfma_f32_16x16x32_bf16 v[24:27], v[128:131], v[180:183], v[24:27]
	v_mfma_f32_16x16x32_bf16 v[12:15], v[108:111], v[206:209], v[12:15]
	v_mfma_f32_16x16x32_bf16 v[8:11], v[128:131], v[206:209], v[8:11]
	s_setprio 0
	s_setprio 1
	v_mfma_f32_16x16x32_bf16 v[52:55], v[144:147], v[160:163], 0
	v_mfma_f32_16x16x32_bf16 v[48:51], v[152:155], v[160:163], 0
	v_mfma_f32_16x16x32_bf16 v[36:39], v[144:147], v[168:171], 0
	v_mfma_f32_16x16x32_bf16 v[32:35], v[152:155], v[168:171], 0
	v_mfma_f32_16x16x32_bf16 v[20:23], v[144:147], v[176:179], 0
	v_mfma_f32_16x16x32_bf16 v[16:19], v[152:155], v[176:179], 0
	v_mfma_f32_16x16x32_bf16 v[4:7], v[144:147], v[202:205], 0
	v_mfma_f32_16x16x32_bf16 v[0:3], v[152:155], v[202:205], 0
	v_mfma_f32_16x16x32_bf16 v[52:55], v[148:151], v[164:167], v[52:55]
	v_mfma_f32_16x16x32_bf16 v[48:51], v[156:159], v[164:167], v[48:51]
	v_mfma_f32_16x16x32_bf16 v[36:39], v[148:151], v[172:175], v[36:39]
	v_mfma_f32_16x16x32_bf16 v[32:35], v[156:159], v[172:175], v[32:35]
	v_mfma_f32_16x16x32_bf16 v[20:23], v[148:151], v[180:183], v[20:23]
	v_mfma_f32_16x16x32_bf16 v[16:19], v[156:159], v[180:183], v[16:19]
	v_mfma_f32_16x16x32_bf16 v[4:7], v[148:151], v[206:209], v[4:7]
	v_mfma_f32_16x16x32_bf16 v[0:3], v[156:159], v[206:209], v[0:3]
	s_setprio 0
	s_barrier
	s_add_i32 s77, 0, 0x18000
	s_add_i32 s78, 0, 0x1c000
	v_add_u32_e32 v128, s77, v221
	v_add_u32_e32 v156, s78, v221
	ds_read_b128 v[96:99], v128
	ds_read_b128 v[108:111], v128 offset:1024
	ds_read_b128 v[120:123], v128 offset:2048
	ds_read_b128 v[128:131], v128 offset:3072
	ds_read_b128 v[144:147], v156
	ds_read_b128 v[148:151], v156 offset:1024
	ds_read_b128 v[152:155], v156 offset:2048
	ds_read_b128 v[156:159], v156 offset:3072
	s_add_u32 s56, s56, 0x40000
	s_addc_u32 s57, s57, 0
	s_mov_b32 m0, s60
	v_lshl_add_u64 v[218:219], s[56:57], 0, v[184:185]
	ds_read_b128 v[160:163], v225 offset:32768
	ds_read_b128 v[164:167], v225 offset:33792
	ds_read_b128 v[168:171], v225 offset:34816
	ds_read_b128 v[172:175], v225 offset:35840
	ds_read_b128 v[176:179], v225 offset:36864
	ds_read_b128 v[180:183], v225 offset:37888
	ds_read_b128 v[202:205], v225 offset:38912
	ds_read_b128 v[206:209], v225 offset:39936
	global_load_lds_dwordx4 v[218:219], off
	v_lshl_add_u64 v[218:219], s[56:57], 0, v[188:189]
	s_mov_b32 m0, s61
	s_nop 0
	global_load_lds_dwordx4 v[218:219], off
	s_waitcnt vmcnt(8)
	s_waitcnt lgkmcnt(0)
	s_barrier
	s_setprio 1
	s_waitcnt lgkmcnt(0)
	v_mfma_f32_16x16x32_bf16 v[140:143], v[96:99], v[160:163], v[140:143]
	v_mfma_f32_16x16x32_bf16 v[136:139], v[120:123], v[160:163], v[136:139]
	v_mfma_f32_16x16x32_bf16 v[116:119], v[96:99], v[168:171], v[116:119]
	v_mfma_f32_16x16x32_bf16 v[112:115], v[120:123], v[168:171], v[112:115]
	v_mfma_f32_16x16x32_bf16 v[92:95], v[96:99], v[176:179], v[92:95]
	v_mfma_f32_16x16x32_bf16 v[88:91], v[120:123], v[176:179], v[88:91]
	v_mfma_f32_16x16x32_bf16 v[76:79], v[96:99], v[202:205], v[76:79]
	v_mfma_f32_16x16x32_bf16 v[72:75], v[120:123], v[202:205], v[72:75]
	v_mfma_f32_16x16x32_bf16 v[140:143], v[108:111], v[164:167], v[140:143]
	v_mfma_f32_16x16x32_bf16 v[136:139], v[128:131], v[164:167], v[136:139]
	v_mfma_f32_16x16x32_bf16 v[116:119], v[108:111], v[172:175], v[116:119]
	v_mfma_f32_16x16x32_bf16 v[112:115], v[128:131], v[172:175], v[112:115]
	v_mfma_f32_16x16x32_bf16 v[92:95], v[108:111], v[180:183], v[92:95]
	v_mfma_f32_16x16x32_bf16 v[88:91], v[128:131], v[180:183], v[88:91]
	v_mfma_f32_16x16x32_bf16 v[76:79], v[108:111], v[206:209], v[76:79]
	v_mfma_f32_16x16x32_bf16 v[72:75], v[128:131], v[206:209], v[72:75]
	s_setprio 0
	s_setprio 1
	v_mfma_f32_16x16x32_bf16 v[132:135], v[144:147], v[160:163], v[132:135]
	v_mfma_f32_16x16x32_bf16 v[124:127], v[152:155], v[160:163], v[124:127]
	v_mfma_f32_16x16x32_bf16 v[104:107], v[144:147], v[168:171], v[104:107]
	v_mfma_f32_16x16x32_bf16 v[100:103], v[152:155], v[168:171], v[100:103]
	v_mfma_f32_16x16x32_bf16 v[84:87], v[144:147], v[176:179], v[84:87]
	v_mfma_f32_16x16x32_bf16 v[80:83], v[152:155], v[176:179], v[80:83]
	v_mfma_f32_16x16x32_bf16 v[68:71], v[144:147], v[202:205], v[68:71]
	v_mfma_f32_16x16x32_bf16 v[64:67], v[152:155], v[202:205], v[64:67]
	v_mfma_f32_16x16x32_bf16 v[132:135], v[148:151], v[164:167], v[132:135]
	v_mfma_f32_16x16x32_bf16 v[124:127], v[156:159], v[164:167], v[124:127]
	v_mfma_f32_16x16x32_bf16 v[104:107], v[148:151], v[172:175], v[104:107]
	v_mfma_f32_16x16x32_bf16 v[100:103], v[156:159], v[172:175], v[100:103]
	v_mfma_f32_16x16x32_bf16 v[84:87], v[148:151], v[180:183], v[84:87]
	v_mfma_f32_16x16x32_bf16 v[80:83], v[156:159], v[180:183], v[80:83]
	v_mfma_f32_16x16x32_bf16 v[68:71], v[148:151], v[206:209], v[68:71]
	v_mfma_f32_16x16x32_bf16 v[64:67], v[156:159], v[206:209], v[64:67]
	s_setprio 0
	s_barrier
; #define PG8_STAGE(bufoff, gbase, voff) do { _Pragma("unroll") for (int _i = 0; _i < 2; ++_i) \
;         __builtin_amdgcn_global_load_lds((const unsigned*)((const char*)(gbase) + (voff)[_i]), (PG8_LAS unsigned*)(lds + (bufoff) + ldsw + _i * 8192), 16, 0, 0); } while (0)
; #define PG8_LDA(dst, b, h) do { _Pragma("unroll") for (int m = 0; m < 4; ++m) _Pragma("unroll") for (int k = 0; k < 2; ++k) dst[m][k] = *(const PG8_LAS bf16x8*)(lds + PG8_SA(b, h) + aoff + m * 2048 + k * 1024); } while (0)
; #define PG8_MMA(ai, bj, At, Bt) do { __builtin_amdgcn_s_setprio(1); _Pragma("unroll") for (int m = 0; m < 4; ++m) _Pragma("unroll") for (int n = 0; n < 2; ++n) _Pragma("unroll") for (int k = 0; k < 2; ++k) \
;         acc[ai][bj][m][n] = __builtin_amdgcn_mfma_f32_16x16x32_bf16(Bt[n][k], At[m][k], acc[ai][bj][m][n], 0, 0, 0); __builtin_amdgcn_s_setprio(0); } while (0)
; #define PG8_WAIT_V(n) asm volatile("s_waitcnt vmcnt(" #n ")" ::: "memory")
; #define PG8_WAIT_L(n) asm volatile("s_waitcnt lgkmcnt(" #n ")" ::: "memory")
; #define PG8_BAR __builtin_amdgcn_s_barrier()
; #define PG8_SCHED __builtin_amdgcn_sched_barrier(0)
; template <class Epi, class Sched, bool ALIGN_EPI = false, bool SP2 = false>
; __device__ __forceinline__ void gemm_phase(PG8_LAS unsigned char* lds, const Gemm g, const Sched& S, const Epi& E) {
;     ...
;         for (int t = 0; t < nt; t += 2) {
;     ...
;             PG8_LDA(At, 1, 1); PG8_STAGE(PG8_SB(1, 0), b3, voffB); PG8_STAGE(PG8_SB(1, 1), b3 + hstep, voffB); PG8_STAGE(PG8_SA(1, 0), a3, voffA);
;             PG8_WAIT_V(8); PG8_WAIT_L(0); PG8_BAR; PG8_MMA(1, 0, At, B0); PG8_MMA(1, 1, At, B1); PG8_BAR; PG8_SCHED;
	s_add_i32 s56, s77, s58
	v_lshl_add_u64 v[210:211], v[210:211], 0, s[12:13]
	s_mov_b32 m0, s56
	ds_read_b128 v[160:163], v225 offset:49152
	ds_read_b128 v[164:167], v225 offset:50176
	ds_read_b128 v[168:171], v225 offset:51200
	ds_read_b128 v[172:175], v225 offset:52224
	ds_read_b128 v[176:179], v225 offset:53248
	ds_read_b128 v[180:183], v225 offset:54272
	ds_read_b128 v[202:205], v225 offset:55296
	ds_read_b128 v[206:209], v225 offset:56320
	global_load_lds_dwordx4 v[210:211], off
	s_add_i32 m0, s56, 0x2000
	s_add_u32 s54, s54, 0x40080
	v_lshl_add_u64 v[210:211], v[212:213], 0, s[12:13]
	s_addc_u32 s55, s55, 0
	s_add_i32 s56, s78, s58
	global_load_lds_dwordx4 v[210:211], off
	v_lshl_add_u64 v[210:211], s[54:55], 0, v[186:187]
	s_mov_b32 m0, s56
	s_nop 0
	global_load_lds_dwordx4 v[210:211], off
	v_lshl_add_u64 v[210:211], s[54:55], 0, v[190:191]
	s_add_i32 m0, s56, 0x2000
	s_nop 0
	global_load_lds_dwordx4 v[210:211], off
	v_lshl_add_u64 v[210:211], v[214:215], 0, s[12:13]
	s_mov_b32 m0, s66
	s_nop 0
	global_load_lds_dwordx4 v[210:211], off
	v_lshl_add_u64 v[210:211], v[216:217], 0, s[12:13]
	s_mov_b32 m0, s67
	s_nop 0
	global_load_lds_dwordx4 v[210:211], off
	s_waitcnt vmcnt(8)
	s_waitcnt lgkmcnt(0)
	s_barrier
	s_setprio 1
	s_waitcnt lgkmcnt(0)
	v_mfma_f32_16x16x32_bf16 v[60:63], v[96:99], v[160:163], v[60:63]
	v_mfma_f32_16x16x32_bf16 v[56:59], v[120:123], v[160:163], v[56:59]
	v_mfma_f32_16x16x32_bf16 v[44:47], v[96:99], v[168:171], v[44:47]
	v_mfma_f32_16x16x32_bf16 v[40:43], v[120:123], v[168:171], v[40:43]
	v_mfma_f32_16x16x32_bf16 v[28:31], v[96:99], v[176:179], v[28:31]
	v_mfma_f32_16x16x32_bf16 v[24:27], v[120:123], v[176:179], v[24:27]
	v_mfma_f32_16x16x32_bf16 v[12:15], v[96:99], v[202:205], v[12:15]
	v_mfma_f32_16x16x32_bf16 v[8:11], v[120:123], v[202:205], v[8:11]
	v_mfma_f32_16x16x32_bf16 v[60:63], v[108:111], v[164:167], v[60:63]
	v_mfma_f32_16x16x32_bf16 v[56:59], v[128:131], v[164:167], v[56:59]
	v_mfma_f32_16x16x32_bf16 v[44:47], v[108:111], v[172:175], v[44:47]
	v_mfma_f32_16x16x32_bf16 v[40:43], v[128:131], v[172:175], v[40:43]
	v_mfma_f32_16x16x32_bf16 v[28:31], v[108:111], v[180:183], v[28:31]
	v_mfma_f32_16x16x32_bf16 v[24:27], v[128:131], v[180:183], v[24:27]
	v_mfma_f32_16x16x32_bf16 v[12:15], v[108:111], v[206:209], v[12:15]
	v_mfma_f32_16x16x32_bf16 v[8:11], v[128:131], v[206:209], v[8:11]
	s_setprio 0
	s_setprio 1
	v_mfma_f32_16x16x32_bf16 v[52:55], v[144:147], v[160:163], v[52:55]
	v_mfma_f32_16x16x32_bf16 v[48:51], v[152:155], v[160:163], v[48:51]
	v_mfma_f32_16x16x32_bf16 v[36:39], v[144:147], v[168:171], v[36:39]
	v_mfma_f32_16x16x32_bf16 v[32:35], v[152:155], v[168:171], v[32:35]
	v_mfma_f32_16x16x32_bf16 v[20:23], v[144:147], v[176:179], v[20:23]
	v_mfma_f32_16x16x32_bf16 v[16:19], v[152:155], v[176:179], v[16:19]
	v_mfma_f32_16x16x32_bf16 v[4:7], v[144:147], v[202:205], v[4:7]
	v_mfma_f32_16x16x32_bf16 v[0:3], v[152:155], v[202:205], v[0:3]
	v_mfma_f32_16x16x32_bf16 v[52:55], v[148:151], v[164:167], v[52:55]
	v_mfma_f32_16x16x32_bf16 v[48:51], v[156:159], v[164:167], v[48:51]
	v_mfma_f32_16x16x32_bf16 v[36:39], v[148:151], v[172:175], v[36:39]
	v_mfma_f32_16x16x32_bf16 v[32:35], v[156:159], v[172:175], v[32:35]
	v_mfma_f32_16x16x32_bf16 v[20:23], v[148:151], v[180:183], v[20:23]
	v_mfma_f32_16x16x32_bf16 v[16:19], v[156:159], v[180:183], v[16:19]
	v_mfma_f32_16x16x32_bf16 v[4:7], v[148:151], v[206:209], v[4:7]
	v_mfma_f32_16x16x32_bf16 v[0:3], v[156:159], v[206:209], v[0:3]
	s_setprio 0
	s_barrier
	s_add_i32 s76, s76, 2
	s_add_u32 s20, s20, 0x100
	s_addc_u32 s21, s21, 0
	s_add_u32 s74, s74, 0x100
	s_addc_u32 s75, s75, 0
	s_cmp_gt_u32 s76, 13

; #define PG8_STAGE(bufoff, gbase, voff) do { _Pragma("unroll") for (int _i = 0; _i < 2; ++_i) \
;         __builtin_amdgcn_global_load_lds((const unsigned*)((const char*)(gbase) + (voff)[_i]), (PG8_LAS unsigned*)(lds + (bufoff) + ldsw + _i * 8192), 16, 0, 0); } while (0)
; #define PG8_LDA(dst, b, h) do { _Pragma("unroll") for (int m = 0; m < 4; ++m) _Pragma("unroll") for (int k = 0; k < 2; ++k) dst[m][k] = *(const PG8_LAS bf16x8*)(lds + PG8_SA(b, h) + aoff + m * 2048 + k * 1024); } while (0)
; #define PG8_LDB(dst, b, h) do { _Pragma("unroll") for (int n = 0; n < 2; ++n) _Pragma("unroll") for (int k = 0; k < 2; ++k) dst[n][k] = *(const PG8_LAS bf16x8*)(lds + PG8_SB(b, h) + boff + n * 2048 + k * 1024); } while (0)
; #define PG8_WAIT_V(n) asm volatile("s_waitcnt vmcnt(" #n ")" ::: "memory")
; #define PG8_WAIT_L(n) asm volatile("s_waitcnt lgkmcnt(" #n ")" ::: "memory")
; #define PG8_BAR __builtin_amdgcn_s_barrier()
; #define PG8_SCHED __builtin_amdgcn_sched_barrier(0)
; template <class Epi, class Sched, bool ALIGN_EPI = false, bool SP2 = false>
; __device__ __forceinline__ void gemm_phase(PG8_LAS unsigned char* lds, const Gemm g, const Sched& S, const Epi& E) {
;     ...
;         const bool has_next = S.next(ui + 1, nxt);
;         const char* nA = has_next ? (const char*)g.A + (size_t)nxt.pm * tstep : cA; const char* nB = has_next ? (const char*)g.Bt + (size_t)nxt.pn * tstep : cB;
;         for (int t = 0; t < nt; t += 2) {
;             const bool last = (t == nt - 2);
;             const char* a1 = cA + (size_t)(t + 1) * kstep;
;             const char* a2 = last ? nA : cA + (size_t)(t + 2) * kstep; const char* b2 = last ? nB : cB + (size_t)(t + 2) * kstep;
;             const char* a3 = a2 + kstep; const char* b3 = b2 + kstep;
;             if (last && has_next) S.a_ready(nxt);
;             if constexpr (SP2) {
;             PG8_LDB(B0, 0, 0); PG8_LDB(B1, 0, 1); PG8_SCHED; PG8_LDA(At, 0, 0); PG8_STAGE(PG8_SA(1, 1), a1 + hstep, voffA);
;             PG8_WAIT_V(8); PG8_WAIT_L(0); PG8_BAR; PG8_MMA(0, 0, At, B0); PG8_MMA(0, 1, At, B1); PG8_BAR; PG8_SCHED;
;             PG8_LDA(At, 0, 1); PG8_STAGE(PG8_SB(0, 0), b2, voffB); PG8_STAGE(PG8_SB(0, 1), b2 + hstep, voffB); PG8_STAGE(PG8_SA(0, 0), a2, voffA);
;             PG8_WAIT_V(8); PG8_WAIT_L(0); PG8_BAR; PG8_MMA(1, 0, At, B0); PG8_MMA(1, 1, At, B1); PG8_BAR; PG8_SCHED;
.LBB0_1739:
	s_ashr_i32 s15, s14, 31
	s_lshl_b64 s[16:17], s[14:15], 19
	s_add_u32 s16, s36, s16
	s_addc_u32 s17, s37, s17
	s_and_b64 s[18:19], s[4:5], exec
	s_cselect_b32 s15, s17, s21
	s_cselect_b32 s63, s16, s20
	s_ashr_i32 s13, s12, 31
	s_lshl_b64 s[18:19], s[12:13], 19
	s_add_u32 s18, s48, s18
	s_addc_u32 s19, s49, s19
	s_and_b64 s[42:43], s[4:5], exec
	s_cselect_b32 s13, s19, s39
	s_cselect_b32 s64, s18, s38
	s_add_u32 s20, s20, 0x40080
	s_addc_u32 s21, s21, 0
	s_add_u32 s65, s38, 0x100
	s_addc_u32 s66, s39, 0
	s_mov_b32 s67, -2
	ds_read_b128 v[154:157], v150
	ds_read_b128 v[158:161], v150 offset:1024
	ds_read_b128 v[162:165], v150 offset:2048
	ds_read_b128 v[166:169], v150 offset:3072
	ds_read_b128 v[170:173], v151
	ds_read_b128 v[174:177], v151 offset:1024
	ds_read_b128 v[178:181], v151 offset:2048
	ds_read_b128 v[182:185], v151 offset:3072
	s_add_u32 s38, s20, 0xfffc0080
	s_addc_u32 s39, s21, -1
	s_cmp_eq_u32 s67, 12
	s_cselect_b32 s43, s15, s39
	s_cselect_b32 s42, s63, s38
	s_cselect_b32 s39, s13, s66
	s_cselect_b32 s38, s64, s65
	v_lshl_add_u64 v[144:145], s[20:21], 0, v[136:137]
	s_add_i32 m0, s35, 0xc000
	ds_read_b128 v[186:189], v152
	ds_read_b128 v[190:193], v152 offset:1024
	ds_read_b128 v[198:201], v152 offset:2048
	ds_read_b128 v[202:205], v152 offset:3072
	ds_read_b128 v[206:209], v152 offset:4096
	ds_read_b128 v[210:213], v152 offset:5120
	ds_read_b128 v[214:217], v152 offset:6144
	ds_read_b128 v[218:221], v152 offset:7168
	global_load_lds_dwordx4 v[144:145], off
	v_lshl_add_u64 v[144:145], s[20:21], 0, v[138:139]
	s_add_i32 m0, s35, 0xe000
	s_nop 0
	global_load_lds_dwordx4 v[144:145], off
	s_waitcnt vmcnt(8)
	s_waitcnt lgkmcnt(0)
	s_barrier
	s_setprio 1
	s_waitcnt lgkmcnt(0)
	v_mfma_f32_16x16x32_bf16 v[124:127], v[154:157], v[186:189], 0
	v_mfma_f32_16x16x32_bf16 v[116:119], v[162:165], v[186:189], 0
	v_mfma_f32_16x16x32_bf16 v[108:111], v[154:157], v[198:201], 0
	v_mfma_f32_16x16x32_bf16 v[100:103], v[162:165], v[198:201], 0
	v_mfma_f32_16x16x32_bf16 v[92:95], v[154:157], v[206:209], 0
	v_mfma_f32_16x16x32_bf16 v[84:87], v[162:165], v[206:209], 0
	v_mfma_f32_16x16x32_bf16 v[76:79], v[154:157], v[214:217], 0
	v_mfma_f32_16x16x32_bf16 v[68:71], v[162:165], v[214:217], 0
	v_mfma_f32_16x16x32_bf16 v[124:127], v[158:161], v[190:193], v[124:127]
	v_mfma_f32_16x16x32_bf16 v[116:119], v[166:169], v[190:193], v[116:119]
	v_mfma_f32_16x16x32_bf16 v[108:111], v[158:161], v[202:205], v[108:111]
	v_mfma_f32_16x16x32_bf16 v[100:103], v[166:169], v[202:205], v[100:103]
	v_mfma_f32_16x16x32_bf16 v[92:95], v[158:161], v[210:213], v[92:95]
	v_mfma_f32_16x16x32_bf16 v[84:87], v[166:169], v[210:213], v[84:87]
	v_mfma_f32_16x16x32_bf16 v[76:79], v[158:161], v[218:221], v[76:79]
	v_mfma_f32_16x16x32_bf16 v[68:71], v[166:169], v[218:221], v[68:71]
	s_setprio 0
	s_setprio 1
	v_mfma_f32_16x16x32_bf16 v[120:123], v[170:173], v[186:189], 0
	v_mfma_f32_16x16x32_bf16 v[112:115], v[178:181], v[186:189], 0
	v_mfma_f32_16x16x32_bf16 v[104:107], v[170:173], v[198:201], 0
	v_mfma_f32_16x16x32_bf16 v[96:99], v[178:181], v[198:201], 0
	v_mfma_f32_16x16x32_bf16 v[88:91], v[170:173], v[206:209], 0
	v_mfma_f32_16x16x32_bf16 v[80:83], v[178:181], v[206:209], 0
	v_mfma_f32_16x16x32_bf16 v[72:75], v[170:173], v[214:217], 0
	v_mfma_f32_16x16x32_bf16 v[64:67], v[178:181], v[214:217], 0
	v_mfma_f32_16x16x32_bf16 v[120:123], v[174:177], v[190:193], v[120:123]
	v_mfma_f32_16x16x32_bf16 v[112:115], v[182:185], v[190:193], v[112:115]
	v_mfma_f32_16x16x32_bf16 v[104:107], v[174:177], v[202:205], v[104:107]
	v_mfma_f32_16x16x32_bf16 v[96:99], v[182:185], v[202:205], v[96:99]
	v_mfma_f32_16x16x32_bf16 v[88:91], v[174:177], v[210:213], v[88:91]
	v_mfma_f32_16x16x32_bf16 v[80:83], v[182:185], v[210:213], v[80:83]
	v_mfma_f32_16x16x32_bf16 v[72:75], v[174:177], v[218:221], v[72:75]
	v_mfma_f32_16x16x32_bf16 v[64:67], v[182:185], v[218:221], v[64:67]
	s_setprio 0
	s_barrier
	s_add_i32 s68, s58, s50
	v_lshl_add_u64 v[144:145], s[38:39], 0, v[132:133]
	s_mov_b32 m0, s68
	ds_read_b128 v[186:189], v152 offset:16384
	ds_read_b128 v[190:193], v152 offset:17408
	ds_read_b128 v[198:201], v152 offset:18432
	ds_read_b128 v[202:205], v152 offset:19456
	ds_read_b128 v[206:209], v152 offset:20480
	ds_read_b128 v[210:213], v152 offset:21504
	ds_read_b128 v[214:217], v152 offset:22528
	ds_read_b128 v[218:221], v152 offset:23552
	global_load_lds_dwordx4 v[144:145], off
	s_add_i32 m0, s68, 0x2000
	s_add_u32 s68, s38, 0x40000
	v_lshl_add_u64 v[194:195], s[38:39], 0, v[128:129]
	s_addc_u32 s69, s39, 0
	s_add_i32 s70, s59, s50
	global_load_lds_dwordx4 v[194:195], off
	v_lshl_add_u64 v[222:223], s[68:69], 0, v[132:133]
	s_mov_b32 m0, s70
	v_lshl_add_u64 v[224:225], s[42:43], 0, v[130:131]
	global_load_lds_dwordx4 v[222:223], off
	v_lshl_add_u64 v[222:223], s[68:69], 0, v[128:129]
	s_add_i32 m0, s70, 0x2000
	s_nop 0
	global_load_lds_dwordx4 v[222:223], off
	v_lshl_add_u64 v[222:223], s[42:43], 0, v[134:135]
	s_mov_b32 m0, s35
	s_nop 0
	global_load_lds_dwordx4 v[222:223], off
	s_mov_b32 m0, s52
	s_nop 0
	global_load_lds_dwordx4 v[224:225], off
	s_waitcnt vmcnt(8)
	s_waitcnt lgkmcnt(0)
	s_barrier
; #define PG8_STAGE(bufoff, gbase, voff) do { _Pragma("unroll") for (int _i = 0; _i < 2; ++_i) \
;         __builtin_amdgcn_global_load_lds((const unsigned*)((const char*)(gbase) + (voff)[_i]), (PG8_LAS unsigned*)(lds + (bufoff) + ldsw + _i * 8192), 16, 0, 0); } while (0)
; #define PG8_LDA(dst, b, h) do { _Pragma("unroll") for (int m = 0; m < 4; ++m) _Pragma("unroll") for (int k = 0; k < 2; ++k) dst[m][k] = *(const PG8_LAS bf16x8*)(lds + PG8_SA(b, h) + aoff + m * 2048 + k * 1024); } while (0)
; #define PG8_LDB(dst, b, h) do { _Pragma("unroll") for (int n = 0; n < 2; ++n) _Pragma("unroll") for (int k = 0; k < 2; ++k) dst[n][k] = *(const PG8_LAS bf16x8*)(lds + PG8_SB(b, h) + boff + n * 2048 + k * 1024); } while (0)
; #define PG8_MMA(ai, bj, At, Bt) do { __builtin_amdgcn_s_setprio(1); _Pragma("unroll") for (int m = 0; m < 4; ++m) _Pragma("unroll") for (int n = 0; n < 2; ++n) _Pragma("unroll") for (int k = 0; k < 2; ++k) \
;         acc[ai][bj][m][n] = __builtin_amdgcn_mfma_f32_16x16x32_bf16(Bt[n][k], At[m][k], acc[ai][bj][m][n], 0, 0, 0); __builtin_amdgcn_s_setprio(0); } while (0)
; #define PG8_WAIT_V(n) asm volatile("s_waitcnt vmcnt(" #n ")" ::: "memory")
; #define PG8_WAIT_L(n) asm volatile("s_waitcnt lgkmcnt(" #n ")" ::: "memory")
; #define PG8_BAR __builtin_amdgcn_s_barrier()
; #define PG8_SCHED __builtin_amdgcn_sched_barrier(0)
; template <class Epi, class Sched, bool ALIGN_EPI = false, bool SP2 = false>
; __device__ __forceinline__ void gemm_phase(PG8_LAS unsigned char* lds, const Gemm g, const Sched& S, const Epi& E) {
;     ...
;             PG8_WAIT_V(8); PG8_WAIT_L(0); PG8_BAR; PG8_MMA(1, 0, At, B0); PG8_MMA(1, 1, At, B1); PG8_BAR; PG8_SCHED;
;             PG8_LDB(B0, 1, 0); PG8_LDB(B1, 1, 1); PG8_SCHED; PG8_LDA(At, 1, 0); PG8_STAGE(PG8_SA(0, 1), a2 + hstep, voffA);
;             PG8_WAIT_V(8); PG8_WAIT_L(0); PG8_BAR; PG8_MMA(0, 0, At, B0); PG8_MMA(0, 1, At, B1); PG8_BAR; PG8_SCHED;
	s_setprio 1
	s_waitcnt lgkmcnt(0)
	v_mfma_f32_16x16x32_bf16 v[60:63], v[154:157], v[186:189], 0
	v_mfma_f32_16x16x32_bf16 v[52:55], v[162:165], v[186:189], 0
	v_mfma_f32_16x16x32_bf16 v[44:47], v[154:157], v[198:201], 0
	v_mfma_f32_16x16x32_bf16 v[36:39], v[162:165], v[198:201], 0
	v_mfma_f32_16x16x32_bf16 v[28:31], v[154:157], v[206:209], 0
	v_mfma_f32_16x16x32_bf16 v[20:23], v[162:165], v[206:209], 0
	v_mfma_f32_16x16x32_bf16 v[12:15], v[154:157], v[214:217], 0
	v_mfma_f32_16x16x32_bf16 v[4:7], v[162:165], v[214:217], 0
	v_mfma_f32_16x16x32_bf16 v[60:63], v[158:161], v[190:193], v[60:63]
	v_mfma_f32_16x16x32_bf16 v[52:55], v[166:169], v[190:193], v[52:55]
	v_mfma_f32_16x16x32_bf16 v[44:47], v[158:161], v[202:205], v[44:47]
	v_mfma_f32_16x16x32_bf16 v[36:39], v[166:169], v[202:205], v[36:39]
	v_mfma_f32_16x16x32_bf16 v[28:31], v[158:161], v[210:213], v[28:31]
	v_mfma_f32_16x16x32_bf16 v[20:23], v[166:169], v[210:213], v[20:23]
	v_mfma_f32_16x16x32_bf16 v[12:15], v[158:161], v[218:221], v[12:15]
	v_mfma_f32_16x16x32_bf16 v[4:7], v[166:169], v[218:221], v[4:7]
	s_setprio 0
	s_setprio 1
	v_mfma_f32_16x16x32_bf16 v[56:59], v[170:173], v[186:189], 0
	v_mfma_f32_16x16x32_bf16 v[48:51], v[178:181], v[186:189], 0
	v_mfma_f32_16x16x32_bf16 v[40:43], v[170:173], v[198:201], 0
	v_mfma_f32_16x16x32_bf16 v[32:35], v[178:181], v[198:201], 0
	v_mfma_f32_16x16x32_bf16 v[24:27], v[170:173], v[206:209], 0
	v_mfma_f32_16x16x32_bf16 v[16:19], v[178:181], v[206:209], 0
	v_mfma_f32_16x16x32_bf16 v[8:11], v[170:173], v[214:217], 0
	v_mfma_f32_16x16x32_bf16 v[0:3], v[178:181], v[214:217], 0
	v_mfma_f32_16x16x32_bf16 v[56:59], v[174:177], v[190:193], v[56:59]
	v_mfma_f32_16x16x32_bf16 v[48:51], v[182:185], v[190:193], v[48:51]
	v_mfma_f32_16x16x32_bf16 v[40:43], v[174:177], v[202:205], v[40:43]
	v_mfma_f32_16x16x32_bf16 v[32:35], v[182:185], v[202:205], v[32:35]
	v_mfma_f32_16x16x32_bf16 v[24:27], v[174:177], v[210:213], v[24:27]
	v_mfma_f32_16x16x32_bf16 v[16:19], v[182:185], v[210:213], v[16:19]
	v_mfma_f32_16x16x32_bf16 v[8:11], v[174:177], v[218:221], v[8:11]
	v_mfma_f32_16x16x32_bf16 v[0:3], v[182:185], v[218:221], v[0:3]
	s_setprio 0
	s_barrier
	s_add_i32 s68, 0, 0x18000
	v_add_u32_e32 v153, s68, v147
	s_add_i32 s69, 0, 0x1c000
	ds_read_b128 v[154:157], v153
	ds_read_b128 v[158:161], v153 offset:1024
	ds_read_b128 v[162:165], v153 offset:2048
	ds_read_b128 v[166:169], v153 offset:3072
	v_add_u32_e32 v153, s69, v147
	ds_read_b128 v[170:173], v153
	ds_read_b128 v[174:177], v153 offset:1024
	ds_read_b128 v[178:181], v153 offset:2048
	ds_read_b128 v[182:185], v153 offset:3072
	s_add_u32 s42, s42, 0x40000
	s_addc_u32 s43, s43, 0
	s_mov_b32 m0, s53
	v_lshl_add_u64 v[226:227], s[42:43], 0, v[134:135]
	ds_read_b128 v[186:189], v152 offset:32768
	ds_read_b128 v[190:193], v152 offset:33792
	ds_read_b128 v[198:201], v152 offset:34816
	ds_read_b128 v[202:205], v152 offset:35840
	ds_read_b128 v[206:209], v152 offset:36864
	ds_read_b128 v[210:213], v152 offset:37888
	ds_read_b128 v[214:217], v152 offset:38912
	ds_read_b128 v[218:221], v152 offset:39936
	global_load_lds_dwordx4 v[226:227], off
	v_lshl_add_u64 v[226:227], s[42:43], 0, v[130:131]
	s_mov_b32 m0, s54
	s_nop 0
	global_load_lds_dwordx4 v[226:227], off
	s_waitcnt vmcnt(8)
	s_waitcnt lgkmcnt(0)
	s_barrier
	s_setprio 1
	s_waitcnt lgkmcnt(0)
	v_mfma_f32_16x16x32_bf16 v[124:127], v[154:157], v[186:189], v[124:127]
	v_mfma_f32_16x16x32_bf16 v[116:119], v[162:165], v[186:189], v[116:119]
	v_mfma_f32_16x16x32_bf16 v[108:111], v[154:157], v[198:201], v[108:111]
	v_mfma_f32_16x16x32_bf16 v[100:103], v[162:165], v[198:201], v[100:103]
	v_mfma_f32_16x16x32_bf16 v[92:95], v[154:157], v[206:209], v[92:95]
	v_mfma_f32_16x16x32_bf16 v[84:87], v[162:165], v[206:209], v[84:87]
	v_mfma_f32_16x16x32_bf16 v[76:79], v[154:157], v[214:217], v[76:79]
	v_mfma_f32_16x16x32_bf16 v[68:71], v[162:165], v[214:217], v[68:71]
	v_mfma_f32_16x16x32_bf16 v[124:127], v[158:161], v[190:193], v[124:127]
	v_mfma_f32_16x16x32_bf16 v[116:119], v[166:169], v[190:193], v[116:119]
	v_mfma_f32_16x16x32_bf16 v[108:111], v[158:161], v[202:205], v[108:111]
	v_mfma_f32_16x16x32_bf16 v[100:103], v[166:169], v[202:205], v[100:103]
	v_mfma_f32_16x16x32_bf16 v[92:95], v[158:161], v[210:213], v[92:95]
	v_mfma_f32_16x16x32_bf16 v[84:87], v[166:169], v[210:213], v[84:87]
	v_mfma_f32_16x16x32_bf16 v[76:79], v[158:161], v[218:221], v[76:79]
	v_mfma_f32_16x16x32_bf16 v[68:71], v[166:169], v[218:221], v[68:71]
	s_setprio 0
	s_setprio 1
	v_mfma_f32_16x16x32_bf16 v[120:123], v[170:173], v[186:189], v[120:123]
	v_mfma_f32_16x16x32_bf16 v[112:115], v[178:181], v[186:189], v[112:115]
	v_mfma_f32_16x16x32_bf16 v[104:107], v[170:173], v[198:201], v[104:107]
	v_mfma_f32_16x16x32_bf16 v[96:99], v[178:181], v[198:201], v[96:99]
	v_mfma_f32_16x16x32_bf16 v[88:91], v[170:173], v[206:209], v[88:91]
	v_mfma_f32_16x16x32_bf16 v[80:83], v[178:181], v[206:209], v[80:83]
	v_mfma_f32_16x16x32_bf16 v[72:75], v[170:173], v[214:217], v[72:75]
	v_mfma_f32_16x16x32_bf16 v[64:67], v[178:181], v[214:217], v[64:67]
	v_mfma_f32_16x16x32_bf16 v[120:123], v[174:177], v[190:193], v[120:123]
	v_mfma_f32_16x16x32_bf16 v[112:115], v[182:185], v[190:193], v[112:115]
	v_mfma_f32_16x16x32_bf16 v[104:107], v[174:177], v[202:205], v[104:107]
	v_mfma_f32_16x16x32_bf16 v[96:99], v[182:185], v[202:205], v[96:99]
	v_mfma_f32_16x16x32_bf16 v[88:91], v[174:177], v[210:213], v[88:91]
	v_mfma_f32_16x16x32_bf16 v[80:83], v[182:185], v[210:213], v[80:83]
	v_mfma_f32_16x16x32_bf16 v[72:75], v[174:177], v[218:221], v[72:75]
	v_mfma_f32_16x16x32_bf16 v[64:67], v[182:185], v[218:221], v[64:67]
	s_setprio 0
	s_barrier
; #define PG8_STAGE(bufoff, gbase, voff) do { _Pragma("unroll") for (int _i = 0; _i < 2; ++_i) \
;         __builtin_amdgcn_global_load_lds((const unsigned*)((const char*)(gbase) + (voff)[_i]), (PG8_LAS unsigned*)(lds + (bufoff) + ldsw + _i * 8192), 16, 0, 0); } while (0)
; #define PG8_LDA(dst, b, h) do { _Pragma("unroll") for (int m = 0; m < 4; ++m) _Pragma("unroll") for (int k = 0; k < 2; ++k) dst[m][k] = *(const PG8_LAS bf16x8*)(lds + PG8_SA(b, h) + aoff + m * 2048 + k * 1024); } while (0)
; #define PG8_MMA(ai, bj, At, Bt) do { __builtin_amdgcn_s_setprio(1); _Pragma("unroll") for (int m = 0; m < 4; ++m) _Pragma("unroll") for (int n = 0; n < 2; ++n) _Pragma("unroll") for (int k = 0; k < 2; ++k) \
;         acc[ai][bj][m][n] = __builtin_amdgcn_mfma_f32_16x16x32_bf16(Bt[n][k], At[m][k], acc[ai][bj][m][n], 0, 0, 0); __builtin_amdgcn_s_setprio(0); } while (0)
; #define PG8_WAIT_V(n) asm volatile("s_waitcnt vmcnt(" #n ")" ::: "memory")
; #define PG8_WAIT_L(n) asm volatile("s_waitcnt lgkmcnt(" #n ")" ::: "memory")
; #define PG8_BAR __builtin_amdgcn_s_barrier()
; #define PG8_SCHED __builtin_amdgcn_sched_barrier(0)
; template <class Epi, class Sched, bool ALIGN_EPI = false, bool SP2 = false>
; __device__ __forceinline__ void gemm_phase(PG8_LAS unsigned char* lds, const Gemm g, const Sched& S, const Epi& E) {
;     ...
;         for (int t = 0; t < nt; t += 2) {
;     ...
;             PG8_LDA(At, 1, 1); PG8_STAGE(PG8_SB(1, 0), b3, voffB); PG8_STAGE(PG8_SB(1, 1), b3 + hstep, voffB); PG8_STAGE(PG8_SA(1, 0), a3, voffA);
;             PG8_WAIT_V(8); PG8_WAIT_L(0); PG8_BAR; PG8_MMA(1, 0, At, B0); PG8_MMA(1, 1, At, B1); PG8_BAR; PG8_SCHED;
	s_add_i32 s42, s68, s50
	v_lshl_add_u64 v[144:145], v[144:145], 0, s[8:9]
	s_mov_b32 m0, s42
	ds_read_b128 v[186:189], v152 offset:49152
	ds_read_b128 v[190:193], v152 offset:50176
	ds_read_b128 v[198:201], v152 offset:51200
	ds_read_b128 v[202:205], v152 offset:52224
	ds_read_b128 v[206:209], v152 offset:53248
	ds_read_b128 v[210:213], v152 offset:54272
	ds_read_b128 v[214:217], v152 offset:55296
	ds_read_b128 v[218:221], v152 offset:56320
	global_load_lds_dwordx4 v[144:145], off
	s_add_i32 m0, s42, 0x2000
	s_add_u32 s38, s38, 0x40080
	v_lshl_add_u64 v[144:145], v[194:195], 0, s[8:9]
	s_addc_u32 s39, s39, 0
	s_add_i32 s42, s69, s50
	global_load_lds_dwordx4 v[144:145], off
	v_lshl_add_u64 v[144:145], s[38:39], 0, v[132:133]
	s_mov_b32 m0, s42
	s_nop 0
	global_load_lds_dwordx4 v[144:145], off
	v_lshl_add_u64 v[144:145], s[38:39], 0, v[128:129]
	s_add_i32 m0, s42, 0x2000
	s_nop 0
	global_load_lds_dwordx4 v[144:145], off
	v_lshl_add_u64 v[144:145], v[222:223], 0, s[8:9]
	s_mov_b32 m0, s56
	s_nop 0
	global_load_lds_dwordx4 v[144:145], off
	v_lshl_add_u64 v[144:145], v[224:225], 0, s[8:9]
	s_mov_b32 m0, s57
	s_nop 0
	global_load_lds_dwordx4 v[144:145], off
	s_waitcnt vmcnt(8)
	s_waitcnt lgkmcnt(0)
	s_barrier
	s_setprio 1
	s_waitcnt lgkmcnt(0)
	v_mfma_f32_16x16x32_bf16 v[60:63], v[154:157], v[186:189], v[60:63]
	v_mfma_f32_16x16x32_bf16 v[52:55], v[162:165], v[186:189], v[52:55]
	v_mfma_f32_16x16x32_bf16 v[44:47], v[154:157], v[198:201], v[44:47]
	v_mfma_f32_16x16x32_bf16 v[36:39], v[162:165], v[198:201], v[36:39]
	v_mfma_f32_16x16x32_bf16 v[28:31], v[154:157], v[206:209], v[28:31]
	v_mfma_f32_16x16x32_bf16 v[20:23], v[162:165], v[206:209], v[20:23]
	v_mfma_f32_16x16x32_bf16 v[12:15], v[154:157], v[214:217], v[12:15]
	v_mfma_f32_16x16x32_bf16 v[4:7], v[162:165], v[214:217], v[4:7]
	v_mfma_f32_16x16x32_bf16 v[60:63], v[158:161], v[190:193], v[60:63]
	v_mfma_f32_16x16x32_bf16 v[52:55], v[166:169], v[190:193], v[52:55]
	v_mfma_f32_16x16x32_bf16 v[44:47], v[158:161], v[202:205], v[44:47]
	v_mfma_f32_16x16x32_bf16 v[36:39], v[166:169], v[202:205], v[36:39]
	v_mfma_f32_16x16x32_bf16 v[28:31], v[158:161], v[210:213], v[28:31]
	v_mfma_f32_16x16x32_bf16 v[20:23], v[166:169], v[210:213], v[20:23]
	v_mfma_f32_16x16x32_bf16 v[12:15], v[158:161], v[218:221], v[12:15]
	v_mfma_f32_16x16x32_bf16 v[4:7], v[166:169], v[218:221], v[4:7]
	s_setprio 0
	s_setprio 1
	v_mfma_f32_16x16x32_bf16 v[56:59], v[170:173], v[186:189], v[56:59]
	v_mfma_f32_16x16x32_bf16 v[48:51], v[178:181], v[186:189], v[48:51]
	v_mfma_f32_16x16x32_bf16 v[40:43], v[170:173], v[198:201], v[40:43]
	v_mfma_f32_16x16x32_bf16 v[32:35], v[178:181], v[198:201], v[32:35]
	v_mfma_f32_16x16x32_bf16 v[24:27], v[170:173], v[206:209], v[24:27]
	v_mfma_f32_16x16x32_bf16 v[16:19], v[178:181], v[206:209], v[16:19]
	v_mfma_f32_16x16x32_bf16 v[8:11], v[170:173], v[214:217], v[8:11]
	v_mfma_f32_16x16x32_bf16 v[0:3], v[178:181], v[214:217], v[0:3]
	v_mfma_f32_16x16x32_bf16 v[56:59], v[174:177], v[190:193], v[56:59]
	v_mfma_f32_16x16x32_bf16 v[48:51], v[182:185], v[190:193], v[48:51]
	v_mfma_f32_16x16x32_bf16 v[40:43], v[174:177], v[202:205], v[40:43]
	v_mfma_f32_16x16x32_bf16 v[32:35], v[182:185], v[202:205], v[32:35]
	v_mfma_f32_16x16x32_bf16 v[24:27], v[174:177], v[210:213], v[24:27]
	v_mfma_f32_16x16x32_bf16 v[16:19], v[182:185], v[210:213], v[16:19]
	v_mfma_f32_16x16x32_bf16 v[8:11], v[174:177], v[218:221], v[8:11]
	v_mfma_f32_16x16x32_bf16 v[0:3], v[182:185], v[218:221], v[0:3]
	s_setprio 0
	s_barrier
	s_add_i32 s67, s67, 2
	s_add_u32 s20, s20, 0x100
	s_addc_u32 s21, s21, 0
	s_add_u32 s65, s65, 0x100
	s_addc_u32 s66, s66, 0
	s_cmp_gt_u32 s67, 13

; #define PG8_STAGE(bufoff, gbase, voff) do { _Pragma("unroll") for (int _i = 0; _i < 2; ++_i) \
;         __builtin_amdgcn_global_load_lds((const unsigned*)((const char*)(gbase) + (voff)[_i]), (PG8_LAS unsigned*)(lds + (bufoff) + ldsw + _i * 8192), 16, 0, 0); } while (0)
; #define PG8_LDA(dst, b, h) do { _Pragma("unroll") for (int m = 0; m < 4; ++m) _Pragma("unroll") for (int k = 0; k < 2; ++k) dst[m][k] = *(const PG8_LAS bf16x8*)(lds + PG8_SA(b, h) + aoff + m * 2048 + k * 1024); } while (0)
; #define PG8_LDB(dst, b, h) do { _Pragma("unroll") for (int n = 0; n < 2; ++n) _Pragma("unroll") for (int k = 0; k < 2; ++k) dst[n][k] = *(const PG8_LAS bf16x8*)(lds + PG8_SB(b, h) + boff + n * 2048 + k * 1024); } while (0)
; #define PG8_MMA(ai, bj, At, Bt) do { __builtin_amdgcn_s_setprio(1); _Pragma("unroll") for (int m = 0; m < 4; ++m) _Pragma("unroll") for (int n = 0; n < 2; ++n) _Pragma("unroll") for (int k = 0; k < 2; ++k) \
;         acc[ai][bj][m][n] = __builtin_amdgcn_mfma_f32_16x16x32_bf16(Bt[n][k], At[m][k], acc[ai][bj][m][n], 0, 0, 0); __builtin_amdgcn_s_setprio(0); } while (0)
; #define PG8_WAIT_V(n) asm volatile("s_waitcnt vmcnt(" #n ")" ::: "memory")
; #define PG8_WAIT_L(n) asm volatile("s_waitcnt lgkmcnt(" #n ")" ::: "memory")
; template <class Epi, class Sched, bool ALIGN_EPI = false, bool SP2 = false>
; __device__ __forceinline__ void gemm_phase(PG8_LAS unsigned char* lds, const Gemm g, const Sched& S, const Epi& E) {
;     ...
;             const bool last = (t == nt - 2);
;             const char* a1 = cA + (size_t)(t + 1) * kstep;
;             const char* a2 = last ? nA : cA + (size_t)(t + 2) * kstep; const char* b2 = last ? nB : cB + (size_t)(t + 2) * kstep;
;             const char* a3 = a2 + kstep; const char* b3 = b2 + kstep;
;             if (last && has_next) S.a_ready(nxt);
;             if constexpr (SP2) {
;             PG8_LDB(B0, 0, 0); PG8_LDB(B1, 0, 1); PG8_SCHED; PG8_LDA(At, 0, 0); PG8_STAGE(PG8_SA(1, 1), a1 + hstep, voffA);
;             PG8_WAIT_V(8); PG8_WAIT_L(0); PG8_BAR; PG8_MMA(0, 0, At, B0); PG8_MMA(0, 1, At, B1); PG8_BAR; PG8_SCHED;
;             PG8_LDA(At, 0, 1); PG8_STAGE(PG8_SB(0, 0), b2, voffB); PG8_STAGE(PG8_SB(0, 1), b2 + hstep, voffB); PG8_STAGE(PG8_SA(0, 0), a2, voffA);
;             PG8_WAIT_V(8); PG8_WAIT_L(0); PG8_BAR; PG8_MMA(1, 0, At, B0); PG8_MMA(1, 1, At, B1); PG8_BAR; PG8_SCHED;
.LBB0_1824:
	s_add_u32 s20, s20, 0xb0080
	s_addc_u32 s21, s21, 0
	s_add_u32 s68, s34, 0x100
	s_addc_u32 s69, s35, 0
	s_mov_b32 s70, -2
	s_waitcnt lgkmcnt(0)
	ds_read_b128 v[96:99], v222
	ds_read_b128 v[108:111], v222 offset:1024
	ds_read_b128 v[120:123], v222 offset:2048
	ds_read_b128 v[128:131], v222 offset:3072
	ds_read_b128 v[144:147], v223
	ds_read_b128 v[148:151], v223 offset:1024
	ds_read_b128 v[152:155], v223 offset:2048
	ds_read_b128 v[156:159], v223 offset:3072
	s_add_u32 s34, s20, 0xfff50080
	s_addc_u32 s35, s21, -1
	s_cmp_eq_u32 s70, 40
	s_cselect_b32 s47, s1, s35
	s_cselect_b32 s46, s0, s34
	s_cselect_b32 s35, s45, s69
	s_cselect_b32 s34, s44, s68
	v_lshl_add_u64 v[210:211], s[20:21], 0, v[192:193]
	s_add_i32 m0, s49, 0xc000
	ds_read_b128 v[160:163], v224
	ds_read_b128 v[164:167], v224 offset:1024
	ds_read_b128 v[168:171], v224 offset:2048
	ds_read_b128 v[172:175], v224 offset:3072
	ds_read_b128 v[176:179], v224 offset:4096
	ds_read_b128 v[180:183], v224 offset:5120
	ds_read_b128 v[202:205], v224 offset:6144
	ds_read_b128 v[206:209], v224 offset:7168
	global_load_lds_dwordx4 v[210:211], off
	v_lshl_add_u64 v[210:211], s[20:21], 0, v[194:195]
	s_add_i32 m0, s49, 0xe000
	s_nop 0
	global_load_lds_dwordx4 v[210:211], off
	s_waitcnt vmcnt(8)
	s_waitcnt lgkmcnt(0)
	s_barrier
	s_setprio 1
	s_waitcnt lgkmcnt(0)
	v_mfma_f32_16x16x32_bf16 v[140:143], v[96:99], v[160:163], 0
	v_mfma_f32_16x16x32_bf16 v[136:139], v[120:123], v[160:163], 0
	v_mfma_f32_16x16x32_bf16 v[116:119], v[96:99], v[168:171], 0
	v_mfma_f32_16x16x32_bf16 v[112:115], v[120:123], v[168:171], 0
	v_mfma_f32_16x16x32_bf16 v[92:95], v[96:99], v[176:179], 0
	v_mfma_f32_16x16x32_bf16 v[88:91], v[120:123], v[176:179], 0
	v_mfma_f32_16x16x32_bf16 v[76:79], v[96:99], v[202:205], 0
	v_mfma_f32_16x16x32_bf16 v[72:75], v[120:123], v[202:205], 0
	v_mfma_f32_16x16x32_bf16 v[140:143], v[108:111], v[164:167], v[140:143]
	v_mfma_f32_16x16x32_bf16 v[136:139], v[128:131], v[164:167], v[136:139]
	v_mfma_f32_16x16x32_bf16 v[116:119], v[108:111], v[172:175], v[116:119]
	v_mfma_f32_16x16x32_bf16 v[112:115], v[128:131], v[172:175], v[112:115]
	v_mfma_f32_16x16x32_bf16 v[92:95], v[108:111], v[180:183], v[92:95]
	v_mfma_f32_16x16x32_bf16 v[88:91], v[128:131], v[180:183], v[88:91]
	v_mfma_f32_16x16x32_bf16 v[76:79], v[108:111], v[206:209], v[76:79]
	v_mfma_f32_16x16x32_bf16 v[72:75], v[128:131], v[206:209], v[72:75]
	s_setprio 0
	s_setprio 1
	v_mfma_f32_16x16x32_bf16 v[132:135], v[144:147], v[160:163], 0
	v_mfma_f32_16x16x32_bf16 v[124:127], v[152:155], v[160:163], 0
	v_mfma_f32_16x16x32_bf16 v[104:107], v[144:147], v[168:171], 0
	v_mfma_f32_16x16x32_bf16 v[100:103], v[152:155], v[168:171], 0
	v_mfma_f32_16x16x32_bf16 v[84:87], v[144:147], v[176:179], 0
	v_mfma_f32_16x16x32_bf16 v[80:83], v[152:155], v[176:179], 0
	v_mfma_f32_16x16x32_bf16 v[68:71], v[144:147], v[202:205], 0
	v_mfma_f32_16x16x32_bf16 v[64:67], v[152:155], v[202:205], 0
	v_mfma_f32_16x16x32_bf16 v[132:135], v[148:151], v[164:167], v[132:135]
	v_mfma_f32_16x16x32_bf16 v[124:127], v[156:159], v[164:167], v[124:127]
	v_mfma_f32_16x16x32_bf16 v[104:107], v[148:151], v[172:175], v[104:107]
	v_mfma_f32_16x16x32_bf16 v[100:103], v[156:159], v[172:175], v[100:103]
	v_mfma_f32_16x16x32_bf16 v[84:87], v[148:151], v[180:183], v[84:87]
	v_mfma_f32_16x16x32_bf16 v[80:83], v[156:159], v[180:183], v[80:83]
	v_mfma_f32_16x16x32_bf16 v[68:71], v[148:151], v[206:209], v[68:71]
	v_mfma_f32_16x16x32_bf16 v[64:67], v[156:159], v[206:209], v[64:67]
	s_setprio 0
	s_barrier
	s_add_i32 s71, s62, s48
	v_lshl_add_u64 v[210:211], s[34:35], 0, v[186:187]
	s_mov_b32 m0, s71
	ds_read_b128 v[160:163], v224 offset:16384
	ds_read_b128 v[164:167], v224 offset:17408
	ds_read_b128 v[168:171], v224 offset:18432
	ds_read_b128 v[172:175], v224 offset:19456
	ds_read_b128 v[176:179], v224 offset:20480
	ds_read_b128 v[180:183], v224 offset:21504
	ds_read_b128 v[202:205], v224 offset:22528
	ds_read_b128 v[206:209], v224 offset:23552
	global_load_lds_dwordx4 v[210:211], off
	s_add_i32 m0, s71, 0x2000
	s_add_u32 s72, s34, 0xb0000
	v_lshl_add_u64 v[212:213], s[34:35], 0, v[190:191]
	s_addc_u32 s73, s35, 0
	s_add_i32 s71, s63, s48
	global_load_lds_dwordx4 v[212:213], off
	v_lshl_add_u64 v[214:215], s[72:73], 0, v[186:187]
	s_mov_b32 m0, s71
	v_lshl_add_u64 v[216:217], s[46:47], 0, v[188:189]
	global_load_lds_dwordx4 v[214:215], off
	v_lshl_add_u64 v[214:215], s[72:73], 0, v[190:191]
	s_add_i32 m0, s71, 0x2000
	s_nop 0
	global_load_lds_dwordx4 v[214:215], off
	v_lshl_add_u64 v[214:215], s[46:47], 0, v[184:185]
	s_mov_b32 m0, s49
	s_nop 0
	global_load_lds_dwordx4 v[214:215], off
	s_mov_b32 m0, s50
	s_nop 0
	global_load_lds_dwordx4 v[216:217], off
	s_waitcnt vmcnt(8)
	s_waitcnt lgkmcnt(0)
	s_barrier
; #define PG8_STAGE(bufoff, gbase, voff) do { _Pragma("unroll") for (int _i = 0; _i < 2; ++_i) \
;         __builtin_amdgcn_global_load_lds((const unsigned*)((const char*)(gbase) + (voff)[_i]), (PG8_LAS unsigned*)(lds + (bufoff) + ldsw + _i * 8192), 16, 0, 0); } while (0)
; #define PG8_LDA(dst, b, h) do { _Pragma("unroll") for (int m = 0; m < 4; ++m) _Pragma("unroll") for (int k = 0; k < 2; ++k) dst[m][k] = *(const PG8_LAS bf16x8*)(lds + PG8_SA(b, h) + aoff + m * 2048 + k * 1024); } while (0)
; #define PG8_LDB(dst, b, h) do { _Pragma("unroll") for (int n = 0; n < 2; ++n) _Pragma("unroll") for (int k = 0; k < 2; ++k) dst[n][k] = *(const PG8_LAS bf16x8*)(lds + PG8_SB(b, h) + boff + n * 2048 + k * 1024); } while (0)
; #define PG8_MMA(ai, bj, At, Bt) do { __builtin_amdgcn_s_setprio(1); _Pragma("unroll") for (int m = 0; m < 4; ++m) _Pragma("unroll") for (int n = 0; n < 2; ++n) _Pragma("unroll") for (int k = 0; k < 2; ++k) \
;         acc[ai][bj][m][n] = __builtin_amdgcn_mfma_f32_16x16x32_bf16(Bt[n][k], At[m][k], acc[ai][bj][m][n], 0, 0, 0); __builtin_amdgcn_s_setprio(0); } while (0)
; #define PG8_WAIT_V(n) asm volatile("s_waitcnt vmcnt(" #n ")" ::: "memory")
; #define PG8_WAIT_L(n) asm volatile("s_waitcnt lgkmcnt(" #n ")" ::: "memory")
; #define PG8_BAR __builtin_amdgcn_s_barrier()
; #define PG8_SCHED __builtin_amdgcn_sched_barrier(0)
; template <class Epi, class Sched, bool ALIGN_EPI = false, bool SP2 = false>
; __device__ __forceinline__ void gemm_phase(PG8_LAS unsigned char* lds, const Gemm g, const Sched& S, const Epi& E) {
;     ...
;             PG8_WAIT_V(8); PG8_WAIT_L(0); PG8_BAR; PG8_MMA(1, 0, At, B0); PG8_MMA(1, 1, At, B1); PG8_BAR; PG8_SCHED;
;             PG8_LDB(B0, 1, 0); PG8_LDB(B1, 1, 1); PG8_SCHED; PG8_LDA(At, 1, 0); PG8_STAGE(PG8_SA(0, 1), a2 + hstep, voffA);
;             PG8_WAIT_V(8); PG8_WAIT_L(0); PG8_BAR; PG8_MMA(0, 0, At, B0); PG8_MMA(0, 1, At, B1); PG8_BAR; PG8_SCHED;
	s_setprio 1
	s_waitcnt lgkmcnt(0)
	v_mfma_f32_16x16x32_bf16 v[60:63], v[96:99], v[160:163], 0
	v_mfma_f32_16x16x32_bf16 v[56:59], v[120:123], v[160:163], 0
	v_mfma_f32_16x16x32_bf16 v[44:47], v[96:99], v[168:171], 0
	v_mfma_f32_16x16x32_bf16 v[40:43], v[120:123], v[168:171], 0
	v_mfma_f32_16x16x32_bf16 v[28:31], v[96:99], v[176:179], 0
	v_mfma_f32_16x16x32_bf16 v[24:27], v[120:123], v[176:179], 0
	v_mfma_f32_16x16x32_bf16 v[12:15], v[96:99], v[202:205], 0
	v_mfma_f32_16x16x32_bf16 v[8:11], v[120:123], v[202:205], 0
	v_mfma_f32_16x16x32_bf16 v[60:63], v[108:111], v[164:167], v[60:63]
	v_mfma_f32_16x16x32_bf16 v[56:59], v[128:131], v[164:167], v[56:59]
	v_mfma_f32_16x16x32_bf16 v[44:47], v[108:111], v[172:175], v[44:47]
	v_mfma_f32_16x16x32_bf16 v[40:43], v[128:131], v[172:175], v[40:43]
	v_mfma_f32_16x16x32_bf16 v[28:31], v[108:111], v[180:183], v[28:31]
	v_mfma_f32_16x16x32_bf16 v[24:27], v[128:131], v[180:183], v[24:27]
	v_mfma_f32_16x16x32_bf16 v[12:15], v[108:111], v[206:209], v[12:15]
	v_mfma_f32_16x16x32_bf16 v[8:11], v[128:131], v[206:209], v[8:11]
	s_setprio 0
	s_setprio 1
	v_mfma_f32_16x16x32_bf16 v[52:55], v[144:147], v[160:163], 0
	v_mfma_f32_16x16x32_bf16 v[48:51], v[152:155], v[160:163], 0
	v_mfma_f32_16x16x32_bf16 v[36:39], v[144:147], v[168:171], 0
	v_mfma_f32_16x16x32_bf16 v[32:35], v[152:155], v[168:171], 0
	v_mfma_f32_16x16x32_bf16 v[20:23], v[144:147], v[176:179], 0
	v_mfma_f32_16x16x32_bf16 v[16:19], v[152:155], v[176:179], 0
	v_mfma_f32_16x16x32_bf16 v[4:7], v[144:147], v[202:205], 0
	v_mfma_f32_16x16x32_bf16 v[0:3], v[152:155], v[202:205], 0
	v_mfma_f32_16x16x32_bf16 v[52:55], v[148:151], v[164:167], v[52:55]
	v_mfma_f32_16x16x32_bf16 v[48:51], v[156:159], v[164:167], v[48:51]
	v_mfma_f32_16x16x32_bf16 v[36:39], v[148:151], v[172:175], v[36:39]
	v_mfma_f32_16x16x32_bf16 v[32:35], v[156:159], v[172:175], v[32:35]
	v_mfma_f32_16x16x32_bf16 v[20:23], v[148:151], v[180:183], v[20:23]
	v_mfma_f32_16x16x32_bf16 v[16:19], v[156:159], v[180:183], v[16:19]
	v_mfma_f32_16x16x32_bf16 v[4:7], v[148:151], v[206:209], v[4:7]
	v_mfma_f32_16x16x32_bf16 v[0:3], v[156:159], v[206:209], v[0:3]
	s_setprio 0
	s_barrier
	s_add_i32 s71, 0, 0x18000
	s_add_i32 s72, 0, 0x1c000
	v_add_u32_e32 v128, s71, v197
	v_add_u32_e32 v156, s72, v197
	ds_read_b128 v[96:99], v128
	ds_read_b128 v[108:111], v128 offset:1024
	ds_read_b128 v[120:123], v128 offset:2048
	ds_read_b128 v[128:131], v128 offset:3072
	ds_read_b128 v[144:147], v156
	ds_read_b128 v[148:151], v156 offset:1024
	ds_read_b128 v[152:155], v156 offset:2048
	ds_read_b128 v[156:159], v156 offset:3072
	s_add_u32 s46, s46, 0xb0000
	s_addc_u32 s47, s47, 0
	s_mov_b32 m0, s51
	v_lshl_add_u64 v[218:219], s[46:47], 0, v[184:185]
	ds_read_b128 v[160:163], v224 offset:32768
	ds_read_b128 v[164:167], v224 offset:33792
	ds_read_b128 v[168:171], v224 offset:34816
	ds_read_b128 v[172:175], v224 offset:35840
	ds_read_b128 v[176:179], v224 offset:36864
	ds_read_b128 v[180:183], v224 offset:37888
	ds_read_b128 v[202:205], v224 offset:38912
	ds_read_b128 v[206:209], v224 offset:39936
	global_load_lds_dwordx4 v[218:219], off
	v_lshl_add_u64 v[218:219], s[46:47], 0, v[188:189]
	s_mov_b32 m0, s52
	s_nop 0
	global_load_lds_dwordx4 v[218:219], off
	s_waitcnt vmcnt(8)
	s_waitcnt lgkmcnt(0)
	s_barrier
	s_setprio 1
	s_waitcnt lgkmcnt(0)
	v_mfma_f32_16x16x32_bf16 v[140:143], v[96:99], v[160:163], v[140:143]
	v_mfma_f32_16x16x32_bf16 v[136:139], v[120:123], v[160:163], v[136:139]
	v_mfma_f32_16x16x32_bf16 v[116:119], v[96:99], v[168:171], v[116:119]
	v_mfma_f32_16x16x32_bf16 v[112:115], v[120:123], v[168:171], v[112:115]
	v_mfma_f32_16x16x32_bf16 v[92:95], v[96:99], v[176:179], v[92:95]
	v_mfma_f32_16x16x32_bf16 v[88:91], v[120:123], v[176:179], v[88:91]
	v_mfma_f32_16x16x32_bf16 v[76:79], v[96:99], v[202:205], v[76:79]
	v_mfma_f32_16x16x32_bf16 v[72:75], v[120:123], v[202:205], v[72:75]
	v_mfma_f32_16x16x32_bf16 v[140:143], v[108:111], v[164:167], v[140:143]
	v_mfma_f32_16x16x32_bf16 v[136:139], v[128:131], v[164:167], v[136:139]
	v_mfma_f32_16x16x32_bf16 v[116:119], v[108:111], v[172:175], v[116:119]
	v_mfma_f32_16x16x32_bf16 v[112:115], v[128:131], v[172:175], v[112:115]
	v_mfma_f32_16x16x32_bf16 v[92:95], v[108:111], v[180:183], v[92:95]
	v_mfma_f32_16x16x32_bf16 v[88:91], v[128:131], v[180:183], v[88:91]
	v_mfma_f32_16x16x32_bf16 v[76:79], v[108:111], v[206:209], v[76:79]
	v_mfma_f32_16x16x32_bf16 v[72:75], v[128:131], v[206:209], v[72:75]
	s_setprio 0
	s_setprio 1
	v_mfma_f32_16x16x32_bf16 v[132:135], v[144:147], v[160:163], v[132:135]
	v_mfma_f32_16x16x32_bf16 v[124:127], v[152:155], v[160:163], v[124:127]
	v_mfma_f32_16x16x32_bf16 v[104:107], v[144:147], v[168:171], v[104:107]
	v_mfma_f32_16x16x32_bf16 v[100:103], v[152:155], v[168:171], v[100:103]
	v_mfma_f32_16x16x32_bf16 v[84:87], v[144:147], v[176:179], v[84:87]
	v_mfma_f32_16x16x32_bf16 v[80:83], v[152:155], v[176:179], v[80:83]
	v_mfma_f32_16x16x32_bf16 v[68:71], v[144:147], v[202:205], v[68:71]
	v_mfma_f32_16x16x32_bf16 v[64:67], v[152:155], v[202:205], v[64:67]
	v_mfma_f32_16x16x32_bf16 v[132:135], v[148:151], v[164:167], v[132:135]
	v_mfma_f32_16x16x32_bf16 v[124:127], v[156:159], v[164:167], v[124:127]
	v_mfma_f32_16x16x32_bf16 v[104:107], v[148:151], v[172:175], v[104:107]
	v_mfma_f32_16x16x32_bf16 v[100:103], v[156:159], v[172:175], v[100:103]
	v_mfma_f32_16x16x32_bf16 v[84:87], v[148:151], v[180:183], v[84:87]
	v_mfma_f32_16x16x32_bf16 v[80:83], v[156:159], v[180:183], v[80:83]
	v_mfma_f32_16x16x32_bf16 v[68:71], v[148:151], v[206:209], v[68:71]
	v_mfma_f32_16x16x32_bf16 v[64:67], v[156:159], v[206:209], v[64:67]
	s_setprio 0
	s_barrier
; #define PG8_STAGE(bufoff, gbase, voff) do { _Pragma("unroll") for (int _i = 0; _i < 2; ++_i) \
;         __builtin_amdgcn_global_load_lds((const unsigned*)((const char*)(gbase) + (voff)[_i]), (PG8_LAS unsigned*)(lds + (bufoff) + ldsw + _i * 8192), 16, 0, 0); } while (0)
; #define PG8_LDA(dst, b, h) do { _Pragma("unroll") for (int m = 0; m < 4; ++m) _Pragma("unroll") for (int k = 0; k < 2; ++k) dst[m][k] = *(const PG8_LAS bf16x8*)(lds + PG8_SA(b, h) + aoff + m * 2048 + k * 1024); } while (0)
; #define PG8_MMA(ai, bj, At, Bt) do { __builtin_amdgcn_s_setprio(1); _Pragma("unroll") for (int m = 0; m < 4; ++m) _Pragma("unroll") for (int n = 0; n < 2; ++n) _Pragma("unroll") for (int k = 0; k < 2; ++k) \
;         acc[ai][bj][m][n] = __builtin_amdgcn_mfma_f32_16x16x32_bf16(Bt[n][k], At[m][k], acc[ai][bj][m][n], 0, 0, 0); __builtin_amdgcn_s_setprio(0); } while (0)
; #define PG8_WAIT_V(n) asm volatile("s_waitcnt vmcnt(" #n ")" ::: "memory")
; #define PG8_WAIT_L(n) asm volatile("s_waitcnt lgkmcnt(" #n ")" ::: "memory")
; #define PG8_BAR __builtin_amdgcn_s_barrier()
; #define PG8_SCHED __builtin_amdgcn_sched_barrier(0)
; template <class Epi, class Sched, bool ALIGN_EPI = false, bool SP2 = false>
; __device__ __forceinline__ void gemm_phase(PG8_LAS unsigned char* lds, const Gemm g, const Sched& S, const Epi& E) {
;     ...
;         for (int t = 0; t < nt; t += 2) {
;             const bool last = (t == nt - 2);
;             const char* a1 = cA + (size_t)(t + 1) * kstep;
;             const char* a2 = last ? nA : cA + (size_t)(t + 2) * kstep; const char* b2 = last ? nB : cB + (size_t)(t + 2) * kstep;
;             const char* a3 = a2 + kstep; const char* b3 = b2 + kstep;
;     ...
;             PG8_LDA(At, 1, 1); PG8_STAGE(PG8_SB(1, 0), b3, voffB); PG8_STAGE(PG8_SB(1, 1), b3 + hstep, voffB); PG8_STAGE(PG8_SA(1, 0), a3, voffA);
;             PG8_WAIT_V(8); PG8_WAIT_L(0); PG8_BAR; PG8_MMA(1, 0, At, B0); PG8_MMA(1, 1, At, B1); PG8_BAR; PG8_SCHED;
	s_add_i32 s46, s71, s48
	v_lshl_add_u64 v[210:211], v[210:211], 0, s[12:13]
	s_mov_b32 m0, s46
	ds_read_b128 v[160:163], v224 offset:49152
	ds_read_b128 v[164:167], v224 offset:50176
	ds_read_b128 v[168:171], v224 offset:51200
	ds_read_b128 v[172:175], v224 offset:52224
	ds_read_b128 v[176:179], v224 offset:53248
	ds_read_b128 v[180:183], v224 offset:54272
	ds_read_b128 v[202:205], v224 offset:55296
	ds_read_b128 v[206:209], v224 offset:56320
	global_load_lds_dwordx4 v[210:211], off
	s_add_i32 m0, s46, 0x2000
	s_add_u32 s34, s34, 0xb0080
	v_lshl_add_u64 v[210:211], v[212:213], 0, s[12:13]
	s_addc_u32 s35, s35, 0
	s_add_i32 s46, s72, s48
	global_load_lds_dwordx4 v[210:211], off
	v_lshl_add_u64 v[210:211], s[34:35], 0, v[186:187]
	s_mov_b32 m0, s46
	s_nop 0
	global_load_lds_dwordx4 v[210:211], off
	v_lshl_add_u64 v[210:211], s[34:35], 0, v[190:191]
	s_add_i32 m0, s46, 0x2000
	s_nop 0
	global_load_lds_dwordx4 v[210:211], off
	v_lshl_add_u64 v[210:211], v[214:215], 0, s[12:13]
	s_mov_b32 m0, s57
	s_nop 0
	global_load_lds_dwordx4 v[210:211], off
	v_lshl_add_u64 v[210:211], v[216:217], 0, s[12:13]
	s_mov_b32 m0, s58
	s_nop 0
	global_load_lds_dwordx4 v[210:211], off
	s_waitcnt vmcnt(8)
	s_waitcnt lgkmcnt(0)
	s_barrier
	s_setprio 1
	s_waitcnt lgkmcnt(0)
	v_mfma_f32_16x16x32_bf16 v[60:63], v[96:99], v[160:163], v[60:63]
	v_mfma_f32_16x16x32_bf16 v[56:59], v[120:123], v[160:163], v[56:59]
	v_mfma_f32_16x16x32_bf16 v[44:47], v[96:99], v[168:171], v[44:47]
	v_mfma_f32_16x16x32_bf16 v[40:43], v[120:123], v[168:171], v[40:43]
	v_mfma_f32_16x16x32_bf16 v[28:31], v[96:99], v[176:179], v[28:31]
	v_mfma_f32_16x16x32_bf16 v[24:27], v[120:123], v[176:179], v[24:27]
	v_mfma_f32_16x16x32_bf16 v[12:15], v[96:99], v[202:205], v[12:15]
	v_mfma_f32_16x16x32_bf16 v[8:11], v[120:123], v[202:205], v[8:11]
	v_mfma_f32_16x16x32_bf16 v[60:63], v[108:111], v[164:167], v[60:63]
	v_mfma_f32_16x16x32_bf16 v[56:59], v[128:131], v[164:167], v[56:59]
	v_mfma_f32_16x16x32_bf16 v[44:47], v[108:111], v[172:175], v[44:47]
	v_mfma_f32_16x16x32_bf16 v[40:43], v[128:131], v[172:175], v[40:43]
	v_mfma_f32_16x16x32_bf16 v[28:31], v[108:111], v[180:183], v[28:31]
	v_mfma_f32_16x16x32_bf16 v[24:27], v[128:131], v[180:183], v[24:27]
	v_mfma_f32_16x16x32_bf16 v[12:15], v[108:111], v[206:209], v[12:15]
	v_mfma_f32_16x16x32_bf16 v[8:11], v[128:131], v[206:209], v[8:11]
	s_setprio 0
	s_setprio 1
	v_mfma_f32_16x16x32_bf16 v[52:55], v[144:147], v[160:163], v[52:55]
	v_mfma_f32_16x16x32_bf16 v[48:51], v[152:155], v[160:163], v[48:51]
	v_mfma_f32_16x16x32_bf16 v[36:39], v[144:147], v[168:171], v[36:39]
	v_mfma_f32_16x16x32_bf16 v[32:35], v[152:155], v[168:171], v[32:35]
	v_mfma_f32_16x16x32_bf16 v[20:23], v[144:147], v[176:179], v[20:23]
	v_mfma_f32_16x16x32_bf16 v[16:19], v[152:155], v[176:179], v[16:19]
	v_mfma_f32_16x16x32_bf16 v[4:7], v[144:147], v[202:205], v[4:7]
	v_mfma_f32_16x16x32_bf16 v[0:3], v[152:155], v[202:205], v[0:3]
	v_mfma_f32_16x16x32_bf16 v[52:55], v[148:151], v[164:167], v[52:55]
	v_mfma_f32_16x16x32_bf16 v[48:51], v[156:159], v[164:167], v[48:51]
	v_mfma_f32_16x16x32_bf16 v[36:39], v[148:151], v[172:175], v[36:39]
	v_mfma_f32_16x16x32_bf16 v[32:35], v[156:159], v[172:175], v[32:35]
	v_mfma_f32_16x16x32_bf16 v[20:23], v[148:151], v[180:183], v[20:23]
	v_mfma_f32_16x16x32_bf16 v[16:19], v[156:159], v[180:183], v[16:19]
	v_mfma_f32_16x16x32_bf16 v[4:7], v[148:151], v[206:209], v[4:7]
	v_mfma_f32_16x16x32_bf16 v[0:3], v[156:159], v[206:209], v[0:3]
	s_setprio 0
	s_barrier
	s_add_i32 s70, s70, 2
	s_add_u32 s20, s20, 0x100
	s_addc_u32 s21, s21, 0
	s_add_u32 s68, s68, 0x100
	s_addc_u32 s69, s69, 0
	s_cmp_gt_u32 s70, 41
